# P7 sample-epilogue: state_conv loads preloaded per quarter (no per-group store drains); P8 epilogue: dropped 2 store-drain waits; P10: loop-invariant gamma/beta loads hoisted
# speedup vs baseline: 1.0161x; 1.0161x over previous
.LBB0_1313:
	s_or_b64 exec, exec, s[66:67]
	v_lshl_add_u32 v209, s64, 8, v197
	v_add_u32_e32 v252, 0xffff8000, v209
	v_ashrrev_i32_e32 v252, 2, v252
	v_mad_i64_i32 v[242:243], s[72:73], v252, s81, 0
	v_lshl_add_u64 v[242:243], s[12:13], 0, v[242:243]
	v_lshl_add_u64 v[242:243], v[190:191], 2, v[242:243]
	v_add_u32_e32 v164, 0xffff8000, v209
	v_ashrrev_i32_e32 v174, 2, v164
	v_ashrrev_i32_e32 v175, 31, v174
	v_lshl_add_u64 v[164:165], v[174:175], 1, v[184:185]
	v_mad_u64_u32 v[192:193], s[46:47], v164, s80, 0
	v_mad_i32_i24 v193, v165, s80, v193
	v_mov_b32_e32 v164, 0
	v_mov_b32_e32 v168, 0
	v_mov_b32_e32 v165, 0
	v_mov_b32_e32 v169, 0
	s_waitcnt lgkmcnt(0)
	v_mov_b32_dpp v164, v170 row_ror:1 row_mask:0xf bank_mask:0xf
	v_mov_b32_dpp v168, v170 row_ror:2 row_mask:0xf bank_mask:0xf
	v_mov_b32_dpp v165, v171 row_ror:1 row_mask:0xf bank_mask:0xf
	v_mov_b32_dpp v169, v171 row_ror:2 row_mask:0xf bank_mask:0xf
	v_mov_b32_e32 v166, 0
	v_mov_b32_e32 v170, 0
	v_mov_b32_e32 v167, 0
	v_mov_b32_e32 v171, 0
	v_mov_b32_dpp v166, v172 row_ror:1 row_mask:0xf bank_mask:0xf
	v_mov_b32_dpp v170, v172 row_ror:2 row_mask:0xf bank_mask:0xf
	v_mov_b32_dpp v167, v173 row_ror:1 row_mask:0xf bank_mask:0xf
	v_mov_b32_dpp v171, v173 row_ror:2 row_mask:0xf bank_mask:0xf
	v_lshl_add_u64 v[172:173], s[18:19], 0, v[192:193]
	v_mov_b32_dpp v164, v148 row_shr:1 row_mask:0xf bank_mask:0xf
	v_mov_b32_dpp v168, v148 row_shr:2 row_mask:0xf bank_mask:0xf
	v_mov_b32_dpp v165, v149 row_shr:1 row_mask:0xf bank_mask:0xf
	v_mov_b32_dpp v169, v149 row_shr:2 row_mask:0xf bank_mask:0xf
	v_mov_b32_dpp v166, v150 row_shr:1 row_mask:0xf bank_mask:0xf
	v_mov_b32_dpp v170, v150 row_shr:2 row_mask:0xf bank_mask:0xf
	v_mov_b32_dpp v167, v151 row_shr:1 row_mask:0xf bank_mask:0xf
	v_mov_b32_dpp v171, v151 row_shr:2 row_mask:0xf bank_mask:0xf
	v_lshl_add_u64 v[192:193], v[190:191], 2, v[172:173]
	v_mov_b64_e32 v[244:245], v[242:243]
	s_mov_b64 s[72:73], 0x2c00
	v_lshl_add_u64 v[246:247], v[244:245], 0, s[72:73]
	s_mov_b64 s[72:73], 0x16000
	v_lshl_add_u64 v[248:249], v[244:245], 0, s[72:73]
	s_mov_b64 s[72:73], 0x2c00
	v_lshl_add_u64 v[250:251], v[248:249], 0, s[72:73]
	global_load_dwordx4 v[210:213], v[246:247], off
	global_load_dwordx4 v[214:217], v[244:245], off
	global_load_dwordx4 v[218:221], v[246:247], off offset:16
	global_load_dwordx4 v[222:225], v[244:245], off offset:16
	global_load_dwordx4 v[226:229], v[250:251], off
	global_load_dwordx4 v[230:233], v[248:249], off
	global_load_dwordx4 v[234:237], v[250:251], off offset:16
	global_load_dwordx4 v[238:241], v[248:249], off offset:16
	s_and_saveexec_b64 s[46:47], s[28:29]
	s_xor_b64 s[64:65], exec, s[46:47]
	s_cbranch_execz .LBB0_1315
	global_store_dwordx4 v[192:193], v[148:151], off
.LBB0_1315:
	s_waitcnt vmcnt(1)
	s_or_saveexec_b64 s[64:65], s[64:65]
	v_mad_i64_i32 v[172:173], s[46:47], v174, s81, 0
	v_lshl_add_u64 v[172:173], s[12:13], 0, v[172:173]
	v_lshl_add_u64 v[194:195], v[190:191], 2, v[172:173]
	s_xor_b64 exec, exec, s[64:65]
	s_cbranch_execz .LBB0_1319
	v_add_co_u32_e32 v168, vcc, 0x2000, v194
	s_nop 1
	v_addc_co_u32_e32 v169, vcc, 0, v195, vcc
	v_mov_b32_e32 v172, v210
	v_mov_b32_e32 v173, v211
	v_mov_b32_e32 v174, v212
	v_mov_b32_e32 v175, v213
	s_waitcnt lgkmcnt(0)
	v_mov_b64_e32 v[168:169], v[172:173]
	v_mov_b64_e32 v[170:171], v[174:175]
	s_and_saveexec_b64 s[66:67], s[6:7]
	s_cbranch_execz .LBB0_1318
	v_mov_b32_e32 v168, v214
	v_mov_b32_e32 v169, v215
	v_mov_b32_e32 v170, v216
	v_mov_b32_e32 v171, v217
	v_mov_b64_e32 v[164:165], v[172:173]
	v_mov_b64_e32 v[166:167], v[174:175]

.LBB0_1319:
	s_or_b64 exec, exec, s[64:65]
	s_waitcnt lgkmcnt(0)
	v_pk_fma_f32 v[170:171], v[86:87], v[170:171], v[90:91]
	v_pk_fma_f32 v[168:169], v[84:85], v[168:169], v[88:89]
	v_pk_fma_f32 v[166:167], v[78:79], v[166:167], v[170:171]
	v_pk_fma_f32 v[164:165], v[76:77], v[164:165], v[168:169]
	v_pk_fma_f32 v[166:167], v[150:151], v[82:83], v[166:167]
	v_pk_fma_f32 v[164:165], v[148:149], v[80:81], v[164:165]
	v_mul_f32_e32 v170, 0xbfb8aa3b, v167
	v_exp_f32_e32 v170, v170
	v_mul_f32_e32 v171, 0xbfb8aa3b, v166
	v_exp_f32_e32 v171, v171
	v_mul_f32_e32 v169, 0xbfb8aa3b, v164
	v_add_f32_e32 v170, 1.0, v170
	v_rcp_f32_e32 v170, v170
	v_add_f32_e32 v168, 1.0, v171
	v_exp_f32_e32 v169, v169
	v_mul_f32_e32 v167, v167, v170
	v_mul_f32_e32 v159, v159, v167
	v_rcp_f32_e32 v167, v168
	v_mul_f32_e32 v168, 0xbfb8aa3b, v165
	v_exp_f32_e32 v168, v168
	v_mul_f32_e32 v166, v166, v167
	v_mul_f32_e32 v158, v158, v166
	v_add_f32_e32 v167, 1.0, v168
	v_add_f32_e32 v168, 1.0, v169
	v_rcp_f32_e32 v167, v167
	v_rcp_f32_e32 v168, v168
	v_mov_b32_e32 v166, 0
	v_mul_f32_e32 v165, v165, v167
	v_mul_f32_e32 v164, v164, v168
	v_mul_f32_e32 v157, v157, v165
	v_mul_f32_e32 v156, v156, v164
	v_cvt_pk_bf16_f32 v156, v156, v157
	v_cvt_pk_bf16_f32 v157, v158, v159
	v_mov_b32_e32 v158, 0
	v_mov_b32_e32 v164, 0
	v_mov_b32_e32 v159, 0
	v_mov_b32_e32 v165, 0
	v_mov_b32_dpp v158, v160 row_ror:1 row_mask:0xf bank_mask:0xf
	v_mov_b32_dpp v164, v160 row_ror:2 row_mask:0xf bank_mask:0xf
	v_mov_b32_dpp v159, v161 row_ror:1 row_mask:0xf bank_mask:0xf
	v_mov_b32_dpp v165, v161 row_ror:2 row_mask:0xf bank_mask:0xf
	v_mov_b32_e32 v160, 0
	v_mov_b32_e32 v161, 0
	v_mov_b32_e32 v167, 0
	v_mov_b32_dpp v160, v162 row_ror:1 row_mask:0xf bank_mask:0xf
	v_mov_b32_dpp v166, v162 row_ror:2 row_mask:0xf bank_mask:0xf
	v_mov_b32_dpp v161, v163 row_ror:1 row_mask:0xf bank_mask:0xf
	v_mov_b32_dpp v167, v163 row_ror:2 row_mask:0xf bank_mask:0xf
	v_mov_b32_dpp v158, v144 row_shr:1 row_mask:0xf bank_mask:0xf
	v_mov_b32_dpp v164, v144 row_shr:2 row_mask:0xf bank_mask:0xf
	v_mov_b32_dpp v159, v145 row_shr:1 row_mask:0xf bank_mask:0xf
	v_mov_b32_dpp v165, v145 row_shr:2 row_mask:0xf bank_mask:0xf
	v_mov_b32_dpp v160, v146 row_shr:1 row_mask:0xf bank_mask:0xf
	v_mov_b32_dpp v166, v146 row_shr:2 row_mask:0xf bank_mask:0xf
	v_mov_b32_dpp v161, v147 row_shr:1 row_mask:0xf bank_mask:0xf
	v_mov_b32_dpp v167, v147 row_shr:2 row_mask:0xf bank_mask:0xf
	s_and_saveexec_b64 s[46:47], s[28:29]
	s_xor_b64 s[64:65], exec, s[46:47]
	s_cbranch_execz .LBB0_1321
	global_store_dwordx4 v[192:193], v[144:147], off offset:16
.LBB0_1321:
	s_andn2_saveexec_b64 s[64:65], s[64:65]
	s_cbranch_execz .LBB0_1325
	v_add_co_u32_e32 v162, vcc, 0x2000, v194
	s_nop 1
	v_addc_co_u32_e32 v163, vcc, 0, v195, vcc
	v_mov_b32_e32 v168, v218
	v_mov_b32_e32 v169, v219
	v_mov_b32_e32 v170, v220
	v_mov_b32_e32 v171, v221
	s_waitcnt lgkmcnt(0)
	v_mov_b64_e32 v[164:165], v[168:169]
	v_mov_b64_e32 v[166:167], v[170:171]
	s_and_saveexec_b64 s[66:67], s[6:7]
	s_cbranch_execz .LBB0_1324
	v_mov_b32_e32 v164, v222
	v_mov_b32_e32 v165, v223
	v_mov_b32_e32 v166, v224
	v_mov_b32_e32 v167, v225
	v_mov_b64_e32 v[158:159], v[168:169]
	v_mov_b64_e32 v[160:161], v[170:171]

.LBB0_1325:
	s_or_b64 exec, exec, s[64:65]
	s_waitcnt lgkmcnt(0)
	v_pk_fma_f32 v[162:163], v[62:63], v[166:167], v[66:67]
	s_nop 0
	v_pk_fma_f32 v[160:161], v[54:55], v[160:161], v[162:163]
	s_nop 0
	v_pk_fma_f32 v[160:161], v[146:147], v[58:59], v[160:161]
	s_nop 0
	v_mul_f32_e32 v162, 0xbfb8aa3b, v161
	v_exp_f32_e32 v166, v162
	v_pk_fma_f32 v[162:163], v[60:61], v[164:165], v[64:65]
	v_mul_f32_e32 v164, 0xbfb8aa3b, v160
	v_exp_f32_e32 v164, v164
	v_add_f32_e32 v165, 1.0, v166
	v_rcp_f32_e32 v165, v165
	v_pk_fma_f32 v[158:159], v[52:53], v[158:159], v[162:163]
	v_add_f32_e32 v162, 1.0, v164
	v_pk_fma_f32 v[158:159], v[144:145], v[56:57], v[158:159]
	v_mul_f32_e32 v161, v161, v165
	v_mul_f32_e32 v155, v155, v161
	v_rcp_f32_e32 v161, v162
	v_mul_f32_e32 v162, 0xbfb8aa3b, v159
	v_mul_f32_e32 v163, 0xbfb8aa3b, v158
	v_exp_f32_e32 v162, v162
	v_exp_f32_e32 v163, v163
	v_mul_f32_e32 v160, v160, v161
	v_mul_f32_e32 v154, v154, v160
	v_add_f32_e32 v161, 1.0, v162
	v_add_f32_e32 v162, 1.0, v163
	v_rcp_f32_e32 v161, v161
	v_rcp_f32_e32 v162, v162
	v_mul_f32_e32 v159, v159, v161
	v_mul_f32_e32 v158, v158, v162
	v_mul_f32_e32 v153, v153, v159
	v_mul_f32_e32 v152, v152, v158
	v_cvt_pk_bf16_f32 v158, v152, v153
	v_mov_b64_e32 v[152:153], s[16:17]
	v_mad_i64_i32 v[152:153], s[46:47], v209, s82, v[152:153]
	v_lshl_add_u64 v[152:153], v[190:191], 1, v[152:153]
	v_cvt_pk_bf16_f32 v159, v154, v155
	global_store_dwordx4 v[152:153], v[156:159], off
	v_add_u32_e32 v152, 0xffff8010, v209
	v_ashrrev_i32_e32 v162, 2, v152
	v_ashrrev_i32_e32 v163, 31, v162
	v_lshl_add_u64 v[152:153], v[162:163], 1, v[184:185]
	v_mad_u64_u32 v[160:161], s[46:47], v152, s80, 0
	v_mad_i32_i24 v161, v153, s80, v161
	v_mov_b32_e32 v152, 0
	v_mov_b32_e32 v156, 0
	v_mov_b32_e32 v153, 0
	v_mov_b32_e32 v157, 0
	v_mov_b32_e32 v154, 0
	v_mov_b32_e32 v158, 0
	v_mov_b32_e32 v155, 0
	v_mov_b32_e32 v159, 0
	v_mov_b32_dpp v152, v148 row_ror:1 row_mask:0xf bank_mask:0xf
	v_mov_b32_dpp v156, v148 row_ror:2 row_mask:0xf bank_mask:0xf
	v_mov_b32_dpp v153, v149 row_ror:1 row_mask:0xf bank_mask:0xf
	v_mov_b32_dpp v157, v149 row_ror:2 row_mask:0xf bank_mask:0xf
	v_mov_b32_dpp v154, v150 row_ror:1 row_mask:0xf bank_mask:0xf
	v_mov_b32_dpp v158, v150 row_ror:2 row_mask:0xf bank_mask:0xf
	v_mov_b32_dpp v155, v151 row_ror:1 row_mask:0xf bank_mask:0xf
	v_mov_b32_dpp v159, v151 row_ror:2 row_mask:0xf bank_mask:0xf
	v_lshl_add_u64 v[148:149], s[18:19], 0, v[160:161]
	v_mov_b32_dpp v152, v132 row_shr:1 row_mask:0xf bank_mask:0xf
	v_mov_b32_dpp v156, v132 row_shr:2 row_mask:0xf bank_mask:0xf
	v_mov_b32_dpp v153, v133 row_shr:1 row_mask:0xf bank_mask:0xf
	v_mov_b32_dpp v157, v133 row_shr:2 row_mask:0xf bank_mask:0xf
	v_mov_b32_dpp v154, v134 row_shr:1 row_mask:0xf bank_mask:0xf
	v_mov_b32_dpp v158, v134 row_shr:2 row_mask:0xf bank_mask:0xf
	v_mov_b32_dpp v155, v135 row_shr:1 row_mask:0xf bank_mask:0xf
	v_mov_b32_dpp v159, v135 row_shr:2 row_mask:0xf bank_mask:0xf
	v_lshl_add_u64 v[160:161], v[190:191], 2, v[148:149]
	s_and_saveexec_b64 s[46:47], s[28:29]
	s_xor_b64 s[64:65], exec, s[46:47]
	s_cbranch_execz .LBB0_1327
	global_store_dwordx4 v[160:161], v[132:135], off
.LBB0_1327:
	s_or_saveexec_b64 s[64:65], s[64:65]
	v_mad_i64_i32 v[148:149], s[46:47], v162, s81, 0
	v_lshl_add_u64 v[148:149], s[12:13], 0, v[148:149]
	v_lshl_add_u64 v[162:163], v[190:191], 2, v[148:149]
	s_xor_b64 exec, exec, s[64:65]
	s_cbranch_execz .LBB0_1331
	v_add_co_u32_e32 v148, vcc, 0x2000, v162
	s_nop 1
	v_addc_co_u32_e32 v149, vcc, 0, v163, vcc
	v_mov_b32_e32 v148, v226
	v_mov_b32_e32 v149, v227
	v_mov_b32_e32 v150, v228
	v_mov_b32_e32 v151, v229
	s_waitcnt lgkmcnt(0)
	v_mov_b64_e32 v[158:159], v[150:151]
	v_mov_b64_e32 v[156:157], v[148:149]
	s_and_saveexec_b64 s[66:67], s[6:7]
	s_cbranch_execz .LBB0_1330
	v_mov_b32_e32 v156, v230
	v_mov_b32_e32 v157, v231
	v_mov_b32_e32 v158, v232
	v_mov_b32_e32 v159, v233
	v_mov_b64_e32 v[154:155], v[150:151]
	v_mov_b64_e32 v[152:153], v[148:149]

.LBB0_1331:
	s_or_b64 exec, exec, s[64:65]
	s_waitcnt lgkmcnt(0)
	v_pk_fma_f32 v[148:149], v[86:87], v[158:159], v[90:91]
	s_nop 0
	v_pk_fma_f32 v[148:149], v[78:79], v[154:155], v[148:149]
	s_nop 0
	v_pk_fma_f32 v[148:149], v[134:135], v[82:83], v[148:149]
	s_nop 0
	v_mul_f32_e32 v150, 0xbfb8aa3b, v149
	v_exp_f32_e32 v154, v150
	v_mul_f32_e32 v155, 0xbfb8aa3b, v148
	v_exp_f32_e32 v155, v155
	v_pk_fma_f32 v[150:151], v[84:85], v[156:157], v[88:89]
	v_add_f32_e32 v154, 1.0, v154
	v_rcp_f32_e32 v154, v154
	v_pk_fma_f32 v[150:151], v[76:77], v[152:153], v[150:151]
	v_add_f32_e32 v152, 1.0, v155
	v_pk_fma_f32 v[150:151], v[132:133], v[80:81], v[150:151]
	v_mul_f32_e32 v149, v149, v154
	v_mul_f32_e32 v143, v143, v149
	v_rcp_f32_e32 v149, v152
	v_mul_f32_e32 v152, 0xbfb8aa3b, v151
	v_exp_f32_e32 v152, v152
	v_mul_f32_e32 v153, 0xbfb8aa3b, v150
	v_exp_f32_e32 v153, v153
	v_mul_f32_e32 v148, v148, v149
	v_add_f32_e32 v149, 1.0, v152
	v_rcp_f32_e32 v149, v149
	v_add_f32_e32 v152, 1.0, v153
	v_rcp_f32_e32 v152, v152
	v_mul_f32_e32 v142, v142, v148
	v_mul_f32_e32 v148, v151, v149
	v_mul_f32_e32 v141, v141, v148
	v_mul_f32_e32 v148, v150, v152
	v_mul_f32_e32 v140, v140, v148
	v_cvt_pk_bf16_f32 v140, v140, v141
	v_cvt_pk_bf16_f32 v141, v142, v143
	v_mov_b32_e32 v142, 0
	v_mov_b32_e32 v148, 0
	v_mov_b32_e32 v143, 0
	v_mov_b32_e32 v149, 0
	v_mov_b32_dpp v142, v144 row_ror:1 row_mask:0xf bank_mask:0xf
	v_mov_b32_dpp v148, v144 row_ror:2 row_mask:0xf bank_mask:0xf
	v_mov_b32_dpp v143, v145 row_ror:1 row_mask:0xf bank_mask:0xf
	v_mov_b32_dpp v149, v145 row_ror:2 row_mask:0xf bank_mask:0xf
	v_mov_b32_e32 v144, 0
	v_mov_b32_e32 v150, 0
	v_mov_b32_e32 v145, 0
	v_mov_b32_e32 v151, 0
	v_mov_b32_dpp v144, v146 row_ror:1 row_mask:0xf bank_mask:0xf
	v_mov_b32_dpp v150, v146 row_ror:2 row_mask:0xf bank_mask:0xf
	v_mov_b32_dpp v145, v147 row_ror:1 row_mask:0xf bank_mask:0xf
	v_mov_b32_dpp v151, v147 row_ror:2 row_mask:0xf bank_mask:0xf
	v_mov_b32_dpp v142, v128 row_shr:1 row_mask:0xf bank_mask:0xf
	v_mov_b32_dpp v148, v128 row_shr:2 row_mask:0xf bank_mask:0xf
	v_mov_b32_dpp v143, v129 row_shr:1 row_mask:0xf bank_mask:0xf
	v_mov_b32_dpp v149, v129 row_shr:2 row_mask:0xf bank_mask:0xf
	v_mov_b32_dpp v144, v130 row_shr:1 row_mask:0xf bank_mask:0xf
	v_mov_b32_dpp v150, v130 row_shr:2 row_mask:0xf bank_mask:0xf
	v_mov_b32_dpp v145, v131 row_shr:1 row_mask:0xf bank_mask:0xf
	v_mov_b32_dpp v151, v131 row_shr:2 row_mask:0xf bank_mask:0xf
	s_and_saveexec_b64 s[46:47], s[28:29]
	s_xor_b64 s[64:65], exec, s[46:47]
	s_cbranch_execz .LBB0_1333
	global_store_dwordx4 v[160:161], v[128:131], off offset:16
.LBB0_1333:
	s_andn2_saveexec_b64 s[64:65], s[64:65]
	s_cbranch_execz .LBB0_1337
	v_add_co_u32_e32 v146, vcc, 0x2000, v162
	s_nop 1
	v_addc_co_u32_e32 v147, vcc, 0, v163, vcc
	v_mov_b32_e32 v152, v234
	v_mov_b32_e32 v153, v235
	v_mov_b32_e32 v154, v236
	v_mov_b32_e32 v155, v237
	s_waitcnt lgkmcnt(0)
	v_mov_b64_e32 v[148:149], v[152:153]
	v_mov_b64_e32 v[150:151], v[154:155]
	s_and_saveexec_b64 s[66:67], s[6:7]
	s_cbranch_execz .LBB0_1336
	v_mov_b32_e32 v148, v238
	v_mov_b32_e32 v149, v239
	v_mov_b32_e32 v150, v240
	v_mov_b32_e32 v151, v241
	v_mov_b64_e32 v[142:143], v[152:153]
	v_mov_b64_e32 v[144:145], v[154:155]

.LBB0_1337:
	s_or_b64 exec, exec, s[64:65]
	s_waitcnt lgkmcnt(0)
	v_pk_fma_f32 v[146:147], v[62:63], v[150:151], v[66:67]
	v_or_b32_e32 v151, 16, v209
	v_pk_fma_f32 v[144:145], v[54:55], v[144:145], v[146:147]
	s_nop 0
	v_pk_fma_f32 v[144:145], v[130:131], v[58:59], v[144:145]
	s_nop 0
	v_mul_f32_e32 v146, 0xbfb8aa3b, v145
	v_exp_f32_e32 v150, v146
	v_pk_fma_f32 v[146:147], v[60:61], v[148:149], v[64:65]
	s_nop 0
	v_pk_fma_f32 v[142:143], v[52:53], v[142:143], v[146:147]
	v_add_f32_e32 v146, 1.0, v150
	v_rcp_f32_e32 v146, v146
	v_mul_f32_e32 v147, 0xbfb8aa3b, v144
	v_exp_f32_e32 v147, v147
	v_pk_fma_f32 v[142:143], v[128:129], v[56:57], v[142:143]
	v_mul_f32_e32 v145, v145, v146
	v_mul_f32_e32 v139, v139, v145
	v_add_f32_e32 v145, 1.0, v147
	v_mul_f32_e32 v146, 0xbfb8aa3b, v143
	v_mul_f32_e32 v147, 0xbfb8aa3b, v142
	v_rcp_f32_e32 v145, v145
	v_exp_f32_e32 v146, v146
	v_exp_f32_e32 v147, v147
	v_mul_f32_e32 v144, v144, v145
	v_add_f32_e32 v145, 1.0, v146
	v_add_f32_e32 v146, 1.0, v147
	v_rcp_f32_e32 v145, v145
	v_rcp_f32_e32 v146, v146
	v_mul_f32_e32 v138, v138, v144
	v_mul_f32_e32 v143, v143, v145
	v_mul_f32_e32 v142, v142, v146
	v_mul_f32_e32 v137, v137, v143
	v_mul_f32_e32 v136, v136, v142
	v_cvt_pk_bf16_f32 v142, v136, v137
	v_mov_b64_e32 v[136:137], s[16:17]
	v_mad_i64_i32 v[136:137], s[46:47], v151, s82, v[136:137]
	v_lshl_add_u64 v[136:137], v[190:191], 1, v[136:137]
	v_cvt_pk_bf16_f32 v143, v138, v139
	global_store_dwordx4 v[136:137], v[140:143], off
	v_add_u32_e32 v136, 0xffff8020, v209
	v_ashrrev_i32_e32 v146, 2, v136
	v_ashrrev_i32_e32 v147, 31, v146
	v_lshl_add_u64 v[136:137], v[146:147], 1, v[184:185]
	v_mad_u64_u32 v[144:145], s[46:47], v136, s80, 0
	v_mad_i32_i24 v145, v137, s80, v145
	v_mov_b32_e32 v136, 0
	v_mov_b32_e32 v140, 0
	v_mov_b32_e32 v137, 0
	v_mov_b32_e32 v141, 0
	v_mov_b32_e32 v138, 0
	v_mov_b32_e32 v142, 0
	v_mov_b32_e32 v139, 0
	v_mov_b32_e32 v143, 0
	v_mov_b32_dpp v136, v132 row_ror:1 row_mask:0xf bank_mask:0xf
	v_mov_b32_dpp v140, v132 row_ror:2 row_mask:0xf bank_mask:0xf
	v_mov_b32_dpp v137, v133 row_ror:1 row_mask:0xf bank_mask:0xf
	v_mov_b32_dpp v141, v133 row_ror:2 row_mask:0xf bank_mask:0xf
	v_mov_b32_dpp v138, v134 row_ror:1 row_mask:0xf bank_mask:0xf
	v_mov_b32_dpp v142, v134 row_ror:2 row_mask:0xf bank_mask:0xf
	v_mov_b32_dpp v139, v135 row_ror:1 row_mask:0xf bank_mask:0xf
	v_mov_b32_dpp v143, v135 row_ror:2 row_mask:0xf bank_mask:0xf
	v_lshl_add_u64 v[132:133], s[18:19], 0, v[144:145]
	v_mov_b32_dpp v136, v116 row_shr:1 row_mask:0xf bank_mask:0xf
	v_mov_b32_dpp v140, v116 row_shr:2 row_mask:0xf bank_mask:0xf
	v_mov_b32_dpp v137, v117 row_shr:1 row_mask:0xf bank_mask:0xf
	v_mov_b32_dpp v141, v117 row_shr:2 row_mask:0xf bank_mask:0xf
	v_mov_b32_dpp v138, v118 row_shr:1 row_mask:0xf bank_mask:0xf
	v_mov_b32_dpp v142, v118 row_shr:2 row_mask:0xf bank_mask:0xf
	v_mov_b32_dpp v139, v119 row_shr:1 row_mask:0xf bank_mask:0xf
	v_mov_b32_dpp v143, v119 row_shr:2 row_mask:0xf bank_mask:0xf
	v_lshl_add_u64 v[144:145], v[190:191], 2, v[132:133]
	s_mov_b64 s[72:73], 0x2c000
	v_lshl_add_u64 v[244:245], v[242:243], 0, s[72:73]
	s_mov_b64 s[72:73], 0x2c00
	v_lshl_add_u64 v[246:247], v[244:245], 0, s[72:73]
	s_mov_b64 s[72:73], 0x16000
	v_lshl_add_u64 v[248:249], v[244:245], 0, s[72:73]
	s_mov_b64 s[72:73], 0x2c00
	v_lshl_add_u64 v[250:251], v[248:249], 0, s[72:73]
	global_load_dwordx4 v[210:213], v[246:247], off
	global_load_dwordx4 v[214:217], v[244:245], off
	global_load_dwordx4 v[218:221], v[246:247], off offset:16
	global_load_dwordx4 v[222:225], v[244:245], off offset:16
	global_load_dwordx4 v[226:229], v[250:251], off
	global_load_dwordx4 v[230:233], v[248:249], off
	global_load_dwordx4 v[234:237], v[250:251], off offset:16
	global_load_dwordx4 v[238:241], v[248:249], off offset:16
	s_and_saveexec_b64 s[46:47], s[28:29]
	s_xor_b64 s[64:65], exec, s[46:47]
	s_cbranch_execz .LBB0_1339
	global_store_dwordx4 v[144:145], v[116:119], off
.LBB0_1339:
	s_waitcnt vmcnt(1)
	s_or_saveexec_b64 s[64:65], s[64:65]
	v_mad_i64_i32 v[132:133], s[46:47], v146, s81, 0
	v_lshl_add_u64 v[132:133], s[12:13], 0, v[132:133]
	v_lshl_add_u64 v[146:147], v[190:191], 2, v[132:133]
	s_xor_b64 exec, exec, s[64:65]
	s_cbranch_execz .LBB0_1343
	v_add_co_u32_e32 v132, vcc, 0x2000, v146
	s_nop 1
	v_addc_co_u32_e32 v133, vcc, 0, v147, vcc
	v_mov_b32_e32 v132, v210
	v_mov_b32_e32 v133, v211
	v_mov_b32_e32 v134, v212
	v_mov_b32_e32 v135, v213
	s_waitcnt lgkmcnt(0)
	v_mov_b64_e32 v[142:143], v[134:135]
	v_mov_b64_e32 v[140:141], v[132:133]
	s_and_saveexec_b64 s[66:67], s[6:7]
	s_cbranch_execz .LBB0_1342
	v_mov_b32_e32 v140, v214
	v_mov_b32_e32 v141, v215
	v_mov_b32_e32 v142, v216
	v_mov_b32_e32 v143, v217
	v_mov_b64_e32 v[138:139], v[134:135]
	v_mov_b64_e32 v[136:137], v[132:133]

.LBB0_1343:
	s_or_b64 exec, exec, s[64:65]
	s_waitcnt lgkmcnt(0)
	v_pk_fma_f32 v[132:133], v[86:87], v[142:143], v[90:91]
	s_nop 0
	v_pk_fma_f32 v[132:133], v[78:79], v[138:139], v[132:133]
	s_nop 0
	v_pk_fma_f32 v[132:133], v[118:119], v[82:83], v[132:133]
	s_nop 0
	v_mul_f32_e32 v134, 0xbfb8aa3b, v133
	v_exp_f32_e32 v138, v134
	v_mul_f32_e32 v139, 0xbfb8aa3b, v132
	v_exp_f32_e32 v139, v139
	v_pk_fma_f32 v[134:135], v[84:85], v[140:141], v[88:89]
	v_add_f32_e32 v138, 1.0, v138
	v_rcp_f32_e32 v138, v138
	v_pk_fma_f32 v[134:135], v[76:77], v[136:137], v[134:135]
	v_add_f32_e32 v136, 1.0, v139
	v_pk_fma_f32 v[134:135], v[116:117], v[80:81], v[134:135]
	v_mul_f32_e32 v133, v133, v138
	v_mul_f32_e32 v127, v127, v133
	v_rcp_f32_e32 v133, v136
	v_mul_f32_e32 v136, 0xbfb8aa3b, v135
	v_exp_f32_e32 v136, v136
	v_mul_f32_e32 v137, 0xbfb8aa3b, v134
	v_exp_f32_e32 v137, v137
	v_mul_f32_e32 v132, v132, v133
	v_add_f32_e32 v133, 1.0, v136
	v_rcp_f32_e32 v133, v133
	v_add_f32_e32 v136, 1.0, v137
	v_rcp_f32_e32 v136, v136
	v_mul_f32_e32 v126, v126, v132
	v_mul_f32_e32 v132, v135, v133
	v_mul_f32_e32 v125, v125, v132
	v_mul_f32_e32 v132, v134, v136
	v_mul_f32_e32 v124, v124, v132
	v_cvt_pk_bf16_f32 v124, v124, v125
	v_cvt_pk_bf16_f32 v125, v126, v127
	v_mov_b32_e32 v126, 0
	v_mov_b32_e32 v132, 0
	v_mov_b32_e32 v127, 0
	v_mov_b32_e32 v133, 0
	v_mov_b32_dpp v126, v128 row_ror:1 row_mask:0xf bank_mask:0xf
	v_mov_b32_dpp v132, v128 row_ror:2 row_mask:0xf bank_mask:0xf
	v_mov_b32_dpp v127, v129 row_ror:1 row_mask:0xf bank_mask:0xf
	v_mov_b32_dpp v133, v129 row_ror:2 row_mask:0xf bank_mask:0xf
	v_mov_b32_e32 v128, 0
	v_mov_b32_e32 v134, 0
	v_mov_b32_e32 v129, 0
	v_mov_b32_e32 v135, 0
	v_mov_b32_dpp v128, v130 row_ror:1 row_mask:0xf bank_mask:0xf
	v_mov_b32_dpp v134, v130 row_ror:2 row_mask:0xf bank_mask:0xf
	v_mov_b32_dpp v129, v131 row_ror:1 row_mask:0xf bank_mask:0xf
	v_mov_b32_dpp v135, v131 row_ror:2 row_mask:0xf bank_mask:0xf
	v_mov_b32_dpp v126, v108 row_shr:1 row_mask:0xf bank_mask:0xf
	v_mov_b32_dpp v132, v108 row_shr:2 row_mask:0xf bank_mask:0xf
	v_mov_b32_dpp v127, v109 row_shr:1 row_mask:0xf bank_mask:0xf
	v_mov_b32_dpp v133, v109 row_shr:2 row_mask:0xf bank_mask:0xf
	v_mov_b32_dpp v128, v110 row_shr:1 row_mask:0xf bank_mask:0xf
	v_mov_b32_dpp v134, v110 row_shr:2 row_mask:0xf bank_mask:0xf
	v_mov_b32_dpp v129, v111 row_shr:1 row_mask:0xf bank_mask:0xf
	v_mov_b32_dpp v135, v111 row_shr:2 row_mask:0xf bank_mask:0xf
	s_and_saveexec_b64 s[46:47], s[28:29]
	s_xor_b64 s[64:65], exec, s[46:47]
	s_cbranch_execz .LBB0_1345
	global_store_dwordx4 v[144:145], v[108:111], off offset:16
.LBB0_1345:
	s_andn2_saveexec_b64 s[64:65], s[64:65]
	s_cbranch_execz .LBB0_1349
	v_add_co_u32_e32 v130, vcc, 0x2000, v146
	s_nop 1
	v_addc_co_u32_e32 v131, vcc, 0, v147, vcc
	v_mov_b32_e32 v136, v218
	v_mov_b32_e32 v137, v219
	v_mov_b32_e32 v138, v220
	v_mov_b32_e32 v139, v221
	s_waitcnt lgkmcnt(0)
	v_mov_b64_e32 v[132:133], v[136:137]
	v_mov_b64_e32 v[134:135], v[138:139]
	s_and_saveexec_b64 s[66:67], s[6:7]
	s_cbranch_execz .LBB0_1348
	v_mov_b32_e32 v132, v222
	v_mov_b32_e32 v133, v223
	v_mov_b32_e32 v134, v224
	v_mov_b32_e32 v135, v225
	v_mov_b64_e32 v[126:127], v[136:137]
	v_mov_b64_e32 v[128:129], v[138:139]

.LBB0_1349:
	s_or_b64 exec, exec, s[64:65]
	s_waitcnt lgkmcnt(0)
	v_pk_fma_f32 v[130:131], v[62:63], v[134:135], v[66:67]
	v_or_b32_e32 v135, 32, v209
	v_pk_fma_f32 v[128:129], v[54:55], v[128:129], v[130:131]
	s_nop 0
	v_pk_fma_f32 v[128:129], v[110:111], v[58:59], v[128:129]
	s_nop 0
	v_mul_f32_e32 v130, 0xbfb8aa3b, v129
	v_exp_f32_e32 v134, v130
	v_pk_fma_f32 v[130:131], v[60:61], v[132:133], v[64:65]
	s_nop 0
	v_pk_fma_f32 v[126:127], v[52:53], v[126:127], v[130:131]
	v_add_f32_e32 v130, 1.0, v134
	v_rcp_f32_e32 v130, v130
	v_mul_f32_e32 v131, 0xbfb8aa3b, v128
	v_exp_f32_e32 v131, v131
	v_pk_fma_f32 v[126:127], v[108:109], v[56:57], v[126:127]
	v_mul_f32_e32 v129, v129, v130
	v_mul_f32_e32 v123, v123, v129
	v_add_f32_e32 v129, 1.0, v131
	v_mul_f32_e32 v130, 0xbfb8aa3b, v127
	v_mul_f32_e32 v131, 0xbfb8aa3b, v126
	v_rcp_f32_e32 v129, v129
	v_exp_f32_e32 v130, v130
	v_exp_f32_e32 v131, v131
	v_mul_f32_e32 v128, v128, v129
	v_add_f32_e32 v129, 1.0, v130
	v_add_f32_e32 v130, 1.0, v131
	v_rcp_f32_e32 v129, v129
	v_rcp_f32_e32 v130, v130
	v_mul_f32_e32 v122, v122, v128
	v_mul_f32_e32 v127, v127, v129
	v_mul_f32_e32 v126, v126, v130
	v_mul_f32_e32 v121, v121, v127
	v_mul_f32_e32 v120, v120, v126
	v_cvt_pk_bf16_f32 v126, v120, v121
	v_mov_b64_e32 v[120:121], s[16:17]
	v_mad_i64_i32 v[120:121], s[46:47], v135, s82, v[120:121]
	v_lshl_add_u64 v[120:121], v[190:191], 1, v[120:121]
	v_cvt_pk_bf16_f32 v127, v122, v123
	global_store_dwordx4 v[120:121], v[124:127], off
	v_add_u32_e32 v120, 0xffff8030, v209
	v_ashrrev_i32_e32 v130, 2, v120
	v_ashrrev_i32_e32 v131, 31, v130
	v_lshl_add_u64 v[120:121], v[130:131], 1, v[184:185]
	v_mad_u64_u32 v[128:129], s[46:47], v120, s80, 0
	v_mad_i32_i24 v129, v121, s80, v129
	v_mov_b32_e32 v120, 0
	v_mov_b32_e32 v124, 0
	v_mov_b32_e32 v121, 0
	v_mov_b32_e32 v125, 0
	v_mov_b32_e32 v122, 0
	v_mov_b32_e32 v126, 0
	v_mov_b32_e32 v123, 0
	v_mov_b32_e32 v127, 0
	v_mov_b32_dpp v120, v116 row_ror:1 row_mask:0xf bank_mask:0xf
	v_mov_b32_dpp v124, v116 row_ror:2 row_mask:0xf bank_mask:0xf
	v_mov_b32_dpp v121, v117 row_ror:1 row_mask:0xf bank_mask:0xf
	v_mov_b32_dpp v125, v117 row_ror:2 row_mask:0xf bank_mask:0xf
	v_mov_b32_dpp v122, v118 row_ror:1 row_mask:0xf bank_mask:0xf
	v_mov_b32_dpp v126, v118 row_ror:2 row_mask:0xf bank_mask:0xf
	v_mov_b32_dpp v123, v119 row_ror:1 row_mask:0xf bank_mask:0xf
	v_mov_b32_dpp v127, v119 row_ror:2 row_mask:0xf bank_mask:0xf
	v_lshl_add_u64 v[116:117], s[18:19], 0, v[128:129]
	v_mov_b32_dpp v120, v112 row_shr:1 row_mask:0xf bank_mask:0xf
	v_mov_b32_dpp v124, v112 row_shr:2 row_mask:0xf bank_mask:0xf
	v_mov_b32_dpp v121, v113 row_shr:1 row_mask:0xf bank_mask:0xf
	v_mov_b32_dpp v125, v113 row_shr:2 row_mask:0xf bank_mask:0xf
	v_mov_b32_dpp v122, v114 row_shr:1 row_mask:0xf bank_mask:0xf
	v_mov_b32_dpp v126, v114 row_shr:2 row_mask:0xf bank_mask:0xf
	v_mov_b32_dpp v123, v115 row_shr:1 row_mask:0xf bank_mask:0xf
	v_mov_b32_dpp v127, v115 row_shr:2 row_mask:0xf bank_mask:0xf
	v_lshl_add_u64 v[128:129], v[190:191], 2, v[116:117]
	s_and_saveexec_b64 s[46:47], s[28:29]
	s_xor_b64 s[64:65], exec, s[46:47]
	s_cbranch_execz .LBB0_1351
	global_store_dwordx4 v[128:129], v[112:115], off
.LBB0_1351:
	s_or_saveexec_b64 s[64:65], s[64:65]
	v_mad_i64_i32 v[116:117], s[46:47], v130, s81, 0
	v_lshl_add_u64 v[116:117], s[12:13], 0, v[116:117]
	v_lshl_add_u64 v[130:131], v[190:191], 2, v[116:117]
	s_xor_b64 exec, exec, s[64:65]
	s_cbranch_execz .LBB0_1355
	v_add_co_u32_e32 v116, vcc, 0x2000, v130
	s_nop 1
	v_addc_co_u32_e32 v117, vcc, 0, v131, vcc
	v_mov_b32_e32 v116, v226
	v_mov_b32_e32 v117, v227
	v_mov_b32_e32 v118, v228
	v_mov_b32_e32 v119, v229
	s_waitcnt lgkmcnt(0)
	v_mov_b64_e32 v[126:127], v[118:119]
	v_mov_b64_e32 v[124:125], v[116:117]
	s_and_saveexec_b64 s[66:67], s[6:7]
	s_cbranch_execz .LBB0_1354
	v_mov_b32_e32 v124, v230
	v_mov_b32_e32 v125, v231
	v_mov_b32_e32 v126, v232
	v_mov_b32_e32 v127, v233
	v_mov_b64_e32 v[122:123], v[118:119]
	v_mov_b64_e32 v[120:121], v[116:117]

.LBB0_1355:
	s_or_b64 exec, exec, s[64:65]
	s_waitcnt lgkmcnt(0)
	v_pk_fma_f32 v[116:117], v[86:87], v[126:127], v[90:91]
	s_nop 0
	v_pk_fma_f32 v[116:117], v[78:79], v[122:123], v[116:117]
	s_nop 0
	v_pk_fma_f32 v[114:115], v[114:115], v[82:83], v[116:117]
	s_nop 0
	v_mul_f32_e32 v116, 0xbfb8aa3b, v115
	v_exp_f32_e32 v118, v116
	v_mul_f32_e32 v119, 0xbfb8aa3b, v114
	v_exp_f32_e32 v119, v119
	v_pk_fma_f32 v[116:117], v[84:85], v[124:125], v[88:89]
	v_add_f32_e32 v118, 1.0, v118
	v_rcp_f32_e32 v118, v118
	v_pk_fma_f32 v[116:117], v[76:77], v[120:121], v[116:117]
	v_mul_f32_e32 v115, v115, v118
	v_pk_fma_f32 v[112:113], v[112:113], v[80:81], v[116:117]
	v_add_f32_e32 v116, 1.0, v119
	v_mul_f32_e32 v107, v107, v115
	v_rcp_f32_e32 v115, v116
	v_mul_f32_e32 v116, 0xbfb8aa3b, v113
	v_mul_f32_e32 v117, 0xbfb8aa3b, v112
	v_exp_f32_e32 v116, v116
	v_exp_f32_e32 v117, v117
	v_mul_f32_e32 v114, v114, v115
	v_mul_f32_e32 v106, v106, v114
	v_add_f32_e32 v115, 1.0, v116
	v_add_f32_e32 v116, 1.0, v117
	v_rcp_f32_e32 v115, v115
	v_rcp_f32_e32 v116, v116
	v_mov_b32_e32 v114, 0
	v_mul_f32_e32 v113, v113, v115
	v_mul_f32_e32 v112, v112, v116
	v_mul_f32_e32 v105, v105, v113
	v_mul_f32_e32 v104, v104, v112
	v_cvt_pk_bf16_f32 v104, v104, v105
	v_cvt_pk_bf16_f32 v105, v106, v107
	v_mov_b32_e32 v106, 0
	v_mov_b32_e32 v112, 0
	v_mov_b32_e32 v107, 0
	v_mov_b32_e32 v113, 0
	v_mov_b32_dpp v106, v108 row_ror:1 row_mask:0xf bank_mask:0xf
	v_mov_b32_dpp v112, v108 row_ror:2 row_mask:0xf bank_mask:0xf
	v_mov_b32_dpp v107, v109 row_ror:1 row_mask:0xf bank_mask:0xf
	v_mov_b32_dpp v113, v109 row_ror:2 row_mask:0xf bank_mask:0xf
	v_mov_b32_e32 v108, 0
	v_mov_b32_e32 v109, 0
	v_mov_b32_e32 v115, 0
	v_mov_b32_dpp v108, v110 row_ror:1 row_mask:0xf bank_mask:0xf
	v_mov_b32_dpp v114, v110 row_ror:2 row_mask:0xf bank_mask:0xf
	v_mov_b32_dpp v109, v111 row_ror:1 row_mask:0xf bank_mask:0xf
	v_mov_b32_dpp v115, v111 row_ror:2 row_mask:0xf bank_mask:0xf
	v_mov_b32_dpp v106, v100 row_shr:1 row_mask:0xf bank_mask:0xf
	v_mov_b32_dpp v112, v100 row_shr:2 row_mask:0xf bank_mask:0xf
	v_mov_b32_dpp v107, v101 row_shr:1 row_mask:0xf bank_mask:0xf
	v_mov_b32_dpp v113, v101 row_shr:2 row_mask:0xf bank_mask:0xf
	v_mov_b32_dpp v108, v102 row_shr:1 row_mask:0xf bank_mask:0xf
	v_mov_b32_dpp v114, v102 row_shr:2 row_mask:0xf bank_mask:0xf
	v_mov_b32_dpp v109, v103 row_shr:1 row_mask:0xf bank_mask:0xf
	v_mov_b32_dpp v115, v103 row_shr:2 row_mask:0xf bank_mask:0xf
	s_and_saveexec_b64 s[46:47], s[28:29]
	s_xor_b64 s[64:65], exec, s[46:47]
	s_cbranch_execz .LBB0_1357
	global_store_dwordx4 v[128:129], v[100:103], off offset:16
.LBB0_1357:
	s_andn2_saveexec_b64 s[64:65], s[64:65]
	s_cbranch_execz .LBB0_1361
	v_add_co_u32_e32 v110, vcc, 0x2000, v130
	s_nop 1
	v_addc_co_u32_e32 v111, vcc, 0, v131, vcc
	v_mov_b32_e32 v116, v234
	v_mov_b32_e32 v117, v235
	v_mov_b32_e32 v118, v236
	v_mov_b32_e32 v119, v237
	s_waitcnt lgkmcnt(0)
	v_mov_b64_e32 v[112:113], v[116:117]
	v_mov_b64_e32 v[114:115], v[118:119]
	s_and_saveexec_b64 s[66:67], s[6:7]
	s_cbranch_execz .LBB0_1360
	v_mov_b32_e32 v112, v238
	v_mov_b32_e32 v113, v239
	v_mov_b32_e32 v114, v240
	v_mov_b32_e32 v115, v241
	v_mov_b64_e32 v[106:107], v[116:117]
	v_mov_b64_e32 v[108:109], v[118:119]

.LBB0_1361:
	s_or_b64 exec, exec, s[64:65]
	s_waitcnt lgkmcnt(0)
	v_pk_fma_f32 v[110:111], v[62:63], v[114:115], v[66:67]
	s_nop 0
	v_pk_fma_f32 v[108:109], v[54:55], v[108:109], v[110:111]
	v_or_b32_e32 v111, 48, v209
	v_pk_fma_f32 v[102:103], v[102:103], v[58:59], v[108:109]
	s_nop 0
	v_mul_f32_e32 v108, 0xbfb8aa3b, v103
	v_exp_f32_e32 v110, v108
	v_pk_fma_f32 v[108:109], v[60:61], v[112:113], v[64:65]
	s_nop 0
	v_pk_fma_f32 v[106:107], v[52:53], v[106:107], v[108:109]
	v_add_f32_e32 v108, 1.0, v110
	v_rcp_f32_e32 v108, v108
	v_mul_f32_e32 v109, 0xbfb8aa3b, v102
	v_exp_f32_e32 v109, v109
	v_pk_fma_f32 v[100:101], v[100:101], v[56:57], v[106:107]
	v_mul_f32_e32 v103, v103, v108
	v_mul_f32_e32 v99, v99, v103
	v_add_f32_e32 v103, 1.0, v109
	v_mul_f32_e32 v106, 0xbfb8aa3b, v101
	v_mul_f32_e32 v107, 0xbfb8aa3b, v100
	v_rcp_f32_e32 v103, v103
	v_exp_f32_e32 v106, v106
	v_exp_f32_e32 v107, v107
	v_mov_b32_e32 v108, 0
	v_mul_f32_e32 v102, v102, v103
	v_add_f32_e32 v103, 1.0, v106
	v_add_f32_e32 v106, 1.0, v107
	v_rcp_f32_e32 v103, v103
	v_rcp_f32_e32 v106, v106
	v_mul_f32_e32 v98, v98, v102
	v_mov_b32_e32 v109, 0
	v_mul_f32_e32 v101, v101, v103
	v_mul_f32_e32 v100, v100, v106
	v_mul_f32_e32 v97, v97, v101
	v_mul_f32_e32 v96, v96, v100
	v_cvt_pk_bf16_f32 v106, v96, v97
	v_mov_b64_e32 v[96:97], s[16:17]
	v_mad_i64_i32 v[96:97], s[46:47], v111, s82, v[96:97]
	v_cvt_pk_bf16_f32 v107, v98, v99
	v_lshl_add_u64 v[96:97], v[190:191], 1, v[96:97]
	global_store_dwordx4 v[96:97], v[104:107], off
	v_mov_b32_e32 v96, 0
	v_mov_b32_e32 v97, 0
	v_mov_b32_e32 v98, 0
	v_mov_b32_e32 v99, 0
	v_mov_b32_e32 v106, 0
	v_mov_b32_e32 v107, 0
	s_and_saveexec_b64 s[64:65], s[40:41]
	s_cbranch_execz .LBB0_1363
	ds_read_b128 v[106:109], v205
	ds_read_b128 v[96:99], v205 offset:16
.LBB0_1363:
	s_or_b64 exec, exec, s[64:65]
	v_add_u32_e32 v100, 0xffff8080, v209
	v_ashrrev_i32_e32 v110, 2, v100
	v_ashrrev_i32_e32 v111, 31, v110
	v_lshl_add_u64 v[100:101], v[110:111], 1, v[184:185]
	v_mad_u64_u32 v[112:113], s[46:47], v100, s80, 0
	v_mad_i32_i24 v113, v101, s80, v113
	v_mov_b32_e32 v100, 0
	v_mov_b32_e32 v104, 0
	v_mov_b32_e32 v101, 0
	v_mov_b32_e32 v105, 0
	s_waitcnt lgkmcnt(1)
	v_mov_b32_dpp v100, v106 row_ror:1 row_mask:0xf bank_mask:0xf
	v_mov_b32_dpp v104, v106 row_ror:2 row_mask:0xf bank_mask:0xf
	v_mov_b32_dpp v101, v107 row_ror:1 row_mask:0xf bank_mask:0xf
	v_mov_b32_dpp v105, v107 row_ror:2 row_mask:0xf bank_mask:0xf
	v_mov_b32_e32 v102, 0
	v_mov_b32_e32 v106, 0
	v_mov_b32_e32 v103, 0
	v_mov_b32_e32 v107, 0
	v_mov_b32_dpp v102, v108 row_ror:1 row_mask:0xf bank_mask:0xf
	v_mov_b32_dpp v106, v108 row_ror:2 row_mask:0xf bank_mask:0xf
	v_mov_b32_dpp v103, v109 row_ror:1 row_mask:0xf bank_mask:0xf
	v_mov_b32_dpp v107, v109 row_ror:2 row_mask:0xf bank_mask:0xf
	v_lshl_add_u64 v[108:109], s[18:19], 0, v[112:113]
	v_mov_b32_dpp v100, v68 row_shr:1 row_mask:0xf bank_mask:0xf
	v_mov_b32_dpp v104, v68 row_shr:2 row_mask:0xf bank_mask:0xf
	v_mov_b32_dpp v101, v69 row_shr:1 row_mask:0xf bank_mask:0xf
	v_mov_b32_dpp v105, v69 row_shr:2 row_mask:0xf bank_mask:0xf
	v_mov_b32_dpp v102, v70 row_shr:1 row_mask:0xf bank_mask:0xf
	v_mov_b32_dpp v106, v70 row_shr:2 row_mask:0xf bank_mask:0xf
	v_mov_b32_dpp v103, v71 row_shr:1 row_mask:0xf bank_mask:0xf
	v_mov_b32_dpp v107, v71 row_shr:2 row_mask:0xf bank_mask:0xf
	v_lshl_add_u64 v[112:113], v[190:191], 2, v[108:109]
	s_mov_b64 s[72:73], 0xb0000
	v_lshl_add_u64 v[244:245], v[242:243], 0, s[72:73]
	s_mov_b64 s[72:73], 0x2c00
	v_lshl_add_u64 v[246:247], v[244:245], 0, s[72:73]
	s_mov_b64 s[72:73], 0x16000
	v_lshl_add_u64 v[248:249], v[244:245], 0, s[72:73]
	s_mov_b64 s[72:73], 0x2c00
	v_lshl_add_u64 v[250:251], v[248:249], 0, s[72:73]
	global_load_dwordx4 v[210:213], v[246:247], off
	global_load_dwordx4 v[214:217], v[244:245], off
	global_load_dwordx4 v[218:221], v[246:247], off offset:16
	global_load_dwordx4 v[222:225], v[244:245], off offset:16
	global_load_dwordx4 v[226:229], v[250:251], off
	global_load_dwordx4 v[230:233], v[248:249], off
	global_load_dwordx4 v[234:237], v[250:251], off offset:16
	global_load_dwordx4 v[238:241], v[248:249], off offset:16
	s_and_saveexec_b64 s[46:47], s[28:29]
	s_xor_b64 s[64:65], exec, s[46:47]
	s_cbranch_execz .LBB0_1365
	global_store_dwordx4 v[112:113], v[68:71], off
.LBB0_1365:
	s_waitcnt vmcnt(1)
	s_or_saveexec_b64 s[64:65], s[64:65]
	v_mad_i64_i32 v[108:109], s[46:47], v110, s81, 0
	v_lshl_add_u64 v[108:109], s[12:13], 0, v[108:109]
	v_lshl_add_u64 v[114:115], v[190:191], 2, v[108:109]
	s_xor_b64 exec, exec, s[64:65]
	s_cbranch_execz .LBB0_1369
	v_add_co_u32_e32 v104, vcc, 0x2000, v114
	s_nop 1
	v_addc_co_u32_e32 v105, vcc, 0, v115, vcc
	v_mov_b32_e32 v108, v210
	v_mov_b32_e32 v109, v211
	v_mov_b32_e32 v110, v212
	v_mov_b32_e32 v111, v213
	s_waitcnt lgkmcnt(0)
	v_mov_b64_e32 v[104:105], v[108:109]
	v_mov_b64_e32 v[106:107], v[110:111]
	s_and_saveexec_b64 s[66:67], s[6:7]
	s_cbranch_execz .LBB0_1368
	v_mov_b32_e32 v104, v214
	v_mov_b32_e32 v105, v215
	v_mov_b32_e32 v106, v216
	v_mov_b32_e32 v107, v217
	v_mov_b64_e32 v[100:101], v[108:109]
	v_mov_b64_e32 v[102:103], v[110:111]

.LBB0_1369:
	s_or_b64 exec, exec, s[64:65]
	s_waitcnt lgkmcnt(0)
	v_pk_fma_f32 v[106:107], v[86:87], v[106:107], v[90:91]
	v_pk_fma_f32 v[104:105], v[84:85], v[104:105], v[88:89]
	v_pk_fma_f32 v[102:103], v[78:79], v[102:103], v[106:107]
	v_pk_fma_f32 v[100:101], v[76:77], v[100:101], v[104:105]
	v_pk_fma_f32 v[102:103], v[70:71], v[82:83], v[102:103]
	v_pk_fma_f32 v[100:101], v[68:69], v[80:81], v[100:101]
	v_mul_f32_e32 v106, 0xbfb8aa3b, v103
	v_exp_f32_e32 v106, v106
	v_mul_f32_e32 v107, 0xbfb8aa3b, v102
	v_exp_f32_e32 v107, v107
	v_mul_f32_e32 v105, 0xbfb8aa3b, v100
	v_add_f32_e32 v106, 1.0, v106
	v_rcp_f32_e32 v106, v106
	v_add_f32_e32 v104, 1.0, v107
	v_exp_f32_e32 v105, v105
	v_mul_f32_e32 v103, v103, v106
	v_mul_f32_e32 v95, v95, v103
	v_rcp_f32_e32 v103, v104
	v_mul_f32_e32 v104, 0xbfb8aa3b, v101
	v_exp_f32_e32 v104, v104
	v_mul_f32_e32 v102, v102, v103
	v_mul_f32_e32 v94, v94, v102
	v_add_f32_e32 v103, 1.0, v104
	v_add_f32_e32 v104, 1.0, v105
	v_rcp_f32_e32 v103, v103
	v_rcp_f32_e32 v104, v104
	v_mov_b32_e32 v102, 0
	v_mul_f32_e32 v101, v101, v103
	v_mul_f32_e32 v100, v100, v104
	v_mul_f32_e32 v93, v93, v101
	v_mul_f32_e32 v92, v92, v100
	v_cvt_pk_bf16_f32 v92, v92, v93
	v_cvt_pk_bf16_f32 v93, v94, v95
	v_mov_b32_e32 v94, 0
	v_mov_b32_e32 v100, 0
	v_mov_b32_e32 v95, 0
	v_mov_b32_e32 v101, 0
	v_mov_b32_dpp v94, v96 row_ror:1 row_mask:0xf bank_mask:0xf
	v_mov_b32_dpp v100, v96 row_ror:2 row_mask:0xf bank_mask:0xf
	v_mov_b32_dpp v95, v97 row_ror:1 row_mask:0xf bank_mask:0xf
	v_mov_b32_dpp v101, v97 row_ror:2 row_mask:0xf bank_mask:0xf
	v_mov_b32_e32 v96, 0
	v_mov_b32_e32 v97, 0
	v_mov_b32_e32 v103, 0
	v_mov_b32_dpp v96, v98 row_ror:1 row_mask:0xf bank_mask:0xf
	v_mov_b32_dpp v102, v98 row_ror:2 row_mask:0xf bank_mask:0xf
	v_mov_b32_dpp v97, v99 row_ror:1 row_mask:0xf bank_mask:0xf
	v_mov_b32_dpp v103, v99 row_ror:2 row_mask:0xf bank_mask:0xf
	v_mov_b32_dpp v94, v48 row_shr:1 row_mask:0xf bank_mask:0xf
	v_mov_b32_dpp v100, v48 row_shr:2 row_mask:0xf bank_mask:0xf
	v_mov_b32_dpp v95, v49 row_shr:1 row_mask:0xf bank_mask:0xf
	v_mov_b32_dpp v101, v49 row_shr:2 row_mask:0xf bank_mask:0xf
	v_mov_b32_dpp v96, v50 row_shr:1 row_mask:0xf bank_mask:0xf
	v_mov_b32_dpp v102, v50 row_shr:2 row_mask:0xf bank_mask:0xf
	v_mov_b32_dpp v97, v51 row_shr:1 row_mask:0xf bank_mask:0xf
	v_mov_b32_dpp v103, v51 row_shr:2 row_mask:0xf bank_mask:0xf
	s_and_saveexec_b64 s[46:47], s[28:29]
	s_xor_b64 s[64:65], exec, s[46:47]
	s_cbranch_execz .LBB0_1371
	global_store_dwordx4 v[112:113], v[48:51], off offset:16
.LBB0_1371:
	s_andn2_saveexec_b64 s[64:65], s[64:65]
	s_cbranch_execz .LBB0_1375
	v_add_co_u32_e32 v98, vcc, 0x2000, v114
	s_nop 1
	v_addc_co_u32_e32 v99, vcc, 0, v115, vcc
	v_mov_b32_e32 v104, v218
	v_mov_b32_e32 v105, v219
	v_mov_b32_e32 v106, v220
	v_mov_b32_e32 v107, v221
	s_waitcnt lgkmcnt(0)
	v_mov_b64_e32 v[100:101], v[104:105]
	v_mov_b64_e32 v[102:103], v[106:107]
	s_and_saveexec_b64 s[66:67], s[6:7]
	s_cbranch_execz .LBB0_1374
	v_mov_b32_e32 v100, v222
	v_mov_b32_e32 v101, v223
	v_mov_b32_e32 v102, v224
	v_mov_b32_e32 v103, v225
	v_mov_b64_e32 v[94:95], v[104:105]
	v_mov_b64_e32 v[96:97], v[106:107]

.LBB0_1375:
	s_or_b64 exec, exec, s[64:65]
	s_waitcnt lgkmcnt(0)
	v_pk_fma_f32 v[98:99], v[62:63], v[102:103], v[66:67]
	v_add_u32_e32 v103, 0x80, v209
	v_pk_fma_f32 v[96:97], v[54:55], v[96:97], v[98:99]
	s_nop 0
	v_pk_fma_f32 v[96:97], v[50:51], v[58:59], v[96:97]
	s_nop 0
	v_mul_f32_e32 v98, 0xbfb8aa3b, v97
	v_exp_f32_e32 v102, v98
	v_pk_fma_f32 v[98:99], v[60:61], v[100:101], v[64:65]
	s_nop 0
	v_pk_fma_f32 v[94:95], v[52:53], v[94:95], v[98:99]
	v_add_f32_e32 v98, 1.0, v102
	v_rcp_f32_e32 v98, v98
	v_mul_f32_e32 v99, 0xbfb8aa3b, v96
	v_exp_f32_e32 v99, v99
	v_pk_fma_f32 v[94:95], v[48:49], v[56:57], v[94:95]
	v_mul_f32_e32 v97, v97, v98
	v_mul_f32_e32 v75, v75, v97
	v_add_f32_e32 v97, 1.0, v99
	v_mul_f32_e32 v98, 0xbfb8aa3b, v95
	v_mul_f32_e32 v99, 0xbfb8aa3b, v94
	v_rcp_f32_e32 v97, v97
	v_exp_f32_e32 v98, v98
	v_exp_f32_e32 v99, v99
	v_mul_f32_e32 v96, v96, v97
	v_add_f32_e32 v97, 1.0, v98
	v_add_f32_e32 v98, 1.0, v99
	v_rcp_f32_e32 v97, v97
	v_rcp_f32_e32 v98, v98
	v_mul_f32_e32 v74, v74, v96
	v_mul_f32_e32 v95, v95, v97
	v_mul_f32_e32 v94, v94, v98
	v_mul_f32_e32 v73, v73, v95
	v_mul_f32_e32 v72, v72, v94
	v_cvt_pk_bf16_f32 v94, v72, v73
	v_mov_b64_e32 v[72:73], s[16:17]
	v_mad_i64_i32 v[72:73], s[46:47], v103, s82, v[72:73]
	v_lshl_add_u64 v[72:73], v[190:191], 1, v[72:73]
	v_cvt_pk_bf16_f32 v95, v74, v75
	global_store_dwordx4 v[72:73], v[92:95], off
	v_add_u32_e32 v72, 0xffff8090, v209
	v_ashrrev_i32_e32 v98, 2, v72
	v_ashrrev_i32_e32 v99, 31, v98
	v_lshl_add_u64 v[72:73], v[98:99], 1, v[184:185]
	v_mad_u64_u32 v[96:97], s[46:47], v72, s80, 0
	v_mad_i32_i24 v97, v73, s80, v97
	v_mov_b32_e32 v72, 0
	v_mov_b32_e32 v92, 0
	v_mov_b32_e32 v73, 0
	v_mov_b32_e32 v93, 0
	v_mov_b32_e32 v74, 0
	v_mov_b32_e32 v94, 0
	v_mov_b32_e32 v75, 0
	v_mov_b32_e32 v95, 0
	v_mov_b32_dpp v72, v68 row_ror:1 row_mask:0xf bank_mask:0xf
	v_mov_b32_dpp v92, v68 row_ror:2 row_mask:0xf bank_mask:0xf
	v_mov_b32_dpp v73, v69 row_ror:1 row_mask:0xf bank_mask:0xf
	v_mov_b32_dpp v93, v69 row_ror:2 row_mask:0xf bank_mask:0xf
	v_mov_b32_dpp v74, v70 row_ror:1 row_mask:0xf bank_mask:0xf
	v_mov_b32_dpp v94, v70 row_ror:2 row_mask:0xf bank_mask:0xf
	v_mov_b32_dpp v75, v71 row_ror:1 row_mask:0xf bank_mask:0xf
	v_mov_b32_dpp v95, v71 row_ror:2 row_mask:0xf bank_mask:0xf
	v_lshl_add_u64 v[68:69], s[18:19], 0, v[96:97]
	v_mov_b32_dpp v72, v36 row_shr:1 row_mask:0xf bank_mask:0xf
	v_mov_b32_dpp v92, v36 row_shr:2 row_mask:0xf bank_mask:0xf
	v_mov_b32_dpp v73, v37 row_shr:1 row_mask:0xf bank_mask:0xf
	v_mov_b32_dpp v93, v37 row_shr:2 row_mask:0xf bank_mask:0xf
	v_mov_b32_dpp v74, v38 row_shr:1 row_mask:0xf bank_mask:0xf
	v_mov_b32_dpp v94, v38 row_shr:2 row_mask:0xf bank_mask:0xf
	v_mov_b32_dpp v75, v39 row_shr:1 row_mask:0xf bank_mask:0xf
	v_mov_b32_dpp v95, v39 row_shr:2 row_mask:0xf bank_mask:0xf
	v_lshl_add_u64 v[96:97], v[190:191], 2, v[68:69]
	s_and_saveexec_b64 s[46:47], s[28:29]
	s_xor_b64 s[64:65], exec, s[46:47]
	s_cbranch_execz .LBB0_1377
	global_store_dwordx4 v[96:97], v[36:39], off
.LBB0_1377:
	s_or_saveexec_b64 s[64:65], s[64:65]
	v_mad_i64_i32 v[68:69], s[46:47], v98, s81, 0
	v_lshl_add_u64 v[68:69], s[12:13], 0, v[68:69]
	v_lshl_add_u64 v[98:99], v[190:191], 2, v[68:69]
	s_xor_b64 exec, exec, s[64:65]
	s_cbranch_execz .LBB0_1381
	v_add_co_u32_e32 v68, vcc, 0x2000, v98
	s_nop 1
	v_addc_co_u32_e32 v69, vcc, 0, v99, vcc
	v_mov_b32_e32 v68, v226
	v_mov_b32_e32 v69, v227
	v_mov_b32_e32 v70, v228
	v_mov_b32_e32 v71, v229
	s_waitcnt lgkmcnt(0)
	v_mov_b64_e32 v[94:95], v[70:71]
	v_mov_b64_e32 v[92:93], v[68:69]
	s_and_saveexec_b64 s[66:67], s[6:7]
	s_cbranch_execz .LBB0_1380
	v_mov_b32_e32 v92, v230
	v_mov_b32_e32 v93, v231
	v_mov_b32_e32 v94, v232
	v_mov_b32_e32 v95, v233
	v_mov_b64_e32 v[74:75], v[70:71]
	v_mov_b64_e32 v[72:73], v[68:69]

.LBB0_1381:
	s_or_b64 exec, exec, s[64:65]
	s_waitcnt lgkmcnt(0)
	v_pk_fma_f32 v[68:69], v[86:87], v[94:95], v[90:91]
	s_nop 0
	v_pk_fma_f32 v[68:69], v[78:79], v[74:75], v[68:69]
	s_nop 0
	v_pk_fma_f32 v[68:69], v[38:39], v[82:83], v[68:69]
	s_nop 0
	v_mul_f32_e32 v70, 0xbfb8aa3b, v69
	v_exp_f32_e32 v74, v70
	v_mul_f32_e32 v75, 0xbfb8aa3b, v68
	v_exp_f32_e32 v75, v75
	v_pk_fma_f32 v[70:71], v[84:85], v[92:93], v[88:89]
	v_add_f32_e32 v74, 1.0, v74
	v_rcp_f32_e32 v74, v74
	v_pk_fma_f32 v[70:71], v[76:77], v[72:73], v[70:71]
	v_add_f32_e32 v72, 1.0, v75
	v_pk_fma_f32 v[70:71], v[36:37], v[80:81], v[70:71]
	v_mul_f32_e32 v69, v69, v74
	v_mul_f32_e32 v47, v47, v69
	v_rcp_f32_e32 v69, v72
	v_mul_f32_e32 v72, 0xbfb8aa3b, v71
	v_exp_f32_e32 v72, v72
	v_mul_f32_e32 v73, 0xbfb8aa3b, v70
	v_exp_f32_e32 v73, v73
	v_mul_f32_e32 v68, v68, v69
	v_add_f32_e32 v69, 1.0, v72
	v_rcp_f32_e32 v69, v69
	v_add_f32_e32 v72, 1.0, v73
	v_rcp_f32_e32 v72, v72
	v_mul_f32_e32 v46, v46, v68
	v_mul_f32_e32 v68, v71, v69
	v_mul_f32_e32 v45, v45, v68
	v_mul_f32_e32 v68, v70, v72
	v_mul_f32_e32 v44, v44, v68
	v_cvt_pk_bf16_f32 v44, v44, v45
	v_cvt_pk_bf16_f32 v45, v46, v47
	v_mov_b32_e32 v46, 0
	v_mov_b32_e32 v68, 0
	v_mov_b32_e32 v47, 0
	v_mov_b32_e32 v69, 0
	v_mov_b32_dpp v46, v48 row_ror:1 row_mask:0xf bank_mask:0xf
	v_mov_b32_dpp v68, v48 row_ror:2 row_mask:0xf bank_mask:0xf
	v_mov_b32_dpp v47, v49 row_ror:1 row_mask:0xf bank_mask:0xf
	v_mov_b32_dpp v69, v49 row_ror:2 row_mask:0xf bank_mask:0xf
	v_mov_b32_e32 v48, 0
	v_mov_b32_e32 v70, 0
	v_mov_b32_e32 v49, 0
	v_mov_b32_e32 v71, 0
	v_mov_b32_dpp v48, v50 row_ror:1 row_mask:0xf bank_mask:0xf
	v_mov_b32_dpp v70, v50 row_ror:2 row_mask:0xf bank_mask:0xf
	v_mov_b32_dpp v49, v51 row_ror:1 row_mask:0xf bank_mask:0xf
	v_mov_b32_dpp v71, v51 row_ror:2 row_mask:0xf bank_mask:0xf
	v_mov_b32_dpp v46, v32 row_shr:1 row_mask:0xf bank_mask:0xf
	v_mov_b32_dpp v68, v32 row_shr:2 row_mask:0xf bank_mask:0xf
	v_mov_b32_dpp v47, v33 row_shr:1 row_mask:0xf bank_mask:0xf
	v_mov_b32_dpp v69, v33 row_shr:2 row_mask:0xf bank_mask:0xf
	v_mov_b32_dpp v48, v34 row_shr:1 row_mask:0xf bank_mask:0xf
	v_mov_b32_dpp v70, v34 row_shr:2 row_mask:0xf bank_mask:0xf
	v_mov_b32_dpp v49, v35 row_shr:1 row_mask:0xf bank_mask:0xf
	v_mov_b32_dpp v71, v35 row_shr:2 row_mask:0xf bank_mask:0xf
	s_and_saveexec_b64 s[46:47], s[28:29]
	s_xor_b64 s[64:65], exec, s[46:47]
	s_cbranch_execz .LBB0_1383
	global_store_dwordx4 v[96:97], v[32:35], off offset:16
.LBB0_1383:
	s_andn2_saveexec_b64 s[64:65], s[64:65]
	s_cbranch_execz .LBB0_1387
	v_add_co_u32_e32 v50, vcc, 0x2000, v98
	s_nop 1
	v_addc_co_u32_e32 v51, vcc, 0, v99, vcc
	v_mov_b32_e32 v72, v234
	v_mov_b32_e32 v73, v235
	v_mov_b32_e32 v74, v236
	v_mov_b32_e32 v75, v237
	s_waitcnt lgkmcnt(0)
	v_mov_b64_e32 v[68:69], v[72:73]
	v_mov_b64_e32 v[70:71], v[74:75]
	s_and_saveexec_b64 s[66:67], s[6:7]
	s_cbranch_execz .LBB0_1386
	v_mov_b32_e32 v68, v238
	v_mov_b32_e32 v69, v239
	v_mov_b32_e32 v70, v240
	v_mov_b32_e32 v71, v241
	v_mov_b64_e32 v[46:47], v[72:73]
	v_mov_b64_e32 v[48:49], v[74:75]

.LBB0_1387:
	s_or_b64 exec, exec, s[64:65]
	s_waitcnt lgkmcnt(0)
	v_pk_fma_f32 v[50:51], v[62:63], v[70:71], v[66:67]
	v_add_u32_e32 v71, 0x90, v209
	v_pk_fma_f32 v[48:49], v[54:55], v[48:49], v[50:51]
	s_nop 0
	v_pk_fma_f32 v[48:49], v[34:35], v[58:59], v[48:49]
	s_nop 0
	v_mul_f32_e32 v50, 0xbfb8aa3b, v49
	v_exp_f32_e32 v70, v50
	v_pk_fma_f32 v[50:51], v[60:61], v[68:69], v[64:65]
	s_nop 0
	v_pk_fma_f32 v[46:47], v[52:53], v[46:47], v[50:51]
	v_add_f32_e32 v50, 1.0, v70
	v_rcp_f32_e32 v50, v50
	v_mul_f32_e32 v51, 0xbfb8aa3b, v48
	v_exp_f32_e32 v51, v51
	v_pk_fma_f32 v[46:47], v[32:33], v[56:57], v[46:47]
	v_mul_f32_e32 v49, v49, v50
	v_mul_f32_e32 v43, v43, v49
	v_add_f32_e32 v49, 1.0, v51
	v_mul_f32_e32 v50, 0xbfb8aa3b, v47
	v_mul_f32_e32 v51, 0xbfb8aa3b, v46
	v_rcp_f32_e32 v49, v49
	v_exp_f32_e32 v50, v50
	v_exp_f32_e32 v51, v51
	v_mul_f32_e32 v48, v48, v49
	v_add_f32_e32 v49, 1.0, v50
	v_add_f32_e32 v50, 1.0, v51
	v_rcp_f32_e32 v49, v49
	v_rcp_f32_e32 v50, v50
	v_mul_f32_e32 v42, v42, v48
	v_mul_f32_e32 v47, v47, v49
	v_mul_f32_e32 v46, v46, v50
	v_mul_f32_e32 v41, v41, v47
	v_mul_f32_e32 v40, v40, v46
	v_cvt_pk_bf16_f32 v46, v40, v41
	v_mov_b64_e32 v[40:41], s[16:17]
	v_mad_i64_i32 v[40:41], s[46:47], v71, s82, v[40:41]
	v_lshl_add_u64 v[40:41], v[190:191], 1, v[40:41]
	v_cvt_pk_bf16_f32 v47, v42, v43
	global_store_dwordx4 v[40:41], v[44:47], off
	v_add_u32_e32 v40, 0xffff80a0, v209
	v_ashrrev_i32_e32 v50, 2, v40
	v_ashrrev_i32_e32 v51, 31, v50
	v_lshl_add_u64 v[40:41], v[50:51], 1, v[184:185]
	v_mad_u64_u32 v[48:49], s[46:47], v40, s80, 0
	v_mad_i32_i24 v49, v41, s80, v49
	v_mov_b32_e32 v40, 0
	v_mov_b32_e32 v44, 0
	v_mov_b32_e32 v41, 0
	v_mov_b32_e32 v45, 0
	v_mov_b32_e32 v42, 0
	v_mov_b32_e32 v46, 0
	v_mov_b32_e32 v43, 0
	v_mov_b32_e32 v47, 0
	v_mov_b32_dpp v40, v36 row_ror:1 row_mask:0xf bank_mask:0xf
	v_mov_b32_dpp v44, v36 row_ror:2 row_mask:0xf bank_mask:0xf
	v_mov_b32_dpp v41, v37 row_ror:1 row_mask:0xf bank_mask:0xf
	v_mov_b32_dpp v45, v37 row_ror:2 row_mask:0xf bank_mask:0xf
	v_mov_b32_dpp v42, v38 row_ror:1 row_mask:0xf bank_mask:0xf
	v_mov_b32_dpp v46, v38 row_ror:2 row_mask:0xf bank_mask:0xf
	v_mov_b32_dpp v43, v39 row_ror:1 row_mask:0xf bank_mask:0xf
	v_mov_b32_dpp v47, v39 row_ror:2 row_mask:0xf bank_mask:0xf
	v_lshl_add_u64 v[36:37], s[18:19], 0, v[48:49]
	v_mov_b32_dpp v40, v20 row_shr:1 row_mask:0xf bank_mask:0xf
	v_mov_b32_dpp v44, v20 row_shr:2 row_mask:0xf bank_mask:0xf
	v_mov_b32_dpp v41, v21 row_shr:1 row_mask:0xf bank_mask:0xf
	v_mov_b32_dpp v45, v21 row_shr:2 row_mask:0xf bank_mask:0xf
	v_mov_b32_dpp v42, v22 row_shr:1 row_mask:0xf bank_mask:0xf
	v_mov_b32_dpp v46, v22 row_shr:2 row_mask:0xf bank_mask:0xf
	v_mov_b32_dpp v43, v23 row_shr:1 row_mask:0xf bank_mask:0xf
	v_mov_b32_dpp v47, v23 row_shr:2 row_mask:0xf bank_mask:0xf
	v_lshl_add_u64 v[48:49], v[190:191], 2, v[36:37]
	s_mov_b64 s[72:73], 0xdc000
	v_lshl_add_u64 v[244:245], v[242:243], 0, s[72:73]
	s_mov_b64 s[72:73], 0x2c00
	v_lshl_add_u64 v[246:247], v[244:245], 0, s[72:73]
	s_mov_b64 s[72:73], 0x16000
	v_lshl_add_u64 v[248:249], v[244:245], 0, s[72:73]
	s_mov_b64 s[72:73], 0x2c00
	v_lshl_add_u64 v[250:251], v[248:249], 0, s[72:73]
	global_load_dwordx4 v[210:213], v[246:247], off
	global_load_dwordx4 v[214:217], v[244:245], off
	global_load_dwordx4 v[218:221], v[246:247], off offset:16
	global_load_dwordx4 v[222:225], v[244:245], off offset:16
	global_load_dwordx4 v[226:229], v[250:251], off
	global_load_dwordx4 v[230:233], v[248:249], off
	global_load_dwordx4 v[234:237], v[250:251], off offset:16
	global_load_dwordx4 v[238:241], v[248:249], off offset:16
	s_and_saveexec_b64 s[46:47], s[28:29]
	s_xor_b64 s[64:65], exec, s[46:47]
	s_cbranch_execz .LBB0_1389
	global_store_dwordx4 v[48:49], v[20:23], off
.LBB0_1389:
	s_waitcnt vmcnt(1)
	s_or_saveexec_b64 s[64:65], s[64:65]
	v_mad_i64_i32 v[36:37], s[46:47], v50, s81, 0
	v_lshl_add_u64 v[36:37], s[12:13], 0, v[36:37]
	v_lshl_add_u64 v[50:51], v[190:191], 2, v[36:37]
	s_xor_b64 exec, exec, s[64:65]
	s_cbranch_execz .LBB0_1393
	v_add_co_u32_e32 v36, vcc, 0x2000, v50
	s_nop 1
	v_addc_co_u32_e32 v37, vcc, 0, v51, vcc
	v_mov_b32_e32 v36, v210
	v_mov_b32_e32 v37, v211
	v_mov_b32_e32 v38, v212
	v_mov_b32_e32 v39, v213
	s_waitcnt lgkmcnt(0)
	v_mov_b64_e32 v[46:47], v[38:39]
	v_mov_b64_e32 v[44:45], v[36:37]
	s_and_saveexec_b64 s[66:67], s[6:7]
	s_cbranch_execz .LBB0_1392
	v_mov_b32_e32 v44, v214
	v_mov_b32_e32 v45, v215
	v_mov_b32_e32 v46, v216
	v_mov_b32_e32 v47, v217
	v_mov_b64_e32 v[42:43], v[38:39]
	v_mov_b64_e32 v[40:41], v[36:37]

.LBB0_1393:
	s_or_b64 exec, exec, s[64:65]
	s_waitcnt lgkmcnt(0)
	v_pk_fma_f32 v[36:37], v[86:87], v[46:47], v[90:91]
	s_nop 0
	v_pk_fma_f32 v[36:37], v[78:79], v[42:43], v[36:37]
	s_nop 0
	v_pk_fma_f32 v[36:37], v[22:23], v[82:83], v[36:37]
	s_nop 0
	v_mul_f32_e32 v38, 0xbfb8aa3b, v37
	v_exp_f32_e32 v42, v38
	v_mul_f32_e32 v43, 0xbfb8aa3b, v36
	v_exp_f32_e32 v43, v43
	v_pk_fma_f32 v[38:39], v[84:85], v[44:45], v[88:89]
	v_add_f32_e32 v42, 1.0, v42
	v_rcp_f32_e32 v42, v42
	v_pk_fma_f32 v[38:39], v[76:77], v[40:41], v[38:39]
	v_add_f32_e32 v40, 1.0, v43
	v_pk_fma_f32 v[38:39], v[20:21], v[80:81], v[38:39]
	v_mul_f32_e32 v37, v37, v42
	v_mul_f32_e32 v31, v31, v37
	v_rcp_f32_e32 v37, v40
	v_mul_f32_e32 v40, 0xbfb8aa3b, v39
	v_exp_f32_e32 v40, v40
	v_mul_f32_e32 v41, 0xbfb8aa3b, v38
	v_exp_f32_e32 v41, v41
	v_mul_f32_e32 v36, v36, v37
	v_add_f32_e32 v37, 1.0, v40
	v_rcp_f32_e32 v37, v37
	v_add_f32_e32 v40, 1.0, v41
	v_rcp_f32_e32 v40, v40
	v_mul_f32_e32 v30, v30, v36
	v_mul_f32_e32 v36, v39, v37
	v_mul_f32_e32 v29, v29, v36
	v_mul_f32_e32 v36, v38, v40
	v_mul_f32_e32 v28, v28, v36
	v_cvt_pk_bf16_f32 v28, v28, v29
	v_cvt_pk_bf16_f32 v29, v30, v31
	v_mov_b32_e32 v30, 0
	v_mov_b32_e32 v36, 0
	v_mov_b32_e32 v31, 0
	v_mov_b32_e32 v37, 0
	v_mov_b32_dpp v30, v32 row_ror:1 row_mask:0xf bank_mask:0xf
	v_mov_b32_dpp v36, v32 row_ror:2 row_mask:0xf bank_mask:0xf
	v_mov_b32_dpp v31, v33 row_ror:1 row_mask:0xf bank_mask:0xf
	v_mov_b32_dpp v37, v33 row_ror:2 row_mask:0xf bank_mask:0xf
	v_mov_b32_e32 v32, 0
	v_mov_b32_e32 v38, 0
	v_mov_b32_e32 v33, 0
	v_mov_b32_e32 v39, 0
	v_mov_b32_dpp v32, v34 row_ror:1 row_mask:0xf bank_mask:0xf
	v_mov_b32_dpp v38, v34 row_ror:2 row_mask:0xf bank_mask:0xf
	v_mov_b32_dpp v33, v35 row_ror:1 row_mask:0xf bank_mask:0xf
	v_mov_b32_dpp v39, v35 row_ror:2 row_mask:0xf bank_mask:0xf
	v_mov_b32_dpp v30, v12 row_shr:1 row_mask:0xf bank_mask:0xf
	v_mov_b32_dpp v36, v12 row_shr:2 row_mask:0xf bank_mask:0xf
	v_mov_b32_dpp v31, v13 row_shr:1 row_mask:0xf bank_mask:0xf
	v_mov_b32_dpp v37, v13 row_shr:2 row_mask:0xf bank_mask:0xf
	v_mov_b32_dpp v32, v14 row_shr:1 row_mask:0xf bank_mask:0xf
	v_mov_b32_dpp v38, v14 row_shr:2 row_mask:0xf bank_mask:0xf
	v_mov_b32_dpp v33, v15 row_shr:1 row_mask:0xf bank_mask:0xf
	v_mov_b32_dpp v39, v15 row_shr:2 row_mask:0xf bank_mask:0xf
	s_and_saveexec_b64 s[46:47], s[28:29]
	s_xor_b64 s[64:65], exec, s[46:47]
	s_cbranch_execz .LBB0_1395
	global_store_dwordx4 v[48:49], v[12:15], off offset:16
.LBB0_1395:
	s_andn2_saveexec_b64 s[64:65], s[64:65]
	s_cbranch_execz .LBB0_1399
	v_add_co_u32_e32 v34, vcc, 0x2000, v50
	s_nop 1
	v_addc_co_u32_e32 v35, vcc, 0, v51, vcc
	v_mov_b32_e32 v40, v218
	v_mov_b32_e32 v41, v219
	v_mov_b32_e32 v42, v220
	v_mov_b32_e32 v43, v221
	s_waitcnt lgkmcnt(0)
	v_mov_b64_e32 v[36:37], v[40:41]
	v_mov_b64_e32 v[38:39], v[42:43]
	s_and_saveexec_b64 s[66:67], s[6:7]
	s_cbranch_execz .LBB0_1398
	v_mov_b32_e32 v36, v222
	v_mov_b32_e32 v37, v223
	v_mov_b32_e32 v38, v224
	v_mov_b32_e32 v39, v225
	v_mov_b64_e32 v[30:31], v[40:41]
	v_mov_b64_e32 v[32:33], v[42:43]

.LBB0_1399:
	s_or_b64 exec, exec, s[64:65]
	s_waitcnt lgkmcnt(0)
	v_pk_fma_f32 v[34:35], v[62:63], v[38:39], v[66:67]
	v_add_u32_e32 v39, 0xa0, v209
	v_pk_fma_f32 v[32:33], v[54:55], v[32:33], v[34:35]
	s_nop 0
	v_pk_fma_f32 v[32:33], v[14:15], v[58:59], v[32:33]
	s_nop 0
	v_mul_f32_e32 v34, 0xbfb8aa3b, v33
	v_exp_f32_e32 v38, v34
	v_pk_fma_f32 v[34:35], v[60:61], v[36:37], v[64:65]
	s_nop 0
	v_pk_fma_f32 v[30:31], v[52:53], v[30:31], v[34:35]
	v_add_f32_e32 v34, 1.0, v38
	v_rcp_f32_e32 v34, v34
	v_mul_f32_e32 v35, 0xbfb8aa3b, v32
	v_exp_f32_e32 v35, v35
	v_pk_fma_f32 v[30:31], v[12:13], v[56:57], v[30:31]
	v_mul_f32_e32 v33, v33, v34
	v_mul_f32_e32 v27, v27, v33
	v_add_f32_e32 v33, 1.0, v35
	v_mul_f32_e32 v34, 0xbfb8aa3b, v31
	v_mul_f32_e32 v35, 0xbfb8aa3b, v30
	v_rcp_f32_e32 v33, v33
	v_exp_f32_e32 v34, v34
	v_exp_f32_e32 v35, v35
	v_mul_f32_e32 v32, v32, v33
	v_add_f32_e32 v33, 1.0, v34
	v_add_f32_e32 v34, 1.0, v35
	v_rcp_f32_e32 v33, v33
	v_rcp_f32_e32 v34, v34
	v_mul_f32_e32 v26, v26, v32
	v_mul_f32_e32 v31, v31, v33
	v_mul_f32_e32 v30, v30, v34
	v_mul_f32_e32 v25, v25, v31
	v_mul_f32_e32 v24, v24, v30
	v_cvt_pk_bf16_f32 v30, v24, v25
	v_mov_b64_e32 v[24:25], s[16:17]
	v_mad_i64_i32 v[24:25], s[46:47], v39, s82, v[24:25]
	v_lshl_add_u64 v[24:25], v[190:191], 1, v[24:25]
	v_cvt_pk_bf16_f32 v31, v26, v27
	global_store_dwordx4 v[24:25], v[28:31], off
	v_add_u32_e32 v24, 0xffff80b0, v209
	v_ashrrev_i32_e32 v34, 2, v24
	v_ashrrev_i32_e32 v35, 31, v34
	v_lshl_add_u64 v[24:25], v[34:35], 1, v[184:185]
	v_mad_u64_u32 v[32:33], s[46:47], v24, s80, 0
	v_mad_i32_i24 v33, v25, s80, v33
	v_mov_b32_e32 v24, 0
	v_mov_b32_e32 v28, 0
	v_mov_b32_e32 v25, 0
	v_mov_b32_e32 v29, 0
	v_mov_b32_e32 v26, 0
	v_mov_b32_e32 v30, 0
	v_mov_b32_e32 v27, 0
	v_mov_b32_e32 v31, 0
	v_mov_b32_dpp v24, v20 row_ror:1 row_mask:0xf bank_mask:0xf
	v_mov_b32_dpp v28, v20 row_ror:2 row_mask:0xf bank_mask:0xf
	v_mov_b32_dpp v25, v21 row_ror:1 row_mask:0xf bank_mask:0xf
	v_mov_b32_dpp v29, v21 row_ror:2 row_mask:0xf bank_mask:0xf
	v_mov_b32_dpp v26, v22 row_ror:1 row_mask:0xf bank_mask:0xf
	v_mov_b32_dpp v30, v22 row_ror:2 row_mask:0xf bank_mask:0xf
	v_mov_b32_dpp v27, v23 row_ror:1 row_mask:0xf bank_mask:0xf
	v_mov_b32_dpp v31, v23 row_ror:2 row_mask:0xf bank_mask:0xf
	v_lshl_add_u64 v[20:21], s[18:19], 0, v[32:33]
	v_mov_b32_dpp v24, v16 row_shr:1 row_mask:0xf bank_mask:0xf
	v_mov_b32_dpp v28, v16 row_shr:2 row_mask:0xf bank_mask:0xf
	v_mov_b32_dpp v25, v17 row_shr:1 row_mask:0xf bank_mask:0xf
	v_mov_b32_dpp v29, v17 row_shr:2 row_mask:0xf bank_mask:0xf
	v_mov_b32_dpp v26, v18 row_shr:1 row_mask:0xf bank_mask:0xf
	v_mov_b32_dpp v30, v18 row_shr:2 row_mask:0xf bank_mask:0xf
	v_mov_b32_dpp v27, v19 row_shr:1 row_mask:0xf bank_mask:0xf
	v_mov_b32_dpp v31, v19 row_shr:2 row_mask:0xf bank_mask:0xf
	v_lshl_add_u64 v[32:33], v[190:191], 2, v[20:21]
	s_and_saveexec_b64 s[46:47], s[28:29]
	s_xor_b64 s[64:65], exec, s[46:47]
	s_cbranch_execz .LBB0_1401
	global_store_dwordx4 v[32:33], v[16:19], off
.LBB0_1401:
	s_or_saveexec_b64 s[64:65], s[64:65]
	v_mad_i64_i32 v[20:21], s[46:47], v34, s81, 0
	v_lshl_add_u64 v[20:21], s[12:13], 0, v[20:21]
	v_lshl_add_u64 v[34:35], v[190:191], 2, v[20:21]
	s_xor_b64 exec, exec, s[64:65]
	s_cbranch_execz .LBB0_1405
	v_add_co_u32_e32 v20, vcc, 0x2000, v34
	s_nop 1
	v_addc_co_u32_e32 v21, vcc, 0, v35, vcc
	v_mov_b32_e32 v20, v226
	v_mov_b32_e32 v21, v227
	v_mov_b32_e32 v22, v228
	v_mov_b32_e32 v23, v229
	s_waitcnt lgkmcnt(0)
	v_mov_b64_e32 v[30:31], v[22:23]
	v_mov_b64_e32 v[28:29], v[20:21]
	s_and_saveexec_b64 s[66:67], s[6:7]
	s_cbranch_execz .LBB0_1404
	v_mov_b32_e32 v28, v230
	v_mov_b32_e32 v29, v231
	v_mov_b32_e32 v30, v232
	v_mov_b32_e32 v31, v233
	v_mov_b64_e32 v[26:27], v[22:23]
	v_mov_b64_e32 v[24:25], v[20:21]

.LBB0_1405:
	s_or_b64 exec, exec, s[64:65]
	s_waitcnt lgkmcnt(0)
	v_pk_fma_f32 v[20:21], v[86:87], v[30:31], v[90:91]
	s_nop 0
	v_pk_fma_f32 v[20:21], v[78:79], v[26:27], v[20:21]
	s_nop 0
	v_pk_fma_f32 v[18:19], v[18:19], v[82:83], v[20:21]
	s_nop 0
	v_mul_f32_e32 v20, 0xbfb8aa3b, v19
	v_exp_f32_e32 v22, v20
	v_mul_f32_e32 v23, 0xbfb8aa3b, v18
	v_exp_f32_e32 v23, v23
	v_pk_fma_f32 v[20:21], v[84:85], v[28:29], v[88:89]
	v_add_f32_e32 v22, 1.0, v22
	v_rcp_f32_e32 v22, v22
	v_pk_fma_f32 v[20:21], v[76:77], v[24:25], v[20:21]
	v_mul_f32_e32 v19, v19, v22
	v_pk_fma_f32 v[16:17], v[16:17], v[80:81], v[20:21]
	v_add_f32_e32 v20, 1.0, v23
	v_mul_f32_e32 v11, v11, v19
	v_rcp_f32_e32 v19, v20
	v_mul_f32_e32 v20, 0xbfb8aa3b, v17
	v_mul_f32_e32 v21, 0xbfb8aa3b, v16
	v_exp_f32_e32 v20, v20
	v_exp_f32_e32 v21, v21
	v_mul_f32_e32 v18, v18, v19
	v_mul_f32_e32 v10, v10, v18
	v_add_f32_e32 v19, 1.0, v20
	v_add_f32_e32 v20, 1.0, v21
	v_rcp_f32_e32 v19, v19
	v_rcp_f32_e32 v20, v20
	v_mov_b32_e32 v18, 0
	v_mul_f32_e32 v17, v17, v19
	v_mul_f32_e32 v16, v16, v20
	v_mul_f32_e32 v9, v9, v17
	v_mul_f32_e32 v8, v8, v16
	v_cvt_pk_bf16_f32 v8, v8, v9
	v_cvt_pk_bf16_f32 v9, v10, v11
	v_mov_b32_e32 v10, 0
	v_mov_b32_e32 v16, 0
	v_mov_b32_e32 v11, 0
	v_mov_b32_e32 v17, 0
	v_mov_b32_dpp v10, v12 row_ror:1 row_mask:0xf bank_mask:0xf
	v_mov_b32_dpp v16, v12 row_ror:2 row_mask:0xf bank_mask:0xf
	v_mov_b32_dpp v11, v13 row_ror:1 row_mask:0xf bank_mask:0xf
	v_mov_b32_dpp v17, v13 row_ror:2 row_mask:0xf bank_mask:0xf
	v_mov_b32_e32 v12, 0
	v_mov_b32_e32 v13, 0
	v_mov_b32_e32 v19, 0
	v_mov_b32_dpp v12, v14 row_ror:1 row_mask:0xf bank_mask:0xf
	v_mov_b32_dpp v18, v14 row_ror:2 row_mask:0xf bank_mask:0xf
	v_mov_b32_dpp v13, v15 row_ror:1 row_mask:0xf bank_mask:0xf
	v_mov_b32_dpp v19, v15 row_ror:2 row_mask:0xf bank_mask:0xf
	v_mov_b32_dpp v10, v4 row_shr:1 row_mask:0xf bank_mask:0xf
	v_mov_b32_dpp v16, v4 row_shr:2 row_mask:0xf bank_mask:0xf
	v_mov_b32_dpp v11, v5 row_shr:1 row_mask:0xf bank_mask:0xf
	v_mov_b32_dpp v17, v5 row_shr:2 row_mask:0xf bank_mask:0xf
	v_mov_b32_dpp v12, v6 row_shr:1 row_mask:0xf bank_mask:0xf
	v_mov_b32_dpp v18, v6 row_shr:2 row_mask:0xf bank_mask:0xf
	v_mov_b32_dpp v13, v7 row_shr:1 row_mask:0xf bank_mask:0xf
	v_mov_b32_dpp v19, v7 row_shr:2 row_mask:0xf bank_mask:0xf
	s_and_saveexec_b64 s[46:47], s[28:29]
	s_xor_b64 s[64:65], exec, s[46:47]
	s_cbranch_execz .LBB0_1407
	global_store_dwordx4 v[32:33], v[4:7], off offset:16
.LBB0_1407:
	s_andn2_saveexec_b64 s[64:65], s[64:65]
	s_cbranch_execz .LBB0_1411
	v_add_co_u32_e32 v14, vcc, 0x2000, v34
	s_nop 1
	v_addc_co_u32_e32 v15, vcc, 0, v35, vcc
	v_mov_b32_e32 v20, v234
	v_mov_b32_e32 v21, v235
	v_mov_b32_e32 v22, v236
	v_mov_b32_e32 v23, v237
	s_waitcnt lgkmcnt(0)
	v_mov_b64_e32 v[16:17], v[20:21]
	v_mov_b64_e32 v[18:19], v[22:23]
	s_and_saveexec_b64 s[66:67], s[6:7]
	s_cbranch_execz .LBB0_1410
	v_mov_b32_e32 v16, v238
	v_mov_b32_e32 v17, v239
	v_mov_b32_e32 v18, v240
	v_mov_b32_e32 v19, v241
	v_mov_b64_e32 v[10:11], v[20:21]
	v_mov_b64_e32 v[12:13], v[22:23]

.LBB0_1411:
	s_or_b64 exec, exec, s[64:65]
	s_waitcnt lgkmcnt(0)
	v_pk_fma_f32 v[14:15], v[62:63], v[18:19], v[66:67]
	s_andn2_b64 vcc, exec, s[60:61]
	v_pk_fma_f32 v[12:13], v[54:55], v[12:13], v[14:15]
	s_mov_b64 s[60:61], -1
	v_pk_fma_f32 v[6:7], v[6:7], v[58:59], v[12:13]
	s_nop 0
	v_mul_f32_e32 v12, 0xbfb8aa3b, v7
	v_exp_f32_e32 v14, v12
	v_mul_f32_e32 v15, 0xbfb8aa3b, v6
	v_exp_f32_e32 v15, v15
	v_pk_fma_f32 v[12:13], v[60:61], v[16:17], v[64:65]
	v_add_f32_e32 v14, 1.0, v14
	v_rcp_f32_e32 v14, v14
	v_pk_fma_f32 v[10:11], v[52:53], v[10:11], v[12:13]
	v_mul_f32_e32 v7, v7, v14
	v_pk_fma_f32 v[4:5], v[4:5], v[56:57], v[10:11]
	v_add_f32_e32 v10, 1.0, v15
	v_mul_f32_e32 v3, v3, v7
	v_rcp_f32_e32 v7, v10
	v_mul_f32_e32 v10, 0xbfb8aa3b, v5
	v_mul_f32_e32 v11, 0xbfb8aa3b, v4
	v_exp_f32_e32 v10, v10
	v_exp_f32_e32 v11, v11
	v_mul_f32_e32 v6, v6, v7
	v_mul_f32_e32 v2, v2, v6
	v_add_f32_e32 v7, 1.0, v10
	v_add_f32_e32 v10, 1.0, v11
	v_rcp_f32_e32 v7, v7
	v_rcp_f32_e32 v10, v10
	v_mul_f32_e32 v5, v5, v7
	v_mul_f32_e32 v4, v4, v10
	v_mul_f32_e32 v1, v1, v5
	v_mul_f32_e32 v0, v0, v4
	v_cvt_pk_bf16_f32 v10, v0, v1
	v_cvt_pk_bf16_f32 v11, v2, v3
	v_add_u32_e32 v2, 0xb0, v209
	v_mov_b64_e32 v[0:1], s[16:17]
	v_mad_i64_i32 v[0:1], s[46:47], v2, s82, v[0:1]
	v_lshl_add_u64 v[0:1], v[190:191], 1, v[0:1]
	global_store_dwordx4 v[0:1], v[8:11], off
	s_waitcnt lgkmcnt(0)
	s_barrier
	s_cbranch_vccnz .LBB0_1302
	s_andn2_b64 vcc, exec, s[14:15]
	s_cbranch_vccnz .LBB0_1301
	s_barrier
	s_branch .LBB0_1301

.LBB0_1482:
	s_ashr_i32 s59, s58, 31
	s_lshl_b64 s[46:47], s[58:59], 19
	s_add_u32 s60, s3, s46
	s_addc_u32 s61, s4, s47
	s_and_b64 s[46:47], s[8:9], exec
	s_cselect_b32 s11, s61, s67
	s_cselect_b32 s35, s60, s66
	s_ashr_i32 s57, s56, 31
	s_lshl_b64 s[46:47], s[56:57], 19
	s_add_u32 s62, s5, s46
	s_addc_u32 s63, s45, s47
	s_and_b64 s[46:47], s[8:9], exec
	s_cselect_b32 s57, s63, s69
	s_cselect_b32 s59, s62, s68
	s_add_u32 s66, s66, 0x40080
	s_addc_u32 s67, s67, 0
	s_add_u32 s65, s68, 0x100
	v_mov_b32_e32 v0, 0
	s_addc_u32 s83, s69, 0
	s_mov_b32 s84, -2
	v_mov_b32_e32 v1, v0
	v_mov_b32_e32 v2, v0
	v_mov_b32_e32 v3, v0
	v_mov_b32_e32 v8, v0
	v_mov_b32_e32 v9, v0
	v_mov_b32_e32 v10, v0
	v_mov_b32_e32 v11, v0
	v_mov_b32_e32 v24, v0
	v_mov_b32_e32 v25, v0
	v_mov_b32_e32 v26, v0
	v_mov_b32_e32 v27, v0
	v_mov_b32_e32 v28, v0
	v_mov_b32_e32 v29, v0
	v_mov_b32_e32 v30, v0
	v_mov_b32_e32 v31, v0
	v_mov_b32_e32 v40, v0
	v_mov_b32_e32 v41, v0
	v_mov_b32_e32 v42, v0
	v_mov_b32_e32 v43, v0
	v_mov_b32_e32 v44, v0
	v_mov_b32_e32 v45, v0
	v_mov_b32_e32 v46, v0
	v_mov_b32_e32 v47, v0
	v_mov_b32_e32 v56, v0
	v_mov_b32_e32 v57, v0
	v_mov_b32_e32 v58, v0
	v_mov_b32_e32 v59, v0
	v_mov_b32_e32 v60, v0
	v_mov_b32_e32 v61, v0
	v_mov_b32_e32 v62, v0
	v_mov_b32_e32 v63, v0
	v_mov_b32_e32 v4, v0
	v_mov_b32_e32 v5, v0
	v_mov_b32_e32 v6, v0
	v_mov_b32_e32 v7, v0
	v_mov_b32_e32 v16, v0
	v_mov_b32_e32 v17, v0
	v_mov_b32_e32 v18, v0
	v_mov_b32_e32 v19, v0
	v_mov_b32_e32 v12, v0
	v_mov_b32_e32 v13, v0
	v_mov_b32_e32 v14, v0
	v_mov_b32_e32 v15, v0
	v_mov_b32_e32 v20, v0
	v_mov_b32_e32 v21, v0
	v_mov_b32_e32 v22, v0
	v_mov_b32_e32 v23, v0
	v_mov_b32_e32 v32, v0
	v_mov_b32_e32 v33, v0
	v_mov_b32_e32 v34, v0
	v_mov_b32_e32 v35, v0
	v_mov_b32_e32 v36, v0
	v_mov_b32_e32 v37, v0
	v_mov_b32_e32 v38, v0
	v_mov_b32_e32 v39, v0
	v_mov_b32_e32 v48, v0
	v_mov_b32_e32 v49, v0
	v_mov_b32_e32 v50, v0
	v_mov_b32_e32 v51, v0
	v_mov_b32_e32 v52, v0
	v_mov_b32_e32 v53, v0
	v_mov_b32_e32 v54, v0
	v_mov_b32_e32 v55, v0
	v_mov_b32_e32 v64, v0
	v_mov_b32_e32 v65, v0
	v_mov_b32_e32 v66, v0
	v_mov_b32_e32 v67, v0
	v_mov_b32_e32 v88, v0
	v_mov_b32_e32 v89, v0
	v_mov_b32_e32 v90, v0
	v_mov_b32_e32 v91, v0
	v_mov_b32_e32 v120, v0
	v_mov_b32_e32 v121, v0
	v_mov_b32_e32 v122, v0
	v_mov_b32_e32 v123, v0
	v_mov_b32_e32 v124, v0
	v_mov_b32_e32 v125, v0
	v_mov_b32_e32 v126, v0
	v_mov_b32_e32 v127, v0
	v_mov_b32_e32 v136, v0
	v_mov_b32_e32 v137, v0
	v_mov_b32_e32 v138, v0
	v_mov_b32_e32 v139, v0
	v_mov_b32_e32 v140, v0
	v_mov_b32_e32 v141, v0
	v_mov_b32_e32 v142, v0
	v_mov_b32_e32 v143, v0
	v_mov_b32_e32 v152, v0
	v_mov_b32_e32 v153, v0
	v_mov_b32_e32 v154, v0
	v_mov_b32_e32 v155, v0
	v_mov_b32_e32 v158, v0
	v_mov_b32_e32 v159, v0
	v_mov_b32_e32 v160, v0
	v_mov_b32_e32 v161, v0
	v_mov_b32_e32 v80, v0
	v_mov_b32_e32 v81, v0
	v_mov_b32_e32 v82, v0
	v_mov_b32_e32 v83, v0
	v_mov_b32_e32 v112, v0
	v_mov_b32_e32 v113, v0
	v_mov_b32_e32 v114, v0
	v_mov_b32_e32 v115, v0
	v_mov_b32_e32 v92, v0
	v_mov_b32_e32 v93, v0
	v_mov_b32_e32 v94, v0
	v_mov_b32_e32 v95, v0
	v_mov_b32_e32 v116, v0
	v_mov_b32_e32 v117, v0
	v_mov_b32_e32 v118, v0
	v_mov_b32_e32 v119, v0
	v_mov_b32_e32 v128, v0
	v_mov_b32_e32 v129, v0
	v_mov_b32_e32 v130, v0
	v_mov_b32_e32 v131, v0
	v_mov_b32_e32 v132, v0
	v_mov_b32_e32 v133, v0
	v_mov_b32_e32 v134, v0
	v_mov_b32_e32 v135, v0
	v_mov_b32_e32 v144, v0
	v_mov_b32_e32 v145, v0
	v_mov_b32_e32 v146, v0
	v_mov_b32_e32 v147, v0
	v_mov_b32_e32 v148, v0
	v_mov_b32_e32 v149, v0
	v_mov_b32_e32 v150, v0
	v_mov_b32_e32 v151, v0
.LBB0_1483:
	ds_read_b128 v[68:71], v202
	ds_read_b128 v[72:75], v202 offset:1024
	ds_read_b128 v[76:79], v202 offset:2048
	ds_read_b128 v[84:87], v202 offset:3072
	ds_read_b128 v[96:99], v203
	ds_read_b128 v[100:103], v203 offset:1024
	ds_read_b128 v[104:107], v203 offset:2048
	ds_read_b128 v[108:111], v203 offset:3072
	s_add_u32 s46, s66, 0xfffc0080
	s_addc_u32 s47, s67, -1
	s_cmp_eq_u32 s84, 12
	s_cselect_b32 s71, s11, s47
	s_cselect_b32 s70, s35, s46
	s_cselect_b32 s69, s57, s83
	s_cselect_b32 s68, s59, s65
	v_lshl_add_u64 v[156:157], s[66:67], 0, v[180:181]
	s_add_i32 m0, s49, 0xc000
	ds_read_b128 v[162:165], v204
	ds_read_b128 v[166:169], v204 offset:1024
	ds_read_b128 v[188:191], v204 offset:2048
	ds_read_b128 v[206:209], v204 offset:3072
	ds_read_b128 v[210:213], v204 offset:4096
	ds_read_b128 v[214:217], v204 offset:5120
	ds_read_b128 v[218:221], v204 offset:6144
	ds_read_b128 v[222:225], v204 offset:7168
	global_load_lds_dwordx4 v[156:157], off
	v_lshl_add_u64 v[156:157], s[66:67], 0, v[182:183]
	s_add_i32 m0, s49, 0xe000
	s_nop 0
	global_load_lds_dwordx4 v[156:157], off
	s_waitcnt vmcnt(8)
	s_waitcnt lgkmcnt(0)
	s_barrier
	s_setprio 1
	s_waitcnt lgkmcnt(0)
	v_mfma_f32_16x16x32_bf16 v[148:151], v[68:71], v[162:165], v[148:151]
	v_mfma_f32_16x16x32_bf16 v[144:147], v[76:79], v[162:165], v[144:147]
	v_mfma_f32_16x16x32_bf16 v[132:135], v[68:71], v[188:191], v[132:135]
	v_mfma_f32_16x16x32_bf16 v[128:131], v[76:79], v[188:191], v[128:131]
	v_mfma_f32_16x16x32_bf16 v[116:119], v[68:71], v[210:213], v[116:119]
	v_mfma_f32_16x16x32_bf16 v[92:95], v[76:79], v[210:213], v[92:95]
	v_mfma_f32_16x16x32_bf16 v[112:115], v[68:71], v[218:221], v[112:115]
	v_mfma_f32_16x16x32_bf16 v[80:83], v[76:79], v[218:221], v[80:83]
	v_mfma_f32_16x16x32_bf16 v[148:151], v[72:75], v[166:169], v[148:151]
	v_mfma_f32_16x16x32_bf16 v[144:147], v[84:87], v[166:169], v[144:147]
	v_mfma_f32_16x16x32_bf16 v[132:135], v[72:75], v[206:209], v[132:135]
	v_mfma_f32_16x16x32_bf16 v[128:131], v[84:87], v[206:209], v[128:131]
	v_mfma_f32_16x16x32_bf16 v[116:119], v[72:75], v[214:217], v[116:119]
	v_mfma_f32_16x16x32_bf16 v[92:95], v[84:87], v[214:217], v[92:95]
	v_mfma_f32_16x16x32_bf16 v[112:115], v[72:75], v[222:225], v[112:115]
	v_mfma_f32_16x16x32_bf16 v[80:83], v[84:87], v[222:225], v[80:83]
	s_setprio 0
	s_setprio 1
	v_mfma_f32_16x16x32_bf16 v[156:159], v[96:99], v[162:165], v[158:161]
	v_mfma_f32_16x16x32_bf16 v[152:155], v[104:107], v[162:165], v[152:155]
	v_mfma_f32_16x16x32_bf16 v[140:143], v[96:99], v[188:191], v[140:143]
	v_mfma_f32_16x16x32_bf16 v[136:139], v[104:107], v[188:191], v[136:139]
	v_mfma_f32_16x16x32_bf16 v[124:127], v[96:99], v[210:213], v[124:127]
	v_mfma_f32_16x16x32_bf16 v[120:123], v[104:107], v[210:213], v[120:123]
	v_mfma_f32_16x16x32_bf16 v[88:91], v[96:99], v[218:221], v[88:91]
	v_mfma_f32_16x16x32_bf16 v[64:67], v[104:107], v[218:221], v[64:67]
	v_mfma_f32_16x16x32_bf16 v[156:159], v[100:103], v[166:169], v[156:159]
	v_mfma_f32_16x16x32_bf16 v[152:155], v[108:111], v[166:169], v[152:155]
	v_mfma_f32_16x16x32_bf16 v[140:143], v[100:103], v[206:209], v[140:143]
	v_mfma_f32_16x16x32_bf16 v[136:139], v[108:111], v[206:209], v[136:139]
	v_mfma_f32_16x16x32_bf16 v[124:127], v[100:103], v[214:217], v[124:127]
	v_mfma_f32_16x16x32_bf16 v[120:123], v[108:111], v[214:217], v[120:123]
	v_mfma_f32_16x16x32_bf16 v[88:91], v[100:103], v[222:225], v[88:91]
	v_mfma_f32_16x16x32_bf16 v[64:67], v[108:111], v[222:225], v[64:67]
	s_setprio 0
	s_barrier
	s_add_i32 s46, s79, s48
	v_lshl_add_u64 v[226:227], s[68:69], 0, v[172:173]
	s_mov_b32 m0, s46
	ds_read_b128 v[160:163], v204 offset:16384
	ds_read_b128 v[164:167], v204 offset:17408
	ds_read_b128 v[188:191], v204 offset:18432
	ds_read_b128 v[206:209], v204 offset:19456
	ds_read_b128 v[210:213], v204 offset:20480
	ds_read_b128 v[214:217], v204 offset:21504
	ds_read_b128 v[218:221], v204 offset:22528
	ds_read_b128 v[222:225], v204 offset:23552
	global_load_lds_dwordx4 v[226:227], off
	s_add_i32 m0, s46, 0x2000
	s_add_u32 s46, s68, 0x40000
	v_lshl_add_u64 v[228:229], s[68:69], 0, v[176:177]
	s_addc_u32 s47, s69, 0
	s_add_i32 s85, s80, s48
	global_load_lds_dwordx4 v[228:229], off
	v_lshl_add_u64 v[168:169], s[46:47], 0, v[172:173]
	s_mov_b32 m0, s85
	v_lshl_add_u64 v[230:231], s[70:71], 0, v[170:171]
	global_load_lds_dwordx4 v[168:169], off
	v_lshl_add_u64 v[168:169], s[46:47], 0, v[176:177]
	s_add_i32 m0, s85, 0x2000
	v_lshl_add_u64 v[232:233], s[70:71], 0, v[174:175]
	global_load_lds_dwordx4 v[168:169], off
	s_mov_b32 m0, s49
	s_nop 0
	global_load_lds_dwordx4 v[230:231], off
	s_mov_b32 m0, s50
	s_nop 0
	global_load_lds_dwordx4 v[232:233], off
	s_waitcnt vmcnt(8)
	s_waitcnt lgkmcnt(0)
	s_barrier
	s_setprio 1
	s_waitcnt lgkmcnt(0)
	v_mfma_f32_16x16x32_bf16 v[52:55], v[68:71], v[160:163], v[52:55]
	v_mfma_f32_16x16x32_bf16 v[48:51], v[76:79], v[160:163], v[48:51]
	v_mfma_f32_16x16x32_bf16 v[36:39], v[68:71], v[188:191], v[36:39]
	v_mfma_f32_16x16x32_bf16 v[32:35], v[76:79], v[188:191], v[32:35]
	v_mfma_f32_16x16x32_bf16 v[20:23], v[68:71], v[210:213], v[20:23]
	v_mfma_f32_16x16x32_bf16 v[12:15], v[76:79], v[210:213], v[12:15]
	v_mfma_f32_16x16x32_bf16 v[16:19], v[68:71], v[218:221], v[16:19]
	v_mfma_f32_16x16x32_bf16 v[4:7], v[76:79], v[218:221], v[4:7]
	v_mfma_f32_16x16x32_bf16 v[52:55], v[72:75], v[164:167], v[52:55]
	v_mfma_f32_16x16x32_bf16 v[48:51], v[84:87], v[164:167], v[48:51]
	v_mfma_f32_16x16x32_bf16 v[36:39], v[72:75], v[206:209], v[36:39]
	v_mfma_f32_16x16x32_bf16 v[32:35], v[84:87], v[206:209], v[32:35]
	v_mfma_f32_16x16x32_bf16 v[20:23], v[72:75], v[214:217], v[20:23]
	v_mfma_f32_16x16x32_bf16 v[12:15], v[84:87], v[214:217], v[12:15]
	v_mfma_f32_16x16x32_bf16 v[16:19], v[72:75], v[222:225], v[16:19]
	v_mfma_f32_16x16x32_bf16 v[4:7], v[84:87], v[222:225], v[4:7]
	s_setprio 0
	s_setprio 1
	v_mfma_f32_16x16x32_bf16 v[60:63], v[96:99], v[160:163], v[60:63]
	v_mfma_f32_16x16x32_bf16 v[56:59], v[104:107], v[160:163], v[56:59]
	v_mfma_f32_16x16x32_bf16 v[44:47], v[96:99], v[188:191], v[44:47]
	v_mfma_f32_16x16x32_bf16 v[40:43], v[104:107], v[188:191], v[40:43]
	v_mfma_f32_16x16x32_bf16 v[28:31], v[96:99], v[210:213], v[28:31]
	v_mfma_f32_16x16x32_bf16 v[24:27], v[104:107], v[210:213], v[24:27]
	v_mfma_f32_16x16x32_bf16 v[8:11], v[96:99], v[218:221], v[8:11]
	v_mfma_f32_16x16x32_bf16 v[0:3], v[104:107], v[218:221], v[0:3]
	v_mfma_f32_16x16x32_bf16 v[60:63], v[100:103], v[164:167], v[60:63]
	v_mfma_f32_16x16x32_bf16 v[56:59], v[108:111], v[164:167], v[56:59]
	v_mfma_f32_16x16x32_bf16 v[44:47], v[100:103], v[206:209], v[44:47]
	v_mfma_f32_16x16x32_bf16 v[40:43], v[108:111], v[206:209], v[40:43]
	v_mfma_f32_16x16x32_bf16 v[28:31], v[100:103], v[214:217], v[28:31]
	v_mfma_f32_16x16x32_bf16 v[24:27], v[108:111], v[214:217], v[24:27]
	v_mfma_f32_16x16x32_bf16 v[8:11], v[100:103], v[222:225], v[8:11]
	v_mfma_f32_16x16x32_bf16 v[0:3], v[108:111], v[222:225], v[0:3]
	s_setprio 0
	s_barrier
	s_add_i32 s85, 0, 0x18000
	s_add_i32 s86, 0, 0x1c000
	v_add_u32_e32 v84, s85, v193
	v_add_u32_e32 v108, s86, v193
	ds_read_b128 v[68:71], v84
	ds_read_b128 v[72:75], v84 offset:1024
	ds_read_b128 v[76:79], v84 offset:2048
	ds_read_b128 v[84:87], v84 offset:3072
	ds_read_b128 v[96:99], v108
	ds_read_b128 v[100:103], v108 offset:1024
	ds_read_b128 v[104:107], v108 offset:2048
	ds_read_b128 v[108:111], v108 offset:3072
	s_add_u32 s46, s70, 0x40000
	s_addc_u32 s47, s71, 0
	s_mov_b32 m0, s51
	v_lshl_add_u64 v[160:161], s[46:47], 0, v[170:171]
	ds_read_b128 v[162:165], v204 offset:32768
	ds_read_b128 v[166:169], v204 offset:33792
	ds_read_b128 v[188:191], v204 offset:34816
	ds_read_b128 v[206:209], v204 offset:35840
	ds_read_b128 v[210:213], v204 offset:36864
	ds_read_b128 v[214:217], v204 offset:37888
	ds_read_b128 v[218:221], v204 offset:38912
	ds_read_b128 v[222:225], v204 offset:39936
	global_load_lds_dwordx4 v[160:161], off
	v_lshl_add_u64 v[160:161], s[46:47], 0, v[174:175]
	s_mov_b32 m0, s72
	s_nop 0
	global_load_lds_dwordx4 v[160:161], off
	s_waitcnt vmcnt(8)
	s_waitcnt lgkmcnt(0)
	s_barrier
	s_setprio 1
	s_waitcnt lgkmcnt(0)
	v_mfma_f32_16x16x32_bf16 v[148:151], v[68:71], v[162:165], v[148:151]
	v_mfma_f32_16x16x32_bf16 v[144:147], v[76:79], v[162:165], v[144:147]
	v_mfma_f32_16x16x32_bf16 v[132:135], v[68:71], v[188:191], v[132:135]
	v_mfma_f32_16x16x32_bf16 v[128:131], v[76:79], v[188:191], v[128:131]
	v_mfma_f32_16x16x32_bf16 v[116:119], v[68:71], v[210:213], v[116:119]
	v_mfma_f32_16x16x32_bf16 v[92:95], v[76:79], v[210:213], v[92:95]
	v_mfma_f32_16x16x32_bf16 v[112:115], v[68:71], v[218:221], v[112:115]
	v_mfma_f32_16x16x32_bf16 v[80:83], v[76:79], v[218:221], v[80:83]
	v_mfma_f32_16x16x32_bf16 v[148:151], v[72:75], v[166:169], v[148:151]
	v_mfma_f32_16x16x32_bf16 v[144:147], v[84:87], v[166:169], v[144:147]
	v_mfma_f32_16x16x32_bf16 v[132:135], v[72:75], v[206:209], v[132:135]
	v_mfma_f32_16x16x32_bf16 v[128:131], v[84:87], v[206:209], v[128:131]
	v_mfma_f32_16x16x32_bf16 v[116:119], v[72:75], v[214:217], v[116:119]
	v_mfma_f32_16x16x32_bf16 v[92:95], v[84:87], v[214:217], v[92:95]
	v_mfma_f32_16x16x32_bf16 v[112:115], v[72:75], v[222:225], v[112:115]
	v_mfma_f32_16x16x32_bf16 v[80:83], v[84:87], v[222:225], v[80:83]
	s_setprio 0
	s_setprio 1
	v_mfma_f32_16x16x32_bf16 v[156:159], v[96:99], v[162:165], v[156:159]
	v_mfma_f32_16x16x32_bf16 v[152:155], v[104:107], v[162:165], v[152:155]
	v_mfma_f32_16x16x32_bf16 v[140:143], v[96:99], v[188:191], v[140:143]
	v_mfma_f32_16x16x32_bf16 v[136:139], v[104:107], v[188:191], v[136:139]
	v_mfma_f32_16x16x32_bf16 v[124:127], v[96:99], v[210:213], v[124:127]
	v_mfma_f32_16x16x32_bf16 v[120:123], v[104:107], v[210:213], v[120:123]
	v_mfma_f32_16x16x32_bf16 v[88:91], v[96:99], v[218:221], v[88:91]
	v_mfma_f32_16x16x32_bf16 v[64:67], v[104:107], v[218:221], v[64:67]
	v_mfma_f32_16x16x32_bf16 v[158:161], v[100:103], v[166:169], v[156:159]
	v_mfma_f32_16x16x32_bf16 v[152:155], v[108:111], v[166:169], v[152:155]
	v_mfma_f32_16x16x32_bf16 v[140:143], v[100:103], v[206:209], v[140:143]
	v_mfma_f32_16x16x32_bf16 v[136:139], v[108:111], v[206:209], v[136:139]
	v_mfma_f32_16x16x32_bf16 v[124:127], v[100:103], v[214:217], v[124:127]
	v_mfma_f32_16x16x32_bf16 v[120:123], v[108:111], v[214:217], v[120:123]
	v_mfma_f32_16x16x32_bf16 v[88:91], v[100:103], v[222:225], v[88:91]
	v_mfma_f32_16x16x32_bf16 v[64:67], v[108:111], v[222:225], v[64:67]
	s_setprio 0
	s_barrier
	s_add_i32 s46, s85, s48
	v_lshl_add_u64 v[156:157], v[226:227], 0, s[28:29]
	s_mov_b32 m0, s46
	ds_read_b128 v[162:165], v204 offset:49152
	ds_read_b128 v[166:169], v204 offset:50176
	ds_read_b128 v[188:191], v204 offset:51200
	ds_read_b128 v[206:209], v204 offset:52224
	ds_read_b128 v[210:213], v204 offset:53248
	ds_read_b128 v[214:217], v204 offset:54272
	ds_read_b128 v[218:221], v204 offset:55296
	ds_read_b128 v[222:225], v204 offset:56320
	global_load_lds_dwordx4 v[156:157], off
	s_add_i32 m0, s46, 0x2000
	s_add_u32 s46, s68, 0x40080
	v_lshl_add_u64 v[156:157], v[228:229], 0, s[28:29]
	s_addc_u32 s47, s69, 0
	s_add_i32 s68, s86, s48
	global_load_lds_dwordx4 v[156:157], off
	v_lshl_add_u64 v[156:157], s[46:47], 0, v[172:173]
	s_mov_b32 m0, s68
	s_nop 0
	global_load_lds_dwordx4 v[156:157], off
	v_lshl_add_u64 v[156:157], s[46:47], 0, v[176:177]
	s_add_i32 m0, s68, 0x2000
	s_nop 0
	global_load_lds_dwordx4 v[156:157], off
	v_lshl_add_u64 v[156:157], v[230:231], 0, s[28:29]
	s_mov_b32 m0, s76
	s_nop 0
	global_load_lds_dwordx4 v[156:157], off
	v_lshl_add_u64 v[156:157], v[232:233], 0, s[28:29]
	s_mov_b32 m0, s77
	s_nop 0
	global_load_lds_dwordx4 v[156:157], off
	s_waitcnt vmcnt(8)
	s_waitcnt lgkmcnt(0)
	s_barrier
	s_setprio 1
	s_waitcnt lgkmcnt(0)
	v_mfma_f32_16x16x32_bf16 v[52:55], v[68:71], v[162:165], v[52:55]
	v_mfma_f32_16x16x32_bf16 v[48:51], v[76:79], v[162:165], v[48:51]
	v_mfma_f32_16x16x32_bf16 v[36:39], v[68:71], v[188:191], v[36:39]
	v_mfma_f32_16x16x32_bf16 v[32:35], v[76:79], v[188:191], v[32:35]
	v_mfma_f32_16x16x32_bf16 v[20:23], v[68:71], v[210:213], v[20:23]
	v_mfma_f32_16x16x32_bf16 v[12:15], v[76:79], v[210:213], v[12:15]
	v_mfma_f32_16x16x32_bf16 v[16:19], v[68:71], v[218:221], v[16:19]
	v_mfma_f32_16x16x32_bf16 v[4:7], v[76:79], v[218:221], v[4:7]
	v_mfma_f32_16x16x32_bf16 v[52:55], v[72:75], v[166:169], v[52:55]
	v_mfma_f32_16x16x32_bf16 v[48:51], v[84:87], v[166:169], v[48:51]
	v_mfma_f32_16x16x32_bf16 v[36:39], v[72:75], v[206:209], v[36:39]
	v_mfma_f32_16x16x32_bf16 v[32:35], v[84:87], v[206:209], v[32:35]
	v_mfma_f32_16x16x32_bf16 v[20:23], v[72:75], v[214:217], v[20:23]
	v_mfma_f32_16x16x32_bf16 v[12:15], v[84:87], v[214:217], v[12:15]
	v_mfma_f32_16x16x32_bf16 v[16:19], v[72:75], v[222:225], v[16:19]
	v_mfma_f32_16x16x32_bf16 v[4:7], v[84:87], v[222:225], v[4:7]
	s_setprio 0
	s_setprio 1
	v_mfma_f32_16x16x32_bf16 v[60:63], v[96:99], v[162:165], v[60:63]
	v_mfma_f32_16x16x32_bf16 v[56:59], v[104:107], v[162:165], v[56:59]
	v_mfma_f32_16x16x32_bf16 v[44:47], v[96:99], v[188:191], v[44:47]
	v_mfma_f32_16x16x32_bf16 v[40:43], v[104:107], v[188:191], v[40:43]
	v_mfma_f32_16x16x32_bf16 v[28:31], v[96:99], v[210:213], v[28:31]
	v_mfma_f32_16x16x32_bf16 v[24:27], v[104:107], v[210:213], v[24:27]
	v_mfma_f32_16x16x32_bf16 v[8:11], v[96:99], v[218:221], v[8:11]
	v_mfma_f32_16x16x32_bf16 v[0:3], v[104:107], v[218:221], v[0:3]
	v_mfma_f32_16x16x32_bf16 v[60:63], v[100:103], v[166:169], v[60:63]
	v_mfma_f32_16x16x32_bf16 v[56:59], v[108:111], v[166:169], v[56:59]
	v_mfma_f32_16x16x32_bf16 v[44:47], v[100:103], v[206:209], v[44:47]
	v_mfma_f32_16x16x32_bf16 v[40:43], v[108:111], v[206:209], v[40:43]
	v_mfma_f32_16x16x32_bf16 v[28:31], v[100:103], v[214:217], v[28:31]
	v_mfma_f32_16x16x32_bf16 v[24:27], v[108:111], v[214:217], v[24:27]
	v_mfma_f32_16x16x32_bf16 v[8:11], v[100:103], v[222:225], v[8:11]
	v_mfma_f32_16x16x32_bf16 v[0:3], v[108:111], v[222:225], v[0:3]
	s_setprio 0
	s_barrier
	s_add_i32 s84, s84, 2
	s_add_u32 s66, s66, 0x100
	s_addc_u32 s67, s67, 0
	s_add_u32 s65, s65, 0x100
	s_addc_u32 s83, s83, 0
	s_cmp_gt_u32 s84, 13
	s_cbranch_scc0 .LBB0_1483
	s_and_b64 vcc, exec, s[30:31]
	s_cbranch_vccz .LBB0_1486
	s_barrier

.LBB0_1501:
	s_or_b64 exec, exec, s[10:11]
	v_mov_b32_e32 v80, 0
	v_mov_b32_e32 v82, 0
	v_mov_b32_e32 v81, 0
	v_mov_b32_e32 v83, 0
	v_mov_b32_e32 v88, 0
	v_mov_b32_e32 v89, 0
	s_waitcnt lgkmcnt(1)
	v_mov_b32_dpp v80, v64 row_ror:1 row_mask:0xf bank_mask:0xf
	v_mov_b32_dpp v82, v64 row_ror:2 row_mask:0xf bank_mask:0xf
	v_mov_b32_dpp v81, v65 row_ror:1 row_mask:0xf bank_mask:0xf
	v_mov_b32_dpp v83, v65 row_ror:2 row_mask:0xf bank_mask:0xf
	v_mov_b32_e32 v64, 0
	v_mov_b32_dpp v88, v66 row_ror:2 row_mask:0xf bank_mask:0xf
	v_mov_b32_e32 v65, 0
	v_mov_b32_dpp v89, v67 row_ror:2 row_mask:0xf bank_mask:0xf
	v_mov_b32_dpp v64, v66 row_ror:1 row_mask:0xf bank_mask:0xf
	v_mov_b32_dpp v88, v54 row_shr:2 row_mask:0xf bank_mask:0xf
	v_mov_b32_dpp v65, v67 row_ror:1 row_mask:0xf bank_mask:0xf
	v_mov_b32_dpp v89, v55 row_shr:2 row_mask:0xf bank_mask:0xf
	v_mov_b32_dpp v64, v54 row_shr:1 row_mask:0xf bank_mask:0xf
	v_mov_b32_dpp v65, v55 row_shr:1 row_mask:0xf bank_mask:0xf
	v_pk_fma_f32 v[66:67], v[102:103], v[88:89], v[110:111]
	v_mov_b32_dpp v82, v52 row_shr:2 row_mask:0xf bank_mask:0xf
	v_pk_fma_f32 v[64:65], v[106:107], v[64:65], v[66:67]
	v_mov_b32_dpp v83, v53 row_shr:2 row_mask:0xf bank_mask:0xf
	v_pk_fma_f32 v[64:65], v[54:55], v[98:99], v[64:65]
	v_mov_b32_dpp v80, v52 row_shr:1 row_mask:0xf bank_mask:0xf
	v_mul_f32_e32 v66, 0xbfb8aa3b, v65
	v_exp_f32_e32 v88, v66
	v_mov_b32_dpp v81, v53 row_shr:1 row_mask:0xf bank_mask:0xf
	v_pk_fma_f32 v[66:67], v[100:101], v[82:83], v[108:109]
	v_add_u32_e32 v90, 0x80, v205
	v_pk_fma_f32 v[66:67], v[104:105], v[80:81], v[66:67]
	v_add_f32_e32 v80, 1.0, v88
	v_rcp_f32_e32 v80, v80
	v_mul_f32_e32 v81, 0xbfb8aa3b, v64
	v_exp_f32_e32 v81, v81
	v_pk_fma_f32 v[66:67], v[52:53], v[96:97], v[66:67]
	v_mul_f32_e32 v65, v65, v80
	v_mul_f32_e32 v63, v63, v65
	v_add_f32_e32 v65, 1.0, v81
	v_mul_f32_e32 v80, 0xbfb8aa3b, v67
	v_rcp_f32_e32 v65, v65
	v_exp_f32_e32 v80, v80
	v_mul_f32_e32 v81, 0xbfb8aa3b, v66
	v_exp_f32_e32 v81, v81
	v_mul_f32_e32 v64, v64, v65
	v_add_f32_e32 v65, 1.0, v80
	v_rcp_f32_e32 v65, v65
	v_add_f32_e32 v80, 1.0, v81
	v_rcp_f32_e32 v80, v80
	v_mul_f32_e32 v62, v62, v64
	v_mul_f32_e32 v64, v67, v65
	v_mul_f32_e32 v61, v61, v64
	v_mul_f32_e32 v64, v66, v80
	v_mov_b32_e32 v80, 0
	v_mov_b32_e32 v81, 0
	v_mov_b32_e32 v66, 0
	s_waitcnt lgkmcnt(0)
	v_mov_b32_dpp v80, v158 row_ror:2 row_mask:0xf bank_mask:0xf
	v_mov_b32_e32 v67, 0
	v_mov_b32_dpp v81, v159 row_ror:2 row_mask:0xf bank_mask:0xf
	v_mov_b32_dpp v66, v158 row_ror:1 row_mask:0xf bank_mask:0xf
	v_mov_b32_dpp v80, v50 row_shr:2 row_mask:0xf bank_mask:0xf
	v_mov_b32_dpp v67, v159 row_ror:1 row_mask:0xf bank_mask:0xf
	v_mov_b32_dpp v81, v51 row_shr:2 row_mask:0xf bank_mask:0xf
	v_mov_b32_dpp v66, v50 row_shr:1 row_mask:0xf bank_mask:0xf
	v_mov_b32_dpp v67, v51 row_shr:1 row_mask:0xf bank_mask:0xf
	v_pk_fma_f32 v[80:81], v[74:75], v[80:81], v[86:87]
	v_mul_f32_e32 v60, v60, v64
	v_pk_fma_f32 v[66:67], v[78:79], v[66:67], v[80:81]
	v_mov_b32_e32 v64, 0
	v_pk_fma_f32 v[66:67], v[50:51], v[70:71], v[66:67]
	v_mov_b32_e32 v65, 0
	v_mul_f32_e32 v80, 0xbfb8aa3b, v67
	v_exp_f32_e32 v80, v80
	v_cvt_pk_bf16_f32 v60, v60, v61
	v_cvt_pk_bf16_f32 v61, v62, v63
	v_mov_b32_e32 v62, 0
	v_mov_b32_dpp v64, v156 row_ror:2 row_mask:0xf bank_mask:0xf
	v_mov_b32_e32 v63, 0
	v_mov_b32_dpp v65, v157 row_ror:2 row_mask:0xf bank_mask:0xf
	v_mov_b32_dpp v62, v156 row_ror:1 row_mask:0xf bank_mask:0xf
	v_mov_b32_dpp v64, v48 row_shr:2 row_mask:0xf bank_mask:0xf
	v_mov_b32_dpp v63, v157 row_ror:1 row_mask:0xf bank_mask:0xf
	v_mov_b32_dpp v65, v49 row_shr:2 row_mask:0xf bank_mask:0xf
	v_mov_b32_dpp v62, v48 row_shr:1 row_mask:0xf bank_mask:0xf
	v_mov_b32_dpp v63, v49 row_shr:1 row_mask:0xf bank_mask:0xf
	v_pk_fma_f32 v[64:65], v[72:73], v[64:65], v[84:85]
	s_andn2_b64 vcc, exec, s[8:9]
	v_pk_fma_f32 v[62:63], v[76:77], v[62:63], v[64:65]
	v_add_f32_e32 v64, 1.0, v80
	v_rcp_f32_e32 v64, v64
	v_mul_f32_e32 v65, 0xbfb8aa3b, v66
	v_exp_f32_e32 v65, v65
	v_pk_fma_f32 v[62:63], v[48:49], v[68:69], v[62:63]
	v_mul_f32_e32 v64, v67, v64
	v_mul_f32_e32 v59, v59, v64
	v_add_f32_e32 v64, 1.0, v65
	v_mul_f32_e32 v65, 0xbfb8aa3b, v63
	v_mul_f32_e32 v67, 0xbfb8aa3b, v62
	v_rcp_f32_e32 v64, v64
	v_exp_f32_e32 v65, v65
	v_exp_f32_e32 v67, v67
	s_mov_b64 s[8:9], -1
	v_mul_f32_e32 v64, v66, v64
	v_add_f32_e32 v65, 1.0, v65
	v_add_f32_e32 v66, 1.0, v67
	v_rcp_f32_e32 v65, v65
	v_rcp_f32_e32 v66, v66
	v_mul_f32_e32 v58, v58, v64
	v_mul_f32_e32 v63, v63, v65
	v_mul_f32_e32 v62, v62, v66
	v_mul_f32_e32 v57, v57, v63
	v_mul_f32_e32 v56, v56, v62
	v_cvt_pk_bf16_f32 v62, v56, v57
	v_mov_b64_e32 v[56:57], s[18:19]
	v_cvt_pk_bf16_f32 v63, v58, v59
	v_mad_i64_i32 v[58:59], s[10:11], v90, s82, v[56:57]
	v_lshl_add_u64 v[58:59], v[58:59], 0, v[152:153]
	global_store_dwordx4 v[58:59], v[60:63], off
	v_mov_b32_e32 v58, 0
	v_mov_b32_e32 v59, 0
	v_mov_b32_e32 v60, 0
	v_mov_b32_e32 v61, 0
	v_mov_b32_e32 v62, 0
	v_mov_b32_e32 v63, 0
	v_mov_b32_dpp v58, v52 row_ror:1 row_mask:0xf bank_mask:0xf
	v_mov_b32_dpp v60, v52 row_ror:2 row_mask:0xf bank_mask:0xf
	v_mov_b32_dpp v59, v53 row_ror:1 row_mask:0xf bank_mask:0xf
	v_mov_b32_dpp v61, v53 row_ror:2 row_mask:0xf bank_mask:0xf
	v_mov_b32_e32 v52, 0
	v_mov_b32_dpp v62, v54 row_ror:2 row_mask:0xf bank_mask:0xf
	v_mov_b32_e32 v53, 0
	v_mov_b32_dpp v63, v55 row_ror:2 row_mask:0xf bank_mask:0xf
	v_mov_b32_dpp v52, v54 row_ror:1 row_mask:0xf bank_mask:0xf
	v_mov_b32_dpp v62, v38 row_shr:2 row_mask:0xf bank_mask:0xf
	v_mov_b32_dpp v53, v55 row_ror:1 row_mask:0xf bank_mask:0xf
	v_mov_b32_dpp v63, v39 row_shr:2 row_mask:0xf bank_mask:0xf
	v_mov_b32_dpp v52, v38 row_shr:1 row_mask:0xf bank_mask:0xf
	v_mov_b32_dpp v53, v39 row_shr:1 row_mask:0xf bank_mask:0xf
	v_pk_fma_f32 v[54:55], v[102:103], v[62:63], v[110:111]
	v_mov_b32_dpp v60, v36 row_shr:2 row_mask:0xf bank_mask:0xf
	v_pk_fma_f32 v[52:53], v[106:107], v[52:53], v[54:55]
	v_mov_b32_dpp v61, v37 row_shr:2 row_mask:0xf bank_mask:0xf
	v_pk_fma_f32 v[52:53], v[38:39], v[98:99], v[52:53]
	v_mov_b32_dpp v58, v36 row_shr:1 row_mask:0xf bank_mask:0xf
	v_mul_f32_e32 v54, 0xbfb8aa3b, v53
	v_exp_f32_e32 v62, v54
	v_mov_b32_dpp v59, v37 row_shr:1 row_mask:0xf bank_mask:0xf
	v_pk_fma_f32 v[54:55], v[100:101], v[60:61], v[108:109]
	s_nop 0
	v_pk_fma_f32 v[54:55], v[104:105], v[58:59], v[54:55]
	v_add_f32_e32 v58, 1.0, v62
	v_rcp_f32_e32 v58, v58
	v_mul_f32_e32 v59, 0xbfb8aa3b, v52
	v_exp_f32_e32 v59, v59
	v_pk_fma_f32 v[54:55], v[36:37], v[96:97], v[54:55]
	v_mul_f32_e32 v53, v53, v58
	v_mul_f32_e32 v47, v47, v53
	v_add_f32_e32 v53, 1.0, v59
	v_mul_f32_e32 v58, 0xbfb8aa3b, v55
	v_rcp_f32_e32 v53, v53
	v_exp_f32_e32 v58, v58
	v_mul_f32_e32 v59, 0xbfb8aa3b, v54
	v_exp_f32_e32 v59, v59
	v_mul_f32_e32 v52, v52, v53
	v_add_f32_e32 v53, 1.0, v58
	v_rcp_f32_e32 v53, v53
	v_add_f32_e32 v58, 1.0, v59
	v_rcp_f32_e32 v58, v58
	v_mul_f32_e32 v46, v46, v52
	v_mul_f32_e32 v52, v55, v53
	v_mul_f32_e32 v45, v45, v52
	v_mul_f32_e32 v52, v54, v58
	v_mul_f32_e32 v44, v44, v52
	v_cvt_pk_bf16_f32 v44, v44, v45
	v_cvt_pk_bf16_f32 v45, v46, v47
	v_mov_b32_e32 v46, 0
	v_mov_b32_e32 v52, 0
	v_mov_b32_e32 v47, 0
	v_mov_b32_e32 v53, 0
	v_mov_b32_e32 v54, 0
	v_mov_b32_e32 v55, 0
	v_mov_b32_dpp v46, v48 row_ror:1 row_mask:0xf bank_mask:0xf
	v_mov_b32_dpp v52, v48 row_ror:2 row_mask:0xf bank_mask:0xf
	v_mov_b32_dpp v47, v49 row_ror:1 row_mask:0xf bank_mask:0xf
	v_mov_b32_dpp v53, v49 row_ror:2 row_mask:0xf bank_mask:0xf
	v_mov_b32_e32 v48, 0
	v_mov_b32_dpp v54, v50 row_ror:2 row_mask:0xf bank_mask:0xf
	v_mov_b32_e32 v49, 0
	v_mov_b32_dpp v55, v51 row_ror:2 row_mask:0xf bank_mask:0xf
	v_mov_b32_dpp v48, v50 row_ror:1 row_mask:0xf bank_mask:0xf
	v_mov_b32_dpp v54, v34 row_shr:2 row_mask:0xf bank_mask:0xf
	v_mov_b32_dpp v49, v51 row_ror:1 row_mask:0xf bank_mask:0xf
	v_mov_b32_dpp v55, v35 row_shr:2 row_mask:0xf bank_mask:0xf
	v_mov_b32_dpp v48, v34 row_shr:1 row_mask:0xf bank_mask:0xf
	v_mov_b32_dpp v49, v35 row_shr:1 row_mask:0xf bank_mask:0xf
	v_pk_fma_f32 v[50:51], v[74:75], v[54:55], v[86:87]
	v_mov_b32_dpp v52, v32 row_shr:2 row_mask:0xf bank_mask:0xf
	v_pk_fma_f32 v[48:49], v[78:79], v[48:49], v[50:51]
	v_mov_b32_dpp v53, v33 row_shr:2 row_mask:0xf bank_mask:0xf
	v_pk_fma_f32 v[48:49], v[34:35], v[70:71], v[48:49]
	v_mov_b32_dpp v46, v32 row_shr:1 row_mask:0xf bank_mask:0xf
	v_mul_f32_e32 v50, 0xbfb8aa3b, v49
	v_exp_f32_e32 v54, v50
	v_mov_b32_dpp v47, v33 row_shr:1 row_mask:0xf bank_mask:0xf
	v_pk_fma_f32 v[50:51], v[72:73], v[52:53], v[84:85]
	s_nop 0
	v_pk_fma_f32 v[46:47], v[76:77], v[46:47], v[50:51]
	v_add_f32_e32 v50, 1.0, v54
	v_rcp_f32_e32 v50, v50
	v_mul_f32_e32 v51, 0xbfb8aa3b, v48
	v_exp_f32_e32 v51, v51
	v_pk_fma_f32 v[46:47], v[32:33], v[68:69], v[46:47]
	v_mul_f32_e32 v49, v49, v50
	v_mul_f32_e32 v43, v43, v49
	v_add_f32_e32 v49, 1.0, v51
	v_mul_f32_e32 v50, 0xbfb8aa3b, v47
	v_mul_f32_e32 v51, 0xbfb8aa3b, v46
	v_rcp_f32_e32 v49, v49
	v_exp_f32_e32 v50, v50
	v_exp_f32_e32 v51, v51
	v_mul_f32_e32 v48, v48, v49
	v_add_f32_e32 v49, 1.0, v50
	v_add_f32_e32 v50, 1.0, v51
	v_rcp_f32_e32 v50, v50
	v_rcp_f32_e32 v49, v49
	v_mul_f32_e32 v42, v42, v48
	v_mul_f32_e32 v46, v46, v50
	v_mul_f32_e32 v47, v47, v49
	v_mul_f32_e32 v40, v40, v46
	v_mul_f32_e32 v41, v41, v47
	v_cvt_pk_bf16_f32 v46, v40, v41
	v_add_u32_e32 v40, 0x90, v205
	v_mad_i64_i32 v[40:41], s[10:11], v40, s82, v[56:57]
	v_lshl_add_u64 v[40:41], v[40:41], 0, v[152:153]
	v_cvt_pk_bf16_f32 v47, v42, v43
	global_store_dwordx4 v[40:41], v[44:47], off
	v_mov_b32_e32 v40, 0
	v_mov_b32_e32 v42, 0
	v_mov_b32_e32 v41, 0
	v_mov_b32_e32 v43, 0
	v_mov_b32_e32 v44, 0
	v_mov_b32_e32 v45, 0
	v_mov_b32_dpp v40, v36 row_ror:1 row_mask:0xf bank_mask:0xf
	v_mov_b32_dpp v42, v36 row_ror:2 row_mask:0xf bank_mask:0xf
	v_mov_b32_dpp v41, v37 row_ror:1 row_mask:0xf bank_mask:0xf
	v_mov_b32_dpp v43, v37 row_ror:2 row_mask:0xf bank_mask:0xf
	v_mov_b32_e32 v36, 0
	v_mov_b32_dpp v44, v38 row_ror:2 row_mask:0xf bank_mask:0xf
	v_mov_b32_e32 v37, 0
	v_mov_b32_dpp v45, v39 row_ror:2 row_mask:0xf bank_mask:0xf
	v_mov_b32_dpp v36, v38 row_ror:1 row_mask:0xf bank_mask:0xf
	v_mov_b32_dpp v44, v22 row_shr:2 row_mask:0xf bank_mask:0xf
	v_mov_b32_dpp v37, v39 row_ror:1 row_mask:0xf bank_mask:0xf
	v_mov_b32_dpp v45, v23 row_shr:2 row_mask:0xf bank_mask:0xf
	v_mov_b32_dpp v36, v22 row_shr:1 row_mask:0xf bank_mask:0xf
	v_mov_b32_dpp v37, v23 row_shr:1 row_mask:0xf bank_mask:0xf
	v_pk_fma_f32 v[38:39], v[102:103], v[44:45], v[110:111]
	v_mov_b32_dpp v42, v20 row_shr:2 row_mask:0xf bank_mask:0xf
	v_pk_fma_f32 v[36:37], v[106:107], v[36:37], v[38:39]
	v_mov_b32_dpp v43, v21 row_shr:2 row_mask:0xf bank_mask:0xf
	v_pk_fma_f32 v[36:37], v[22:23], v[98:99], v[36:37]
	v_mov_b32_dpp v40, v20 row_shr:1 row_mask:0xf bank_mask:0xf
	v_mul_f32_e32 v38, 0xbfb8aa3b, v37
	v_exp_f32_e32 v44, v38
	v_mov_b32_dpp v41, v21 row_shr:1 row_mask:0xf bank_mask:0xf
	v_pk_fma_f32 v[38:39], v[100:101], v[42:43], v[108:109]
	s_nop 0
	v_pk_fma_f32 v[38:39], v[104:105], v[40:41], v[38:39]
	v_add_f32_e32 v40, 1.0, v44
	v_rcp_f32_e32 v40, v40
	v_mul_f32_e32 v41, 0xbfb8aa3b, v36
	v_exp_f32_e32 v41, v41
	v_pk_fma_f32 v[38:39], v[20:21], v[96:97], v[38:39]
	v_mul_f32_e32 v37, v37, v40
	v_mul_f32_e32 v31, v31, v37
	v_add_f32_e32 v37, 1.0, v41
	v_mul_f32_e32 v40, 0xbfb8aa3b, v39
	v_rcp_f32_e32 v37, v37
	v_exp_f32_e32 v40, v40
	v_mul_f32_e32 v41, 0xbfb8aa3b, v38
	v_exp_f32_e32 v41, v41
	v_mul_f32_e32 v36, v36, v37
	v_add_f32_e32 v37, 1.0, v40
	v_rcp_f32_e32 v37, v37
	v_add_f32_e32 v40, 1.0, v41
	v_rcp_f32_e32 v40, v40
	v_mul_f32_e32 v30, v30, v36
	v_mul_f32_e32 v36, v39, v37
	v_mul_f32_e32 v29, v29, v36
	v_mul_f32_e32 v36, v38, v40
	v_mul_f32_e32 v28, v28, v36
	v_cvt_pk_bf16_f32 v28, v28, v29
	v_cvt_pk_bf16_f32 v29, v30, v31
	v_mov_b32_e32 v30, 0
	v_mov_b32_e32 v36, 0
	v_mov_b32_e32 v31, 0
	v_mov_b32_e32 v37, 0
	v_mov_b32_e32 v38, 0
	v_mov_b32_e32 v39, 0
	v_mov_b32_dpp v30, v32 row_ror:1 row_mask:0xf bank_mask:0xf
	v_mov_b32_dpp v36, v32 row_ror:2 row_mask:0xf bank_mask:0xf
	v_mov_b32_dpp v31, v33 row_ror:1 row_mask:0xf bank_mask:0xf
	v_mov_b32_dpp v37, v33 row_ror:2 row_mask:0xf bank_mask:0xf
	v_mov_b32_e32 v32, 0
	v_mov_b32_dpp v38, v34 row_ror:2 row_mask:0xf bank_mask:0xf
	v_mov_b32_e32 v33, 0
	v_mov_b32_dpp v39, v35 row_ror:2 row_mask:0xf bank_mask:0xf
	v_mov_b32_dpp v32, v34 row_ror:1 row_mask:0xf bank_mask:0xf
	v_mov_b32_dpp v38, v14 row_shr:2 row_mask:0xf bank_mask:0xf
	v_mov_b32_dpp v33, v35 row_ror:1 row_mask:0xf bank_mask:0xf
	v_mov_b32_dpp v39, v15 row_shr:2 row_mask:0xf bank_mask:0xf
	v_mov_b32_dpp v32, v14 row_shr:1 row_mask:0xf bank_mask:0xf
	v_mov_b32_dpp v33, v15 row_shr:1 row_mask:0xf bank_mask:0xf
	v_pk_fma_f32 v[34:35], v[74:75], v[38:39], v[86:87]
	v_mov_b32_dpp v36, v12 row_shr:2 row_mask:0xf bank_mask:0xf
	v_pk_fma_f32 v[32:33], v[78:79], v[32:33], v[34:35]
	v_mov_b32_dpp v37, v13 row_shr:2 row_mask:0xf bank_mask:0xf
	v_pk_fma_f32 v[32:33], v[14:15], v[70:71], v[32:33]
	v_mov_b32_dpp v30, v12 row_shr:1 row_mask:0xf bank_mask:0xf
	v_mul_f32_e32 v34, 0xbfb8aa3b, v33
	v_exp_f32_e32 v38, v34
	v_mov_b32_dpp v31, v13 row_shr:1 row_mask:0xf bank_mask:0xf
	v_pk_fma_f32 v[34:35], v[72:73], v[36:37], v[84:85]
	s_nop 0
	v_pk_fma_f32 v[30:31], v[76:77], v[30:31], v[34:35]
	v_add_f32_e32 v34, 1.0, v38
	v_rcp_f32_e32 v34, v34
	v_mul_f32_e32 v35, 0xbfb8aa3b, v32
	v_exp_f32_e32 v35, v35
	v_pk_fma_f32 v[30:31], v[12:13], v[68:69], v[30:31]
	v_mul_f32_e32 v33, v33, v34
	v_mul_f32_e32 v27, v27, v33
	v_add_f32_e32 v33, 1.0, v35
	v_mul_f32_e32 v34, 0xbfb8aa3b, v31
	v_mul_f32_e32 v35, 0xbfb8aa3b, v30
	v_rcp_f32_e32 v33, v33
	v_exp_f32_e32 v34, v34
	v_exp_f32_e32 v35, v35
	v_mul_f32_e32 v32, v32, v33
	v_add_f32_e32 v33, 1.0, v34
	v_add_f32_e32 v34, 1.0, v35
	v_rcp_f32_e32 v34, v34
	v_rcp_f32_e32 v33, v33
	v_mul_f32_e32 v26, v26, v32
	v_mul_f32_e32 v30, v30, v34
	v_mul_f32_e32 v31, v31, v33
	v_mul_f32_e32 v24, v24, v30
	v_mul_f32_e32 v25, v25, v31
	v_cvt_pk_bf16_f32 v30, v24, v25
	v_add_u32_e32 v24, 0xa0, v205
	v_mad_i64_i32 v[24:25], s[10:11], v24, s82, v[56:57]
	v_lshl_add_u64 v[24:25], v[24:25], 0, v[152:153]
	v_cvt_pk_bf16_f32 v31, v26, v27
	global_store_dwordx4 v[24:25], v[28:31], off
	v_mov_b32_e32 v24, 0
	v_mov_b32_e32 v26, 0
	v_mov_b32_e32 v25, 0
	v_mov_b32_e32 v27, 0
	v_mov_b32_e32 v28, 0
	v_mov_b32_e32 v29, 0
	v_mov_b32_dpp v24, v20 row_ror:1 row_mask:0xf bank_mask:0xf
	v_mov_b32_dpp v26, v20 row_ror:2 row_mask:0xf bank_mask:0xf
	v_mov_b32_dpp v25, v21 row_ror:1 row_mask:0xf bank_mask:0xf
	v_mov_b32_dpp v27, v21 row_ror:2 row_mask:0xf bank_mask:0xf
	v_mov_b32_e32 v20, 0
	v_mov_b32_dpp v28, v22 row_ror:2 row_mask:0xf bank_mask:0xf
	v_mov_b32_e32 v21, 0
	v_mov_b32_dpp v29, v23 row_ror:2 row_mask:0xf bank_mask:0xf
	v_mov_b32_dpp v20, v22 row_ror:1 row_mask:0xf bank_mask:0xf
	v_mov_b32_dpp v28, v18 row_shr:2 row_mask:0xf bank_mask:0xf
	v_mov_b32_dpp v21, v23 row_ror:1 row_mask:0xf bank_mask:0xf
	v_mov_b32_dpp v29, v19 row_shr:2 row_mask:0xf bank_mask:0xf
	v_mov_b32_dpp v20, v18 row_shr:1 row_mask:0xf bank_mask:0xf
	v_mov_b32_dpp v21, v19 row_shr:1 row_mask:0xf bank_mask:0xf
	v_pk_fma_f32 v[22:23], v[102:103], v[28:29], v[110:111]
	v_mov_b32_dpp v26, v16 row_shr:2 row_mask:0xf bank_mask:0xf
	v_pk_fma_f32 v[20:21], v[106:107], v[20:21], v[22:23]
	v_mov_b32_dpp v27, v17 row_shr:2 row_mask:0xf bank_mask:0xf
	v_pk_fma_f32 v[18:19], v[18:19], v[98:99], v[20:21]
	v_mov_b32_dpp v24, v16 row_shr:1 row_mask:0xf bank_mask:0xf
	v_mul_f32_e32 v20, 0xbfb8aa3b, v19
	v_exp_f32_e32 v22, v20
	v_mul_f32_e32 v23, 0xbfb8aa3b, v18
	v_exp_f32_e32 v23, v23
	v_mov_b32_dpp v25, v17 row_shr:1 row_mask:0xf bank_mask:0xf
	v_add_f32_e32 v22, 1.0, v22
	v_rcp_f32_e32 v22, v22
	v_pk_fma_f32 v[20:21], v[100:101], v[26:27], v[108:109]
	v_mul_f32_e32 v19, v19, v22
	v_pk_fma_f32 v[20:21], v[104:105], v[24:25], v[20:21]
	v_mul_f32_e32 v11, v11, v19
	v_pk_fma_f32 v[16:17], v[16:17], v[96:97], v[20:21]
	v_add_f32_e32 v19, 1.0, v23
	v_mul_f32_e32 v20, 0xbfb8aa3b, v17
	v_mul_f32_e32 v21, 0xbfb8aa3b, v16
	v_rcp_f32_e32 v19, v19
	v_exp_f32_e32 v20, v20
	v_exp_f32_e32 v21, v21
	v_mul_f32_e32 v18, v18, v19
	v_add_f32_e32 v19, 1.0, v20
	v_add_f32_e32 v20, 1.0, v21
	v_rcp_f32_e32 v19, v19
	v_rcp_f32_e32 v20, v20
	v_mul_f32_e32 v10, v10, v18
	v_mov_b32_e32 v18, 0
	v_mul_f32_e32 v17, v17, v19
	v_mul_f32_e32 v16, v16, v20
	v_mul_f32_e32 v9, v9, v17
	v_mul_f32_e32 v8, v8, v16
	v_cvt_pk_bf16_f32 v8, v8, v9
	v_cvt_pk_bf16_f32 v9, v10, v11
	v_mov_b32_e32 v10, 0
	v_mov_b32_e32 v16, 0
	v_mov_b32_e32 v11, 0
	v_mov_b32_e32 v17, 0
	v_mov_b32_e32 v19, 0
	v_mov_b32_dpp v10, v12 row_ror:1 row_mask:0xf bank_mask:0xf
	v_mov_b32_dpp v16, v12 row_ror:2 row_mask:0xf bank_mask:0xf
	v_mov_b32_dpp v11, v13 row_ror:1 row_mask:0xf bank_mask:0xf
	v_mov_b32_dpp v17, v13 row_ror:2 row_mask:0xf bank_mask:0xf
	v_mov_b32_e32 v12, 0
	v_mov_b32_dpp v18, v14 row_ror:2 row_mask:0xf bank_mask:0xf
	v_mov_b32_e32 v13, 0
	v_mov_b32_dpp v19, v15 row_ror:2 row_mask:0xf bank_mask:0xf
	v_mov_b32_dpp v12, v14 row_ror:1 row_mask:0xf bank_mask:0xf
	v_mov_b32_dpp v18, v6 row_shr:2 row_mask:0xf bank_mask:0xf
	v_mov_b32_dpp v13, v15 row_ror:1 row_mask:0xf bank_mask:0xf
	v_mov_b32_dpp v19, v7 row_shr:2 row_mask:0xf bank_mask:0xf
	v_mov_b32_dpp v12, v6 row_shr:1 row_mask:0xf bank_mask:0xf
	v_mov_b32_dpp v13, v7 row_shr:1 row_mask:0xf bank_mask:0xf
	v_pk_fma_f32 v[14:15], v[74:75], v[18:19], v[86:87]
	v_mov_b32_dpp v16, v4 row_shr:2 row_mask:0xf bank_mask:0xf
	v_pk_fma_f32 v[12:13], v[78:79], v[12:13], v[14:15]
	v_mov_b32_dpp v17, v5 row_shr:2 row_mask:0xf bank_mask:0xf
	v_pk_fma_f32 v[6:7], v[6:7], v[70:71], v[12:13]
	v_mov_b32_dpp v10, v4 row_shr:1 row_mask:0xf bank_mask:0xf
	v_mul_f32_e32 v12, 0xbfb8aa3b, v7
	v_exp_f32_e32 v14, v12
	v_mov_b32_dpp v11, v5 row_shr:1 row_mask:0xf bank_mask:0xf
	v_pk_fma_f32 v[12:13], v[72:73], v[16:17], v[84:85]
	s_nop 0
	v_pk_fma_f32 v[10:11], v[76:77], v[10:11], v[12:13]
	v_add_f32_e32 v12, 1.0, v14
	v_rcp_f32_e32 v12, v12
	v_mul_f32_e32 v13, 0xbfb8aa3b, v6
	v_exp_f32_e32 v13, v13
	v_pk_fma_f32 v[4:5], v[4:5], v[68:69], v[10:11]
	v_mul_f32_e32 v7, v7, v12
	v_mul_f32_e32 v3, v3, v7
	v_add_f32_e32 v7, 1.0, v13
	v_mul_f32_e32 v10, 0xbfb8aa3b, v5
	v_mul_f32_e32 v11, 0xbfb8aa3b, v4
	v_rcp_f32_e32 v7, v7
	v_exp_f32_e32 v10, v10
	v_exp_f32_e32 v11, v11
	v_mul_f32_e32 v6, v6, v7
	v_add_f32_e32 v7, 1.0, v10
	v_add_f32_e32 v10, 1.0, v11
	v_rcp_f32_e32 v10, v10
	v_rcp_f32_e32 v7, v7
	v_mul_f32_e32 v2, v2, v6
	v_mul_f32_e32 v4, v4, v10
	v_mul_f32_e32 v5, v5, v7
	v_mul_f32_e32 v0, v0, v4
	v_mul_f32_e32 v1, v1, v5
	v_cvt_pk_bf16_f32 v10, v0, v1
	v_add_u32_e32 v0, 0xb0, v205
	v_mad_i64_i32 v[0:1], s[10:11], v0, s82, v[56:57]
	v_lshl_add_u64 v[0:1], v[0:1], 0, v[152:153]
	v_cvt_pk_bf16_f32 v11, v2, v3
	global_store_dwordx4 v[0:1], v[8:11], off
	s_waitcnt lgkmcnt(0)
	s_barrier
	s_cbranch_vccnz .LBB0_1479
	s_andn2_b64 vcc, exec, s[16:17]
	s_cbranch_vccnz .LBB0_1478
	s_barrier
	s_branch .LBB0_1478

.LBB0_1663:
	s_cmp_lt_i32 s96, 11
	s_cselect_b64 s[2:3], -1, 0
	s_cmp_gt_i32 s97, 10
	s_cselect_b64 s[4:5], -1, 0
	s_and_b64 s[2:3], s[2:3], s[4:5]
	s_andn2_b64 vcc, exec, s[2:3]
	s_cbranch_vccnz .LBB0_1672
	s_and_b32 s2, s95, 0xffffffc0
	v_mbcnt_hi_u32_b32 v0, -1, v254
	v_add_u32_e32 v1, s2, v0
	v_xor_b32_e32 v2, 1, v0
	v_and_b32_e32 v92, 63, v1
	v_and_b32_e32 v1, 64, v0
	v_add_u32_e32 v1, 64, v1
	v_cmp_lt_i32_e32 vcc, v2, v1
	s_cmpk_gt_i32 s34, 0x1fff
	v_lshlrev_b32_e32 v8, 3, v92
	v_cndmask_b32_e32 v2, v0, v2, vcc
	v_lshlrev_b32_e32 v86, 2, v2
	v_xor_b32_e32 v2, 2, v0
	v_cmp_lt_i32_e32 vcc, v2, v1
	v_mov_b32_e32 v9, 0
	s_nop 0
	v_cndmask_b32_e32 v2, v0, v2, vcc
	v_lshlrev_b32_e32 v87, 2, v2
	v_xor_b32_e32 v2, 4, v0
	v_cmp_lt_i32_e32 vcc, v2, v1
	s_nop 1
	v_cndmask_b32_e32 v2, v0, v2, vcc
	v_lshlrev_b32_e32 v88, 2, v2
	v_xor_b32_e32 v2, 8, v0
	v_cmp_lt_i32_e32 vcc, v2, v1
	s_nop 1
	v_cndmask_b32_e32 v2, v0, v2, vcc
	v_lshlrev_b32_e32 v89, 2, v2
	v_xor_b32_e32 v2, 16, v0
	v_cmp_lt_i32_e32 vcc, v2, v1
	s_nop 1
	v_cndmask_b32_e32 v2, v0, v2, vcc
	v_lshlrev_b32_e32 v90, 2, v2
	v_xor_b32_e32 v2, 32, v0
	v_cmp_lt_i32_e32 vcc, v2, v1
	s_nop 1
	v_cndmask_b32_e32 v0, v0, v2, vcc
	v_lshlrev_b32_e32 v91, 2, v0
	s_cbranch_scc1 .LBB0_1667
	s_lshl_b32 s14, s34, 2
	s_ashr_i32 s15, s14, 31
	s_lshl_b32 s12, s44, 5
	s_lshl_b64 s[2:3], s[14:15], 11
	s_add_u32 s2, s38, s2
	s_load_dwordx4 s[4:7], s[0:1], 0xd0
	s_addc_u32 s3, s39, s3
	v_lshl_add_u64 v[2:3], s[2:3], 0, v[8:9]
	s_mov_b64 s[2:3], 0x35300000
	s_ashr_i32 s13, s12, 31
	v_lshl_add_u64 v[14:15], v[2:3], 0, s[2:3]
	s_lshl_b64 s[16:17], s[12:13], 11
	s_lshl_b64 s[2:3], s[14:15], 12
	s_add_u32 s2, s36, s2
	v_lshlrev_b32_e32 v0, 4, v92
	v_mov_b32_e32 v1, v9
	s_addc_u32 s3, s37, s3
	s_waitcnt lgkmcnt(0)
	v_lshl_add_u64 v[10:11], s[4:5], 0, v[0:1]
	v_lshl_add_u64 v[12:13], s[6:7], 0, v[0:1]
	s_waitcnt vmcnt(0)
	v_lshl_add_u64 v[16:17], s[2:3], 0, v[0:1]
	s_lshl_b64 s[18:19], s[12:13], 12
	s_movk_i32 s13, 0x1000
	v_mov_b32_e32 v9, 0x3727c5ac
	s_mov_b32 s15, 0xf800000
	v_mov_b32_e32 v93, 0x260
	s_movk_i32 s20, 0x2000
	s_movk_i32 s21, 0x3000
	global_load_dwordx4 v[160:163], v[10:11], off offset:1024
	global_load_dwordx4 v[164:167], v[12:13], off offset:1024
	global_load_dwordx4 v[168:171], v[10:11], off offset:2048
	global_load_dwordx4 v[172:175], v[12:13], off offset:2048
	global_load_dwordx4 v[176:179], v[10:11], off offset:3072
	global_load_dwordx4 v[180:183], v[12:13], off offset:3072
.LBB0_1666:
	global_load_dwordx2 v[36:37], v[14:15], off nt
	global_load_dwordx2 v[22:23], v[14:15], off offset:1536 nt
	global_load_dwordx2 v[34:35], v[14:15], off offset:2048 nt
	global_load_dwordx2 v[24:25], v[14:15], off offset:3584 nt
	global_load_dwordx2 v[32:33], v[14:15], off offset:512 nt
	global_load_dwordx2 v[30:31], v[14:15], off offset:2560 nt
	global_load_dwordx2 v[28:29], v[14:15], off offset:1024 nt
	global_load_dwordx2 v[26:27], v[14:15], off offset:3072 nt
	v_add_co_u32_e32 v38, vcc, 0x1000, v14
	global_load_dwordx4 v[0:3], v[10:11], off
	global_load_dwordx4 v[4:7], v[12:13], off
	v_addc_co_u32_e32 v39, vcc, 0, v15, vcc
	global_load_dwordx2 v[40:41], v[38:39], off nt
	global_load_dwordx2 v[42:43], v[38:39], off offset:1536 nt
	global_load_dwordx2 v[44:45], v[38:39], off offset:2048 nt
	global_load_dwordx2 v[46:47], v[38:39], off offset:3584 nt
	global_load_dwordx2 v[48:49], v[38:39], off offset:512 nt
	global_load_dwordx2 v[50:51], v[38:39], off offset:2560 nt
	global_load_dwordx2 v[52:53], v[38:39], off offset:1024 nt
	global_load_dwordx2 v[54:55], v[38:39], off offset:3072 nt
	v_add_co_u32_e64 v18, s[2:3], s20, v16
	s_add_i32 s14, s14, s12
	s_nop 0
	v_addc_co_u32_e64 v19, s[2:3], 0, v17, s[2:3]
	v_add_co_u32_e64 v20, s[2:3], s21, v16
	v_lshl_add_u64 v[14:15], v[14:15], 0, s[16:17]
	s_nop 0
	v_addc_co_u32_e64 v21, s[2:3], 0, v17, s[2:3]
	s_cmpk_gt_i32 s14, 0x7fff
	s_waitcnt vmcnt(17)
	v_lshlrev_b32_e32 v38, 16, v36
	v_and_b32_e32 v39, 0xffff0000, v36
	s_waitcnt vmcnt(15)
	v_lshlrev_b32_e32 v62, 16, v34
	v_lshlrev_b32_e32 v74, 16, v22
	v_and_b32_e32 v75, 0xffff0000, v22
	v_add_f32_e32 v22, 0, v38
	v_lshlrev_b32_e32 v36, 16, v37
	v_lshlrev_b32_e32 v56, 16, v23
	v_and_b32_e32 v57, 0xffff0000, v23
	v_and_b32_e32 v63, 0xffff0000, v34
	v_add_f32_e32 v23, 0, v62
	v_add_f32_e32 v22, v22, v39
	v_and_b32_e32 v37, 0xffff0000, v37
	v_lshlrev_b32_e32 v34, 16, v35
	v_add_f32_e32 v23, v23, v63
	s_waitcnt vmcnt(7)
	v_lshlrev_b32_e32 v82, 16, v40
	s_waitcnt vmcnt(5)
	v_lshlrev_b32_e32 v96, 16, v44
	v_add_f32_e32 v22, v22, v36
	v_and_b32_e32 v35, 0xffff0000, v35
	v_lshlrev_b32_e32 v64, 16, v25
	v_and_b32_e32 v65, 0xffff0000, v25
	v_lshlrev_b32_e32 v58, 16, v32
	v_lshlrev_b32_e32 v80, 16, v24
	v_and_b32_e32 v81, 0xffff0000, v24
	v_and_b32_e32 v83, 0xffff0000, v40
	v_and_b32_e32 v97, 0xffff0000, v44
	v_add_f32_e32 v23, v23, v34
	v_add_f32_e32 v24, 0, v82
	v_add_f32_e32 v25, 0, v96
	v_add_f32_e32 v22, v22, v37
	v_and_b32_e32 v59, 0xffff0000, v32
	v_lshlrev_b32_e32 v66, 16, v30
	v_lshlrev_b32_e32 v84, 16, v41
	v_lshlrev_b32_e32 v98, 16, v45
	v_add_f32_e32 v23, v23, v35
	v_add_f32_e32 v24, v24, v83
	v_add_f32_e32 v25, v25, v97
	v_add_f32_e32 v22, v22, v58
	v_lshlrev_b32_e32 v32, 16, v33
	v_and_b32_e32 v67, 0xffff0000, v30
	v_and_b32_e32 v85, 0xffff0000, v41
	v_and_b32_e32 v99, 0xffff0000, v45
	v_add_f32_e32 v24, v24, v84
	v_add_f32_e32 v25, v25, v98
	v_add_f32_e32 v23, v23, v66
	v_add_f32_e32 v22, v22, v59
	v_and_b32_e32 v33, 0xffff0000, v33
	v_lshlrev_b32_e32 v30, 16, v31
	s_waitcnt vmcnt(3)
	v_lshlrev_b32_e32 v102, 16, v48
	s_waitcnt vmcnt(2)
	v_lshlrev_b32_e32 v104, 16, v50
	v_add_f32_e32 v24, v24, v85
	v_add_f32_e32 v25, v25, v99
	v_add_f32_e32 v23, v23, v67
	v_add_f32_e32 v22, v22, v32
	v_and_b32_e32 v31, 0xffff0000, v31
	v_lshlrev_b32_e32 v68, 16, v28
	v_and_b32_e32 v103, 0xffff0000, v48
	v_and_b32_e32 v105, 0xffff0000, v50
	v_add_f32_e32 v23, v23, v30
	v_add_f32_e32 v24, v24, v102
	v_add_f32_e32 v25, v25, v104
	v_add_f32_e32 v22, v22, v33
	v_and_b32_e32 v69, 0xffff0000, v28
	v_lshlrev_b32_e32 v78, 16, v26
	v_lshlrev_b32_e32 v48, 16, v49
	v_lshlrev_b32_e32 v50, 16, v51
	v_add_f32_e32 v23, v23, v31
	v_add_f32_e32 v24, v24, v103
	v_add_f32_e32 v25, v25, v105
	v_add_f32_e32 v22, v22, v68
	v_lshlrev_b32_e32 v28, 16, v29
	v_and_b32_e32 v79, 0xffff0000, v26
	v_and_b32_e32 v49, 0xffff0000, v49
	v_and_b32_e32 v51, 0xffff0000, v51
	v_add_f32_e32 v24, v24, v48
	v_add_f32_e32 v25, v25, v50
	v_add_f32_e32 v23, v23, v78
	v_add_f32_e32 v22, v22, v69
	v_and_b32_e32 v29, 0xffff0000, v29
	v_lshlrev_b32_e32 v26, 16, v27
	s_waitcnt vmcnt(1)
	v_lshlrev_b32_e32 v106, 16, v52
	s_waitcnt vmcnt(0)
	v_lshlrev_b32_e32 v108, 16, v54
	v_add_f32_e32 v24, v24, v49
	v_add_f32_e32 v25, v25, v51
	v_add_f32_e32 v23, v23, v79
	v_add_f32_e32 v22, v22, v28
	v_and_b32_e32 v27, 0xffff0000, v27
	v_and_b32_e32 v107, 0xffff0000, v52
	v_and_b32_e32 v109, 0xffff0000, v54
	v_add_f32_e32 v23, v23, v26
	v_add_f32_e32 v24, v24, v106
	v_add_f32_e32 v25, v25, v108
	v_add_f32_e32 v22, v22, v29
	v_lshlrev_b32_e32 v52, 16, v53
	v_lshlrev_b32_e32 v110, 16, v55
	v_add_f32_e32 v23, v23, v27
	v_add_f32_e32 v24, v24, v107
	v_add_f32_e32 v25, v25, v109
	v_add_f32_e32 v22, v22, v74
	v_and_b32_e32 v53, 0xffff0000, v53
	v_and_b32_e32 v111, 0xffff0000, v55
	v_add_f32_e32 v24, v24, v52
	v_add_f32_e32 v25, v25, v110
	v_add_f32_e32 v23, v23, v80
	v_add_f32_e32 v22, v22, v75
	v_lshlrev_b32_e32 v112, 16, v42
	v_lshlrev_b32_e32 v114, 16, v46
	v_add_f32_e32 v24, v24, v53
	v_add_f32_e32 v25, v25, v111
	v_add_f32_e32 v23, v23, v81
	v_add_f32_e32 v22, v22, v56
	v_and_b32_e32 v113, 0xffff0000, v42
	v_and_b32_e32 v115, 0xffff0000, v46
	v_add_f32_e32 v23, v23, v64
	v_add_f32_e32 v24, v24, v112
	v_add_f32_e32 v25, v25, v114
	v_add_f32_e32 v22, v22, v57
	v_lshlrev_b32_e32 v94, 16, v43
	v_lshlrev_b32_e32 v100, 16, v47
	v_add_f32_e32 v23, v23, v65
	v_add_f32_e32 v24, v24, v113
	v_add_f32_e32 v25, v25, v115
	ds_bpermute_b32 v40, v86, v22
	v_and_b32_e32 v95, 0xffff0000, v43
	v_and_b32_e32 v101, 0xffff0000, v47
	ds_bpermute_b32 v41, v86, v23
	v_add_f32_e32 v24, v24, v94
	v_add_f32_e32 v25, v25, v100
	v_add_f32_e32 v24, v24, v95
	v_add_f32_e32 v25, v25, v101
	ds_bpermute_b32 v42, v86, v24
	ds_bpermute_b32 v43, v86, v25
	s_waitcnt lgkmcnt(3)
	v_add_f32_e32 v22, v22, v40
	s_waitcnt lgkmcnt(2)
	v_add_f32_e32 v23, v23, v41
	ds_bpermute_b32 v40, v87, v22
	ds_bpermute_b32 v41, v87, v23
	s_waitcnt lgkmcnt(3)
	v_add_f32_e32 v24, v24, v42
	s_waitcnt lgkmcnt(2)
	v_add_f32_e32 v25, v25, v43
	ds_bpermute_b32 v42, v87, v24
	ds_bpermute_b32 v43, v87, v25
	s_waitcnt lgkmcnt(3)
	v_add_f32_e32 v22, v22, v40
	s_waitcnt lgkmcnt(2)
	v_add_f32_e32 v23, v23, v41
	ds_bpermute_b32 v40, v88, v22
	ds_bpermute_b32 v41, v88, v23
	s_waitcnt lgkmcnt(3)
	v_add_f32_e32 v24, v24, v42
	s_waitcnt lgkmcnt(2)
	v_add_f32_e32 v25, v25, v43
	ds_bpermute_b32 v42, v88, v24
	ds_bpermute_b32 v43, v88, v25
	s_waitcnt lgkmcnt(3)
	v_add_f32_e32 v22, v22, v40
	s_waitcnt lgkmcnt(2)
	v_add_f32_e32 v23, v23, v41
	ds_bpermute_b32 v40, v89, v22
	ds_bpermute_b32 v41, v89, v23
	s_waitcnt lgkmcnt(3)
	v_add_f32_e32 v24, v24, v42
	s_waitcnt lgkmcnt(2)
	v_add_f32_e32 v25, v25, v43
	ds_bpermute_b32 v42, v89, v24
	ds_bpermute_b32 v43, v89, v25
	s_waitcnt lgkmcnt(3)
	v_add_f32_e32 v22, v22, v40
	s_waitcnt lgkmcnt(2)
	v_add_f32_e32 v23, v23, v41
	ds_bpermute_b32 v40, v90, v22
	ds_bpermute_b32 v41, v90, v23
	s_waitcnt lgkmcnt(3)
	v_add_f32_e32 v24, v24, v42
	s_waitcnt lgkmcnt(2)
	v_add_f32_e32 v25, v25, v43
	ds_bpermute_b32 v42, v90, v24
	ds_bpermute_b32 v43, v90, v25
	s_waitcnt lgkmcnt(3)
	v_add_f32_e32 v22, v22, v40
	s_waitcnt lgkmcnt(2)
	v_add_f32_e32 v23, v23, v41
	ds_bpermute_b32 v40, v91, v22
	ds_bpermute_b32 v41, v91, v23
	s_waitcnt lgkmcnt(3)
	v_add_f32_e32 v47, v24, v42
	s_waitcnt lgkmcnt(2)
	v_add_f32_e32 v116, v25, v43
	ds_bpermute_b32 v117, v91, v47
	ds_bpermute_b32 v118, v91, v116
	s_waitcnt lgkmcnt(3)
	v_add_f32_e32 v22, v22, v40
	s_waitcnt lgkmcnt(2)
	v_add_f32_e32 v23, v23, v41
	v_mul_f32_e32 v24, 0x3a800000, v22
	v_mul_f32_e32 v46, 0x3a800000, v23
	v_pk_add_f32 v[70:71], v[38:39], v[24:25] op_sel_hi:[1,0] neg_lo:[0,1] neg_hi:[0,1]
	v_pk_add_f32 v[72:73], v[36:37], v[24:25] op_sel_hi:[1,0] neg_lo:[0,1] neg_hi:[0,1]
	v_pk_add_f32 v[58:59], v[58:59], v[24:25] op_sel_hi:[1,0] neg_lo:[0,1] neg_hi:[0,1]
	v_pk_add_f32 v[60:61], v[32:33], v[24:25] op_sel_hi:[1,0] neg_lo:[0,1] neg_hi:[0,1]
	v_pk_add_f32 v[42:43], v[68:69], v[24:25] op_sel_hi:[1,0] neg_lo:[0,1] neg_hi:[0,1]
	v_pk_add_f32 v[44:45], v[28:29], v[24:25] op_sel_hi:[1,0] neg_lo:[0,1] neg_hi:[0,1]
	v_pk_add_f32 v[22:23], v[74:75], v[24:25] op_sel_hi:[1,0] neg_lo:[0,1] neg_hi:[0,1]
	v_pk_add_f32 v[24:25], v[56:57], v[24:25] op_sel_hi:[1,0] neg_lo:[0,1] neg_hi:[0,1]
	v_pk_add_f32 v[74:75], v[62:63], v[46:47] op_sel_hi:[1,0] neg_lo:[0,1] neg_hi:[0,1]
	v_pk_add_f32 v[76:77], v[34:35], v[46:47] op_sel_hi:[1,0] neg_lo:[0,1] neg_hi:[0,1]
	v_pk_add_f32 v[56:57], v[30:31], v[46:47] op_sel_hi:[1,0] neg_lo:[0,1] neg_hi:[0,1]
	s_waitcnt lgkmcnt(1)
	v_add_f32_e32 v34, v47, v117
	s_waitcnt lgkmcnt(0)
	v_add_f32_e32 v35, v116, v118
	v_pk_mul_f32 v[30:31], v[70:71], v[70:71]
	v_pk_mul_f32 v[116:117], v[72:73], v[72:73]
	v_pk_mul_f32 v[32:33], v[74:75], v[74:75]
	v_mul_f32_e32 v34, 0x3a800000, v34
	v_mul_f32_e32 v36, 0x3a800000, v35
	v_add_f32_e32 v144, v30, v31
	v_pk_add_f32 v[38:39], v[78:79], v[46:47] op_sel_hi:[1,0] neg_lo:[0,1] neg_hi:[0,1]
	v_pk_mul_f32 v[130:131], v[76:77], v[76:77]
	v_add_f32_e32 v145, v32, v33
	v_pk_add_f32 v[78:79], v[82:83], v[34:35] op_sel_hi:[1,0] neg_lo:[0,1] neg_hi:[0,1]
	v_pk_add_f32 v[82:83], v[96:97], v[36:37] op_sel_hi:[1,0] neg_lo:[0,1] neg_hi:[0,1]
	v_add_f32_e32 v116, v144, v116
	v_pk_add_f32 v[54:55], v[66:67], v[46:47] op_sel_hi:[1,0] neg_lo:[0,1] neg_hi:[0,1]
	v_pk_add_f32 v[40:41], v[26:27], v[46:47] op_sel_hi:[1,0] neg_lo:[0,1] neg_hi:[0,1]
	v_pk_add_f32 v[26:27], v[80:81], v[46:47] op_sel_hi:[1,0] neg_lo:[0,1] neg_hi:[0,1]
	v_pk_mul_f32 v[118:119], v[58:59], v[58:59]
	v_pk_add_f32 v[80:81], v[84:85], v[34:35] op_sel_hi:[1,0] neg_lo:[0,1] neg_hi:[0,1]
	v_pk_add_f32 v[32:33], v[94:95], v[34:35] op_sel_hi:[1,0] neg_lo:[0,1] neg_hi:[0,1]
	v_pk_add_f32 v[66:67], v[50:51], v[36:37] op_sel_hi:[1,0] neg_lo:[0,1] neg_hi:[0,1]
	v_pk_add_f32 v[50:51], v[110:111], v[36:37] op_sel_hi:[1,0] neg_lo:[0,1] neg_hi:[0,1]
	v_add_f32_e32 v130, v145, v130
	v_pk_mul_f32 v[94:95], v[78:79], v[78:79]
	v_pk_mul_f32 v[110:111], v[82:83], v[82:83]
	v_add_f32_e32 v116, v116, v117
	v_pk_mul_f32 v[132:133], v[54:55], v[54:55]
	v_pk_add_f32 v[84:85], v[98:99], v[36:37] op_sel_hi:[1,0] neg_lo:[0,1] neg_hi:[0,1]
	v_pk_mul_f32 v[96:97], v[80:81], v[80:81]
	v_add_f32_e32 v117, v130, v131
	v_add_f32_e32 v94, v94, v95
	v_add_f32_e32 v95, v110, v111
	v_add_f32_e32 v110, v116, v118
	v_pk_add_f32 v[28:29], v[64:65], v[46:47] op_sel_hi:[1,0] neg_lo:[0,1] neg_hi:[0,1]
	v_pk_mul_f32 v[120:121], v[60:61], v[60:61]
	v_pk_add_f32 v[64:65], v[102:103], v[34:35] op_sel_hi:[1,0] neg_lo:[0,1] neg_hi:[0,1]
	v_pk_add_f32 v[30:31], v[112:113], v[34:35] op_sel_hi:[1,0] neg_lo:[0,1] neg_hi:[0,1]
	v_pk_mul_f32 v[112:113], v[84:85], v[84:85]
	v_add_f32_e32 v111, v117, v132
	v_add_f32_e32 v94, v94, v96
	v_add_f32_e32 v96, v110, v119
	v_pk_mul_f32 v[134:135], v[56:57], v[56:57]
	v_pk_add_f32 v[62:63], v[104:105], v[36:37] op_sel_hi:[1,0] neg_lo:[0,1] neg_hi:[0,1]
	v_pk_mul_f32 v[98:99], v[64:65], v[64:65]
	v_add_f32_e32 v95, v95, v112
	v_add_f32_e32 v110, v111, v133
	v_add_f32_e32 v94, v94, v97
	v_add_f32_e32 v96, v96, v120
	v_pk_mul_f32 v[122:123], v[42:43], v[42:43]
	v_pk_add_f32 v[68:69], v[48:49], v[34:35] op_sel_hi:[1,0] neg_lo:[0,1] neg_hi:[0,1]
	v_pk_add_f32 v[48:49], v[106:107], v[34:35] op_sel_hi:[1,0] neg_lo:[0,1] neg_hi:[0,1]
	v_pk_add_f32 v[52:53], v[52:53], v[34:35] op_sel_hi:[1,0] neg_lo:[0,1] neg_hi:[0,1]
	v_pk_add_f32 v[34:35], v[114:115], v[36:37] op_sel_hi:[1,0] neg_lo:[0,1] neg_hi:[0,1]
	v_pk_mul_f32 v[114:115], v[62:63], v[62:63]
	v_add_f32_e32 v95, v95, v113
	v_add_f32_e32 v97, v110, v134
	v_add_f32_e32 v94, v94, v98
	v_add_f32_e32 v96, v96, v121
	v_pk_mul_f32 v[136:137], v[38:39], v[38:39]
	v_pk_add_f32 v[46:47], v[108:109], v[36:37] op_sel_hi:[1,0] neg_lo:[0,1] neg_hi:[0,1]
	v_pk_add_f32 v[36:37], v[100:101], v[36:37] op_sel_hi:[1,0] neg_lo:[0,1] neg_hi:[0,1]
	v_pk_mul_f32 v[100:101], v[68:69], v[68:69]
	v_add_f32_e32 v95, v95, v114
	v_add_f32_e32 v97, v97, v135
	v_add_f32_e32 v94, v94, v99
	v_add_f32_e32 v96, v96, v122
	v_pk_mul_f32 v[124:125], v[44:45], v[44:45]
	v_pk_mul_f32 v[144:145], v[66:67], v[66:67]
	v_add_f32_e32 v95, v95, v115
	v_add_f32_e32 v97, v97, v136
	v_add_f32_e32 v94, v94, v100
	v_add_f32_e32 v96, v96, v123
	v_pk_mul_f32 v[138:139], v[40:41], v[40:41]
	v_pk_mul_f32 v[102:103], v[48:49], v[48:49]
	v_add_f32_e32 v95, v95, v144
	v_add_f32_e32 v97, v97, v137
	v_add_f32_e32 v94, v94, v101
	v_add_f32_e32 v96, v96, v124
	v_pk_mul_f32 v[126:127], v[22:23], v[22:23]
	v_pk_mul_f32 v[146:147], v[46:47], v[46:47]
	v_add_f32_e32 v95, v95, v145
	v_add_f32_e32 v97, v97, v138
	v_add_f32_e32 v94, v94, v102
	v_add_f32_e32 v96, v96, v125
	v_pk_mul_f32 v[140:141], v[26:27], v[26:27]
	v_pk_mul_f32 v[104:105], v[52:53], v[52:53]
	v_add_f32_e32 v95, v95, v146
	v_add_f32_e32 v97, v97, v139
	v_add_f32_e32 v94, v94, v103
	v_add_f32_e32 v96, v96, v126
	v_pk_mul_f32 v[128:129], v[24:25], v[24:25]
	v_pk_mul_f32 v[148:149], v[50:51], v[50:51]
	v_add_f32_e32 v95, v95, v147
	v_add_f32_e32 v97, v97, v140
	v_add_f32_e32 v94, v94, v104
	v_add_f32_e32 v96, v96, v127
	v_pk_mul_f32 v[142:143], v[28:29], v[28:29]
	v_pk_mul_f32 v[106:107], v[30:31], v[30:31]
	v_add_f32_e32 v95, v95, v148
	v_add_f32_e32 v97, v97, v141
	v_add_f32_e32 v94, v94, v105
	v_add_f32_e32 v96, v96, v128
	v_pk_mul_f32 v[150:151], v[34:35], v[34:35]
	v_add_f32_e32 v95, v95, v149
	v_add_f32_e32 v97, v97, v142
	v_add_f32_e32 v94, v94, v106
	v_add_f32_e32 v96, v96, v129
	v_pk_mul_f32 v[108:109], v[32:33], v[32:33]
	v_add_f32_e32 v95, v95, v150
	v_add_f32_e32 v97, v97, v143
	v_add_f32_e32 v94, v94, v107
	ds_bpermute_b32 v98, v86, v96
	v_pk_mul_f32 v[152:153], v[36:37], v[36:37]
	v_add_f32_e32 v95, v95, v151
	ds_bpermute_b32 v99, v86, v97
	v_add_f32_e32 v94, v94, v108
	v_add_f32_e32 v95, v95, v152
	v_add_f32_e32 v94, v94, v109
	v_add_f32_e32 v95, v95, v153
	ds_bpermute_b32 v100, v86, v94
	ds_bpermute_b32 v101, v86, v95
	s_waitcnt lgkmcnt(3)
	v_add_f32_e32 v96, v96, v98
	s_waitcnt lgkmcnt(2)
	v_add_f32_e32 v97, v97, v99
	ds_bpermute_b32 v98, v87, v96
	ds_bpermute_b32 v99, v87, v97
	s_waitcnt lgkmcnt(3)
	v_add_f32_e32 v94, v94, v100
	s_waitcnt lgkmcnt(2)
	v_add_f32_e32 v95, v95, v101
	ds_bpermute_b32 v100, v87, v94
	ds_bpermute_b32 v101, v87, v95
	s_waitcnt lgkmcnt(3)
	v_add_f32_e32 v96, v96, v98
	s_waitcnt lgkmcnt(2)
	v_add_f32_e32 v97, v97, v99
	ds_bpermute_b32 v98, v88, v96
	ds_bpermute_b32 v99, v88, v97
	s_waitcnt lgkmcnt(3)
	v_add_f32_e32 v94, v94, v100
	s_waitcnt lgkmcnt(2)
	v_add_f32_e32 v95, v95, v101
	ds_bpermute_b32 v100, v88, v94
	ds_bpermute_b32 v101, v88, v95
	s_waitcnt lgkmcnt(3)
	v_add_f32_e32 v96, v96, v98
	s_waitcnt lgkmcnt(2)
	v_add_f32_e32 v97, v97, v99
	ds_bpermute_b32 v98, v89, v96
	ds_bpermute_b32 v99, v89, v97
	s_waitcnt lgkmcnt(3)
	v_add_f32_e32 v94, v94, v100
	s_waitcnt lgkmcnt(2)
	v_add_f32_e32 v95, v95, v101
	ds_bpermute_b32 v100, v89, v94
	ds_bpermute_b32 v101, v89, v95
	s_waitcnt lgkmcnt(3)
	v_add_f32_e32 v96, v96, v98
	s_waitcnt lgkmcnt(2)
	v_add_f32_e32 v97, v97, v99
	ds_bpermute_b32 v98, v90, v96
	ds_bpermute_b32 v99, v90, v97
	s_waitcnt lgkmcnt(3)
	v_add_f32_e32 v94, v94, v100
	s_waitcnt lgkmcnt(2)
	v_add_f32_e32 v95, v95, v101
	ds_bpermute_b32 v100, v90, v94
	ds_bpermute_b32 v101, v90, v95
	s_waitcnt lgkmcnt(3)
	v_add_f32_e32 v96, v96, v98
	s_waitcnt lgkmcnt(2)
	v_add_f32_e32 v97, v97, v99
	ds_bpermute_b32 v98, v91, v96
	ds_bpermute_b32 v99, v91, v97
	s_waitcnt lgkmcnt(3)
	v_add_f32_e32 v94, v94, v100
	s_waitcnt lgkmcnt(2)
	v_add_f32_e32 v95, v95, v101
	ds_bpermute_b32 v100, v91, v94
	ds_bpermute_b32 v101, v91, v95
	s_waitcnt lgkmcnt(3)
	v_add_f32_e32 v96, v96, v98
	s_waitcnt lgkmcnt(2)
	v_add_f32_e32 v97, v97, v99
	v_fmamk_f32 v96, v96, 0x3a800000, v9
	v_fmamk_f32 v97, v97, 0x3a800000, v9
	v_mul_f32_e32 v98, 0x4f800000, v96
	v_cmp_gt_f32_e64 s[2:3], s15, v96
	v_mul_f32_e32 v99, 0x4f800000, v97
	v_cmp_gt_f32_e32 vcc, s15, v97
	s_waitcnt lgkmcnt(1)
	v_add_f32_e32 v94, v94, v100
	v_cndmask_b32_e64 v96, v96, v98, s[2:3]
	s_waitcnt lgkmcnt(0)
	v_add_f32_e32 v95, v95, v101
	v_cndmask_b32_e32 v97, v97, v99, vcc
	v_fmamk_f32 v94, v94, 0x3a800000, v9
	v_sqrt_f32_e32 v98, v96
	v_fmamk_f32 v95, v95, 0x3a800000, v9
	v_sqrt_f32_e32 v99, v97
	v_mul_f32_e32 v100, 0x4f800000, v94
	v_cmp_gt_f32_e64 s[6:7], s15, v94
	v_mul_f32_e32 v101, 0x4f800000, v95
	v_cmp_gt_f32_e64 s[4:5], s15, v95
	v_cndmask_b32_e64 v94, v94, v100, s[6:7]
	v_sqrt_f32_e32 v100, v94
	v_cndmask_b32_e64 v95, v95, v101, s[4:5]
	v_sqrt_f32_e32 v101, v95
	v_add_u32_e32 v102, -1, v98
	v_add_u32_e32 v103, 1, v98
	v_add_u32_e32 v104, -1, v99
	v_fma_f32 v106, -v102, v98, v96
	v_add_u32_e32 v105, 1, v99
	v_fma_f32 v107, -v103, v98, v96
	v_fma_f32 v108, -v104, v99, v97
	v_cmp_ge_f32_e64 s[8:9], 0, v106
	v_fma_f32 v109, -v105, v99, v97
	v_cmp_lt_f32_e64 s[10:11], 0, v107
	v_cndmask_b32_e64 v98, v98, v102, s[8:9]
	v_cmp_ge_f32_e64 s[8:9], 0, v108
	v_add_u32_e32 v102, -1, v100
	v_add_u32_e32 v106, -1, v101
	v_cndmask_b32_e64 v99, v99, v104, s[8:9]
	v_cmp_lt_f32_e64 s[8:9], 0, v109
	v_add_u32_e32 v104, 1, v100
	v_cndmask_b32_e64 v98, v98, v103, s[10:11]
	v_fma_f32 v103, -v102, v100, v94
	v_add_u32_e32 v108, 1, v101
	v_cndmask_b32_e64 v99, v99, v105, s[8:9]
	v_fma_f32 v105, -v104, v100, v94
	v_fma_f32 v107, -v106, v101, v95
	v_cmp_ge_f32_e64 s[8:9], 0, v103
	v_fma_f32 v109, -v108, v101, v95
	v_mul_f32_e32 v110, 0x37800000, v98
	v_mul_f32_e32 v111, 0x37800000, v99
	v_cndmask_b32_e64 v100, v100, v102, s[8:9]
	v_cmp_lt_f32_e64 s[8:9], 0, v105
	v_cmp_ge_f32_e64 s[10:11], 0, v107
	v_cndmask_b32_e64 v98, v98, v110, s[2:3]
	v_cndmask_b32_e32 v99, v99, v111, vcc
	v_cndmask_b32_e64 v101, v101, v106, s[10:11]
	v_cmp_lt_f32_e64 s[10:11], 0, v109
	v_cmp_class_f32_e32 vcc, v97, v93
	v_cndmask_b32_e64 v100, v100, v104, s[8:9]
	v_cmp_class_f32_e64 s[2:3], v96, v93
	v_cndmask_b32_e64 v101, v101, v108, s[10:11]
	v_cndmask_b32_e32 v97, v99, v97, vcc
	v_cndmask_b32_e64 v96, v98, v96, s[2:3]
	v_mul_f32_e32 v98, 0x37800000, v100
	v_mul_f32_e32 v99, 0x37800000, v101
	v_div_scale_f32 v102, s[2:3], v96, v96, 1.0
	v_div_scale_f32 v104, s[2:3], v97, v97, 1.0
	v_cndmask_b32_e64 v98, v100, v98, s[6:7]
	v_cmp_class_f32_e64 s[6:7], v94, v93
	v_cndmask_b32_e64 v99, v101, v99, s[4:5]
	v_cmp_class_f32_e64 s[4:5], v95, v93
	v_rcp_f32_e32 v100, v102
	v_rcp_f32_e32 v101, v104
	v_cndmask_b32_e64 v98, v98, v94, s[6:7]
	v_cndmask_b32_e64 v95, v99, v95, s[4:5]
	v_div_scale_f32 v99, s[4:5], v98, v98, 1.0
	v_div_scale_f32 v107, s[6:7], v95, v95, 1.0
	v_rcp_f32_e32 v109, v99
	v_rcp_f32_e32 v110, v107
	v_fma_f32 v94, -v102, v100, 1.0
	v_fma_f32 v111, -v104, v101, 1.0
	v_div_scale_f32 v103, vcc, 1.0, v96, 1.0
	v_div_scale_f32 v105, s[2:3], 1.0, v97, 1.0
	v_fmac_f32_e32 v100, v94, v100
	v_fmac_f32_e32 v101, v111, v101
	v_mul_f32_e32 v94, v103, v100
	v_mul_f32_e32 v111, v105, v101
	v_fma_f32 v112, -v99, v109, 1.0
	v_div_scale_f32 v106, s[4:5], 1.0, v98, 1.0
	v_fma_f32 v113, -v107, v110, 1.0
	v_fma_f32 v114, -v102, v94, v103
	v_fma_f32 v115, -v104, v111, v105
	v_fmac_f32_e32 v109, v112, v109
	v_div_scale_f32 v108, s[6:7], 1.0, v95, 1.0
	v_fmac_f32_e32 v110, v113, v110
	v_fmac_f32_e32 v94, v114, v100
	v_fmac_f32_e32 v111, v115, v101
	v_mul_f32_e32 v112, v106, v109
	v_mul_f32_e32 v113, v108, v110
	v_fma_f32 v102, -v102, v94, v103
	v_fma_f32 v103, -v104, v111, v105
	v_fma_f32 v104, -v99, v112, v106
	v_fma_f32 v105, -v107, v113, v108
	v_div_fmas_f32 v94, v102, v100, v94
	v_fmac_f32_e32 v112, v104, v109
	s_mov_b64 vcc, s[2:3]
	v_fmac_f32_e32 v113, v105, v110
	v_div_fixup_f32 v94, v94, v96, 1.0
	v_div_fmas_f32 v96, v103, v101, v111
	v_fma_f32 v99, -v99, v112, v106
	s_mov_b64 vcc, s[4:5]
	v_fma_f32 v100, -v107, v113, v108
	v_pk_mul_f32 v[70:71], v[70:71], v[94:95] op_sel_hi:[1,0]
	v_pk_mul_f32 v[72:73], v[72:73], v[94:95] op_sel_hi:[1,0]
	v_div_fixup_f32 v96, v96, v97, 1.0
	v_div_fmas_f32 v97, v99, v109, v112
	s_mov_b64 vcc, s[6:7]
	v_pk_fma_f32 v[72:73], v[2:3], v[72:73], v[6:7]
	v_pk_fma_f32 v[70:71], v[0:1], v[70:71], v[4:5]
	v_pk_mul_f32 v[74:75], v[74:75], v[96:97] op_sel_hi:[1,0]
	v_pk_mul_f32 v[76:77], v[76:77], v[96:97] op_sel_hi:[1,0]
	v_div_fixup_f32 v98, v97, v98, 1.0
	v_div_fmas_f32 v97, v100, v110, v113
	global_store_dwordx4 v[16:17], v[70:73], off nt
	v_pk_mul_f32 v[60:61], v[60:61], v[94:95] op_sel_hi:[1,0]
	v_pk_mul_f32 v[58:59], v[58:59], v[94:95] op_sel_hi:[1,0]
	v_pk_fma_f32 v[72:73], v[2:3], v[76:77], v[6:7]
	v_pk_fma_f32 v[70:71], v[0:1], v[74:75], v[4:5]
	v_pk_mul_f32 v[74:75], v[78:79], v[98:99] op_sel_hi:[1,0]
	v_pk_mul_f32 v[76:77], v[80:81], v[98:99] op_sel_hi:[1,0]
	v_div_fixup_f32 v78, v97, v95, 1.0
	global_store_dwordx4 v[18:19], v[70:73], off offset:-4096 nt
	v_pk_mul_f32 v[68:69], v[68:69], v[98:99] op_sel_hi:[1,0]
	v_pk_mul_f32 v[64:65], v[64:65], v[98:99] op_sel_hi:[1,0]
	v_pk_fma_f32 v[72:73], v[2:3], v[76:77], v[6:7]
	v_pk_fma_f32 v[70:71], v[0:1], v[74:75], v[4:5]
	v_pk_mul_f32 v[74:75], v[82:83], v[78:79] op_sel_hi:[1,0]
	v_pk_mul_f32 v[76:77], v[84:85], v[78:79] op_sel_hi:[1,0]
	v_pk_fma_f32 v[0:1], v[0:1], v[74:75], v[4:5]
	v_pk_fma_f32 v[2:3], v[2:3], v[76:77], v[6:7]
	global_store_dwordx4 v[18:19], v[70:73], off nt
	global_store_dwordx4 v[20:21], v[0:3], off nt
	v_mov_b32_e32 v4, v164
	v_mov_b32_e32 v5, v165
	v_mov_b32_e32 v6, v166
	v_mov_b32_e32 v7, v167
	v_mov_b32_e32 v0, v160
	v_mov_b32_e32 v1, v161
	v_mov_b32_e32 v2, v162
	v_mov_b32_e32 v3, v163
	v_add_co_u32_e32 v70, vcc, s13, v16
	v_pk_mul_f32 v[72:73], v[56:57], v[96:97] op_sel_hi:[1,0]
	v_pk_mul_f32 v[74:75], v[54:55], v[96:97] op_sel_hi:[1,0]
	v_pk_mul_f32 v[66:67], v[66:67], v[78:79] op_sel_hi:[1,0]
	v_pk_mul_f32 v[76:77], v[62:63], v[78:79] op_sel_hi:[1,0]
	v_addc_co_u32_e32 v71, vcc, 0, v17, vcc
	v_pk_mul_f32 v[44:45], v[44:45], v[94:95] op_sel_hi:[1,0]
	v_pk_mul_f32 v[42:43], v[42:43], v[94:95] op_sel_hi:[1,0]
	v_pk_mul_f32 v[52:53], v[52:53], v[98:99] op_sel_hi:[1,0]
	v_pk_mul_f32 v[48:49], v[48:49], v[98:99] op_sel_hi:[1,0]
	v_pk_mul_f32 v[50:51], v[50:51], v[78:79] op_sel_hi:[1,0]
	v_pk_mul_f32 v[24:25], v[24:25], v[94:95] op_sel_hi:[1,0]
	v_pk_mul_f32 v[22:23], v[22:23], v[94:95] op_sel_hi:[1,0]
	v_pk_mul_f32 v[28:29], v[28:29], v[96:97] op_sel_hi:[1,0]
	v_pk_mul_f32 v[26:27], v[26:27], v[96:97] op_sel_hi:[1,0]
	v_pk_mul_f32 v[32:33], v[32:33], v[98:99] op_sel_hi:[1,0]
	v_pk_mul_f32 v[30:31], v[30:31], v[98:99] op_sel_hi:[1,0]
	v_pk_mul_f32 v[36:37], v[36:37], v[78:79] op_sel_hi:[1,0]
	v_pk_mul_f32 v[34:35], v[34:35], v[78:79] op_sel_hi:[1,0]
	v_pk_fma_f32 v[54:55], v[0:1], v[58:59], v[4:5]
	v_pk_fma_f32 v[56:57], v[2:3], v[60:61], v[6:7]
	v_pk_fma_f32 v[58:59], v[0:1], v[74:75], v[4:5]
	v_pk_fma_f32 v[60:61], v[2:3], v[72:73], v[6:7]
	v_pk_fma_f32 v[62:63], v[0:1], v[64:65], v[4:5]
	v_pk_fma_f32 v[64:65], v[2:3], v[68:69], v[6:7]
	v_pk_fma_f32 v[0:1], v[0:1], v[76:77], v[4:5]
	v_pk_fma_f32 v[2:3], v[2:3], v[66:67], v[6:7]
	global_store_dwordx4 v[16:17], v[54:57], off offset:1024 nt
	global_store_dwordx4 v[70:71], v[58:61], off offset:1024 nt
	global_store_dwordx4 v[18:19], v[62:65], off offset:1024 nt
	global_store_dwordx4 v[20:21], v[0:3], off offset:1024 nt
	v_mov_b32_e32 v4, v172
	v_mov_b32_e32 v5, v173
	v_mov_b32_e32 v6, v174
	v_mov_b32_e32 v7, v175
	v_mov_b32_e32 v0, v168
	v_mov_b32_e32 v1, v169
	v_mov_b32_e32 v2, v170
	v_mov_b32_e32 v3, v171
	v_pk_mul_f32 v[54:55], v[40:41], v[96:97] op_sel_hi:[1,0]
	v_pk_mul_f32 v[56:57], v[38:39], v[96:97] op_sel_hi:[1,0]
	v_pk_mul_f32 v[58:59], v[46:47], v[78:79] op_sel_hi:[1,0]
	v_pk_fma_f32 v[38:39], v[0:1], v[42:43], v[4:5]
	v_pk_fma_f32 v[40:41], v[2:3], v[44:45], v[6:7]
	v_pk_fma_f32 v[42:43], v[0:1], v[56:57], v[4:5]
	v_pk_fma_f32 v[44:45], v[2:3], v[54:55], v[6:7]
	v_pk_fma_f32 v[46:47], v[0:1], v[48:49], v[4:5]
	v_pk_fma_f32 v[48:49], v[2:3], v[52:53], v[6:7]
	v_pk_fma_f32 v[0:1], v[0:1], v[58:59], v[4:5]
	v_pk_fma_f32 v[2:3], v[2:3], v[50:51], v[6:7]
	global_store_dwordx4 v[16:17], v[38:41], off offset:2048 nt
	global_store_dwordx4 v[70:71], v[42:45], off offset:2048 nt
	global_store_dwordx4 v[18:19], v[46:49], off offset:2048 nt
	global_store_dwordx4 v[20:21], v[0:3], off offset:2048 nt
	v_mov_b32_e32 v4, v180
	v_mov_b32_e32 v5, v181
	v_mov_b32_e32 v6, v182
	v_mov_b32_e32 v7, v183
	v_mov_b32_e32 v0, v176
	v_mov_b32_e32 v1, v177
	v_mov_b32_e32 v2, v178
	v_mov_b32_e32 v3, v179
	v_pk_fma_f32 v[22:23], v[0:1], v[22:23], v[4:5]
	v_pk_fma_f32 v[24:25], v[2:3], v[24:25], v[6:7]
	v_pk_fma_f32 v[26:27], v[0:1], v[26:27], v[4:5]
	v_pk_fma_f32 v[28:29], v[2:3], v[28:29], v[6:7]
	v_pk_fma_f32 v[30:31], v[0:1], v[30:31], v[4:5]
	v_pk_fma_f32 v[32:33], v[2:3], v[32:33], v[6:7]
	v_pk_fma_f32 v[0:1], v[0:1], v[34:35], v[4:5]
	v_pk_fma_f32 v[2:3], v[2:3], v[36:37], v[6:7]
	global_store_dwordx4 v[16:17], v[22:25], off offset:3072 nt
	global_store_dwordx4 v[70:71], v[26:29], off offset:3072 nt
	global_store_dwordx4 v[18:19], v[30:33], off offset:3072 nt
	global_store_dwordx4 v[20:21], v[0:3], off offset:3072 nt
	v_lshl_add_u64 v[16:17], v[16:17], 0, s[18:19]
	s_cbranch_scc0 .LBB0_1666

	.amdhsa_kernel _Z9hymba_fwd4Args
		.amdhsa_group_segment_fixed_size 0
		.amdhsa_private_segment_fixed_size 0
		.amdhsa_kernarg_size 504
		.amdhsa_user_sgpr_count 2
		.amdhsa_user_sgpr_dispatch_ptr 0
		.amdhsa_user_sgpr_queue_ptr 0
		.amdhsa_user_sgpr_kernarg_segment_ptr 1
		.amdhsa_user_sgpr_dispatch_id 0
		.amdhsa_user_sgpr_kernarg_preload_length 0
		.amdhsa_user_sgpr_kernarg_preload_offset 0
		.amdhsa_user_sgpr_private_segment_size 0
		.amdhsa_uses_dynamic_stack 0
		.amdhsa_enable_private_segment 0
		.amdhsa_system_sgpr_workgroup_id_x 1
		.amdhsa_system_sgpr_workgroup_id_y 0
		.amdhsa_system_sgpr_workgroup_id_z 0
		.amdhsa_system_sgpr_workgroup_info 0
		.amdhsa_system_vgpr_workitem_id 0
		.amdhsa_next_free_vgpr 256
		.amdhsa_next_free_sgpr 102
		.amdhsa_accum_offset 256
		.amdhsa_reserve_vcc 1
		.amdhsa_float_round_mode_32 0
		.amdhsa_float_round_mode_16_64 0
		.amdhsa_float_denorm_mode_32 3
		.amdhsa_float_denorm_mode_16_64 3
		.amdhsa_dx10_clamp 1
		.amdhsa_ieee_mode 1
		.amdhsa_fp16_overflow 0
		.amdhsa_tg_split 0
		.amdhsa_exception_fp_ieee_invalid_op 0
		.amdhsa_exception_fp_denorm_src 0
		.amdhsa_exception_fp_ieee_div_zero 0
		.amdhsa_exception_fp_ieee_overflow 0
		.amdhsa_exception_fp_ieee_underflow 0
		.amdhsa_exception_fp_ieee_inexact 0
		.amdhsa_exception_int_div_zero 0
	.end_amdhsa_kernel

amdhsa.kernels:
  - .agpr_count:     0
    .args:
      - .offset:         0
        .size:           248
        .value_kind:     by_value
      - .offset:         248
        .size:           4
        .value_kind:     hidden_block_count_x
      - .offset:         252
        .size:           4
        .value_kind:     hidden_block_count_y
      - .offset:         256
        .size:           4
        .value_kind:     hidden_block_count_z
      - .offset:         260
        .size:           2
        .value_kind:     hidden_group_size_x
      - .offset:         262
        .size:           2
        .value_kind:     hidden_group_size_y
      - .offset:         264
        .size:           2
        .value_kind:     hidden_group_size_z
      - .offset:         266
        .size:           2
        .value_kind:     hidden_remainder_x
      - .offset:         268
        .size:           2
        .value_kind:     hidden_remainder_y
      - .offset:         270
        .size:           2
        .value_kind:     hidden_remainder_z
      - .offset:         288
        .size:           8
        .value_kind:     hidden_global_offset_x
      - .offset:         296
        .size:           8
        .value_kind:     hidden_global_offset_y
      - .offset:         304
        .size:           8
        .value_kind:     hidden_global_offset_z
      - .offset:         312
        .size:           2
        .value_kind:     hidden_grid_dims
      - .offset:         368
        .size:           4
        .value_kind:     hidden_dynamic_lds_size
    .group_segment_fixed_size: 0
    .kernarg_segment_align: 8
    .kernarg_segment_size: 504
    .language:       OpenCL C
    .language_version:
      - 2
      - 0
    .max_flat_workgroup_size: 512
    .name:           _Z9hymba_fwd4Args
    .private_segment_fixed_size: 0
    .sgpr_count:     108
    .sgpr_spill_count: 10
    .symbol:         _Z9hymba_fwd4Args.kd
    .uniform_work_group_size: 1
    .uses_dynamic_stack: false
    .vgpr_count:     256
    .vgpr_spill_count: 0
    .wavefront_size: 64
